# GEMM phases: first K-loop iteration peeled with inline-0 C operand instead of zeroing 128 accumulator registers per unit; on top of attention DMA spread
# baseline (speedup 1.0000x reference)
; #define PG8_STAGE(bufoff, gbase, voff) do { _Pragma("unroll") for (int _i = 0; _i < 2; ++_i) \
;         __builtin_amdgcn_global_load_lds((const unsigned*)((const char*)(gbase) + (voff)[_i]), (PG8_LAS unsigned*)(lds + (bufoff) + ldsw + _i * 8192), 16, 0, 0); } while (0)
; #define PG8_LDA(dst, b, h) do { _Pragma("unroll") for (int m = 0; m < 4; ++m) _Pragma("unroll") for (int k = 0; k < 2; ++k) dst[m][k] = *(const PG8_LAS bf16x8*)(lds + PG8_SA(b, h) + aoff + m * 2048 + k * 1024); } while (0)
; #define PG8_LDB(dst, b, h) do { _Pragma("unroll") for (int n = 0; n < 2; ++n) _Pragma("unroll") for (int k = 0; k < 2; ++k) dst[n][k] = *(const PG8_LAS bf16x8*)(lds + PG8_SB(b, h) + boff + n * 2048 + k * 1024); } while (0)
; #define PG8_MMA(ai, bj, At, Bt) do { __builtin_amdgcn_s_setprio(1); _Pragma("unroll") for (int m = 0; m < 4; ++m) _Pragma("unroll") for (int n = 0; n < 2; ++n) _Pragma("unroll") for (int k = 0; k < 2; ++k) \
;         acc[ai][bj][m][n] = __builtin_amdgcn_mfma_f32_16x16x32_bf16(Bt[n][k], At[m][k], acc[ai][bj][m][n], 0, 0, 0); __builtin_amdgcn_s_setprio(0); } while (0)
; template <class Epi, class Sched, bool ALIGN_EPI = false, bool SP2 = false>
; __device__ __forceinline__ void gemm_phase(PG8_LAS unsigned char* lds, const Gemm g, const Sched& S, const Epi& E) {
;     ...
;         const bool has_next = S.next(ui + 1, nxt);
;         const char* nA = has_next ? (const char*)g.A + (size_t)nxt.pm * tstep + (size_t)nxt.ks * K * 2 : cA; const char* nB = has_next ? (const char*)g.Bt + (size_t)nxt.pn * tstep + (size_t)nxt.ks * K * 2 : cB;
;         for (int t = 0; t < nt; t += 2) {
;             const bool last = (t == nt - 2);
;             const char* a1 = cA + (size_t)(t + 1) * kstep;
;             const char* a2 = last ? nA : cA + (size_t)(t + 2) * kstep; const char* b2 = last ? nB : cB + (size_t)(t + 2) * kstep;
;             const char* a3 = a2 + kstep; const char* b3 = b2 + kstep;
;             if (last && has_next) S.a_ready(nxt);
;             if constexpr (SP2) {
;             PG8_LDB(B0, 0, 0); PG8_LDB(B1, 0, 1); PG8_SCHED; PG8_LDA(At, 0, 0); PG8_STAGE(PG8_SA(1, 1), a1 + hstep, voffA);
;             PG8_WAIT_V(8); PG8_WAIT_L(0); PG8_BAR; PG8_MMA(0, 0, At, B0); PG8_MMA(0, 1, At, B1); PG8_BAR; PG8_SCHED;
;             PG8_LDA(At, 0, 1); PG8_STAGE(PG8_SB(0, 0), b2, voffB); PG8_STAGE(PG8_SB(0, 1), b2 + hstep, voffB); PG8_STAGE(PG8_SA(0, 0), a2, voffA);
.LBB0_256:
	s_ashr_i32 s13, s12, 31
	s_lshl_b64 s[22:23], s[12:13], 19
	s_add_u32 s22, s28, s22
	s_addc_u32 s23, s29, s23
	s_and_b64 s[24:25], s[2:3], exec
	s_cselect_b32 s13, s23, s45
	s_cselect_b32 s36, s22, s44
	s_ashr_i32 s11, s10, 31
	s_lshl_b64 s[24:25], s[10:11], 19
	s_add_u32 s24, s30, s24
	s_addc_u32 s25, s31, s25
	s_and_b64 s[40:41], s[2:3], exec
	s_cselect_b32 s11, s25, s43
	s_cselect_b32 s37, s24, s42
	s_add_u32 s40, s42, 0x100
	s_addc_u32 s41, s43, 0
	s_add_u32 s42, s44, 0x40080
	s_addc_u32 s43, s45, 0
	s_mov_b32 s48, -2
	ds_read_b128 v[146:149], v152
	ds_read_b128 v[158:161], v152 offset:1024
	ds_read_b128 v[162:165], v152 offset:2048
	ds_read_b128 v[166:169], v152 offset:3072
	ds_read_b128 v[170:173], v153
	ds_read_b128 v[174:177], v153 offset:1024
	ds_read_b128 v[178:181], v153 offset:2048
	ds_read_b128 v[182:185], v153 offset:3072
	s_add_u32 s44, s42, 0xfffc0080
	s_addc_u32 s45, s43, -1
	s_cmp_eq_u32 s48, 12
	s_cselect_b32 s47, s13, s45
	s_cselect_b32 s46, s36, s44
	s_cselect_b32 s45, s11, s41
	s_cselect_b32 s44, s37, s40
	v_lshl_add_u64 v[218:219], s[42:43], 0, v[140:141]
	s_add_i32 m0, s61, 0xc000
	ds_read_b128 v[186:189], v154
	ds_read_b128 v[190:193], v154 offset:1024
	ds_read_b128 v[194:197], v154 offset:2048
	ds_read_b128 v[198:201], v154 offset:3072
	ds_read_b128 v[202:205], v154 offset:4096
	ds_read_b128 v[206:209], v154 offset:5120
	ds_read_b128 v[210:213], v154 offset:6144
	ds_read_b128 v[214:217], v154 offset:7168
	global_load_lds_dwordx4 v[218:219], off
	v_lshl_add_u64 v[218:219], s[42:43], 0, v[138:139]
	s_add_i32 m0, s61, 0xe000
	s_nop 0
	global_load_lds_dwordx4 v[218:219], off
	s_waitcnt vmcnt(8)
	s_waitcnt lgkmcnt(0)
	s_barrier
	s_setprio 1
	s_waitcnt lgkmcnt(0)
	v_mfma_f32_16x16x32_bf16 v[126:129], v[146:149], v[186:189], 0
	v_mfma_f32_16x16x32_bf16 v[118:121], v[162:165], v[186:189], 0
	v_mfma_f32_16x16x32_bf16 v[110:113], v[146:149], v[194:197], 0
	v_mfma_f32_16x16x32_bf16 v[102:105], v[162:165], v[194:197], 0
	v_mfma_f32_16x16x32_bf16 v[94:97], v[146:149], v[202:205], 0
	v_mfma_f32_16x16x32_bf16 v[86:89], v[162:165], v[202:205], 0
	v_mfma_f32_16x16x32_bf16 v[78:81], v[146:149], v[210:213], 0
	v_mfma_f32_16x16x32_bf16 v[70:73], v[162:165], v[210:213], 0
	v_mfma_f32_16x16x32_bf16 v[126:129], v[158:161], v[190:193], v[126:129]
	v_mfma_f32_16x16x32_bf16 v[118:121], v[166:169], v[190:193], v[118:121]
	v_mfma_f32_16x16x32_bf16 v[110:113], v[158:161], v[198:201], v[110:113]
	v_mfma_f32_16x16x32_bf16 v[102:105], v[166:169], v[198:201], v[102:105]
	v_mfma_f32_16x16x32_bf16 v[94:97], v[158:161], v[206:209], v[94:97]
	v_mfma_f32_16x16x32_bf16 v[86:89], v[166:169], v[206:209], v[86:89]
	v_mfma_f32_16x16x32_bf16 v[78:81], v[158:161], v[214:217], v[78:81]
	v_mfma_f32_16x16x32_bf16 v[70:73], v[166:169], v[214:217], v[70:73]
	s_setprio 0
	s_setprio 1
	v_mfma_f32_16x16x32_bf16 v[122:125], v[170:173], v[186:189], 0
	v_mfma_f32_16x16x32_bf16 v[114:117], v[178:181], v[186:189], 0
	v_mfma_f32_16x16x32_bf16 v[106:109], v[170:173], v[194:197], 0
	v_mfma_f32_16x16x32_bf16 v[98:101], v[178:181], v[194:197], 0
	v_mfma_f32_16x16x32_bf16 v[90:93], v[170:173], v[202:205], 0
	v_mfma_f32_16x16x32_bf16 v[82:85], v[178:181], v[202:205], 0
	v_mfma_f32_16x16x32_bf16 v[74:77], v[170:173], v[210:213], 0
	v_mfma_f32_16x16x32_bf16 v[66:69], v[178:181], v[210:213], 0
	v_mfma_f32_16x16x32_bf16 v[122:125], v[174:177], v[190:193], v[122:125]
	v_mfma_f32_16x16x32_bf16 v[114:117], v[182:185], v[190:193], v[114:117]
	v_mfma_f32_16x16x32_bf16 v[106:109], v[174:177], v[198:201], v[106:109]
	v_mfma_f32_16x16x32_bf16 v[98:101], v[182:185], v[198:201], v[98:101]
	v_mfma_f32_16x16x32_bf16 v[90:93], v[174:177], v[206:209], v[90:93]
	v_mfma_f32_16x16x32_bf16 v[82:85], v[182:185], v[206:209], v[82:85]
	v_mfma_f32_16x16x32_bf16 v[74:77], v[174:177], v[214:217], v[74:77]
	v_mfma_f32_16x16x32_bf16 v[66:69], v[182:185], v[214:217], v[66:69]
	s_setprio 0
	s_barrier
	s_mov_b32 m0, s39
	v_lshl_add_u64 v[218:219], s[44:45], 0, v[134:135]
	s_add_u32 s50, s44, 0x40000
	ds_read_b128 v[186:189], v154 offset:16384
	ds_read_b128 v[190:193], v154 offset:17408
	ds_read_b128 v[194:197], v154 offset:18432
	ds_read_b128 v[198:201], v154 offset:19456
	ds_read_b128 v[202:205], v154 offset:20480
	ds_read_b128 v[206:209], v154 offset:21504
	ds_read_b128 v[210:213], v154 offset:22528
	ds_read_b128 v[214:217], v154 offset:23552
	global_load_lds_dwordx4 v[218:219], off
	v_lshl_add_u64 v[220:221], s[44:45], 0, v[130:131]
	s_mov_b32 m0, s56
	s_addc_u32 s51, s45, 0
	global_load_lds_dwordx4 v[220:221], off
	v_lshl_add_u64 v[222:223], s[50:51], 0, v[134:135]
	s_mov_b32 m0, s57
	v_lshl_add_u64 v[224:225], s[46:47], 0, v[132:133]
	global_load_lds_dwordx4 v[222:223], off
	v_lshl_add_u64 v[222:223], s[50:51], 0, v[130:131]
	s_mov_b32 m0, s60
	s_nop 0
	global_load_lds_dwordx4 v[222:223], off
	v_lshl_add_u64 v[222:223], s[46:47], 0, v[136:137]
	s_mov_b32 m0, s61
	s_nop 0
	global_load_lds_dwordx4 v[222:223], off
	s_mov_b32 m0, s62
	s_nop 0
	global_load_lds_dwordx4 v[224:225], off
	s_waitcnt vmcnt(8)
	s_waitcnt lgkmcnt(0)
	s_barrier
; #define PG8_STAGE(bufoff, gbase, voff) do { _Pragma("unroll") for (int _i = 0; _i < 2; ++_i) \
;         __builtin_amdgcn_global_load_lds((const unsigned*)((const char*)(gbase) + (voff)[_i]), (PG8_LAS unsigned*)(lds + (bufoff) + ldsw + _i * 8192), 16, 0, 0); } while (0)
; #define PG8_LDA(dst, b, h) do { _Pragma("unroll") for (int m = 0; m < 4; ++m) _Pragma("unroll") for (int k = 0; k < 2; ++k) dst[m][k] = *(const PG8_LAS bf16x8*)(lds + PG8_SA(b, h) + aoff + m * 2048 + k * 1024); } while (0)
; #define PG8_LDB(dst, b, h) do { _Pragma("unroll") for (int n = 0; n < 2; ++n) _Pragma("unroll") for (int k = 0; k < 2; ++k) dst[n][k] = *(const PG8_LAS bf16x8*)(lds + PG8_SB(b, h) + boff + n * 2048 + k * 1024); } while (0)
; #define PG8_MMA(ai, bj, At, Bt) do { __builtin_amdgcn_s_setprio(1); _Pragma("unroll") for (int m = 0; m < 4; ++m) _Pragma("unroll") for (int n = 0; n < 2; ++n) _Pragma("unroll") for (int k = 0; k < 2; ++k) \
;         acc[ai][bj][m][n] = __builtin_amdgcn_mfma_f32_16x16x32_bf16(Bt[n][k], At[m][k], acc[ai][bj][m][n], 0, 0, 0); __builtin_amdgcn_s_setprio(0); } while (0)
; #define PG8_WAIT_V(n) asm volatile("s_waitcnt vmcnt(" #n ")" ::: "memory")
; #define PG8_WAIT_L(n) asm volatile("s_waitcnt lgkmcnt(" #n ")" ::: "memory")
; #define PG8_BAR __builtin_amdgcn_s_barrier()
; #define PG8_SCHED __builtin_amdgcn_sched_barrier(0)
; template <class Epi, class Sched, bool ALIGN_EPI = false, bool SP2 = false>
; __device__ __forceinline__ void gemm_phase(PG8_LAS unsigned char* lds, const Gemm g, const Sched& S, const Epi& E) {
;     ...
;             PG8_WAIT_V(8); PG8_WAIT_L(0); PG8_BAR; PG8_MMA(1, 0, At, B0); PG8_MMA(1, 1, At, B1); PG8_BAR; PG8_SCHED;
;             PG8_LDB(B0, 1, 0); PG8_LDB(B1, 1, 1); PG8_SCHED; PG8_LDA(At, 1, 0); PG8_STAGE(PG8_SA(0, 1), a2 + hstep, voffA);
;             PG8_WAIT_V(8); PG8_WAIT_L(0); PG8_BAR; PG8_MMA(0, 0, At, B0); PG8_MMA(0, 1, At, B1); PG8_BAR; PG8_SCHED;
	s_setprio 1
	s_waitcnt lgkmcnt(0)
	v_mfma_f32_16x16x32_bf16 v[62:65], v[146:149], v[186:189], 0
	v_mfma_f32_16x16x32_bf16 v[54:57], v[162:165], v[186:189], 0
	v_mfma_f32_16x16x32_bf16 v[46:49], v[146:149], v[194:197], 0
	v_mfma_f32_16x16x32_bf16 v[38:41], v[162:165], v[194:197], 0
	v_mfma_f32_16x16x32_bf16 v[30:33], v[146:149], v[202:205], 0
	v_mfma_f32_16x16x32_bf16 v[22:25], v[162:165], v[202:205], 0
	v_mfma_f32_16x16x32_bf16 v[14:17], v[146:149], v[210:213], 0
	v_mfma_f32_16x16x32_bf16 v[6:9], v[162:165], v[210:213], 0
	v_mfma_f32_16x16x32_bf16 v[62:65], v[158:161], v[190:193], v[62:65]
	v_mfma_f32_16x16x32_bf16 v[54:57], v[166:169], v[190:193], v[54:57]
	v_mfma_f32_16x16x32_bf16 v[46:49], v[158:161], v[198:201], v[46:49]
	v_mfma_f32_16x16x32_bf16 v[38:41], v[166:169], v[198:201], v[38:41]
	v_mfma_f32_16x16x32_bf16 v[30:33], v[158:161], v[206:209], v[30:33]
	v_mfma_f32_16x16x32_bf16 v[22:25], v[166:169], v[206:209], v[22:25]
	v_mfma_f32_16x16x32_bf16 v[14:17], v[158:161], v[214:217], v[14:17]
	v_mfma_f32_16x16x32_bf16 v[6:9], v[166:169], v[214:217], v[6:9]
	s_setprio 0
	s_setprio 1
	v_mfma_f32_16x16x32_bf16 v[58:61], v[170:173], v[186:189], 0
	v_mfma_f32_16x16x32_bf16 v[50:53], v[178:181], v[186:189], 0
	v_mfma_f32_16x16x32_bf16 v[42:45], v[170:173], v[194:197], 0
	v_mfma_f32_16x16x32_bf16 v[34:37], v[178:181], v[194:197], 0
	v_mfma_f32_16x16x32_bf16 v[26:29], v[170:173], v[202:205], 0
	v_mfma_f32_16x16x32_bf16 v[18:21], v[178:181], v[202:205], 0
	v_mfma_f32_16x16x32_bf16 v[10:13], v[170:173], v[210:213], 0
	v_mfma_f32_16x16x32_bf16 v[2:5], v[178:181], v[210:213], 0
	v_mfma_f32_16x16x32_bf16 v[58:61], v[174:177], v[190:193], v[58:61]
	v_mfma_f32_16x16x32_bf16 v[50:53], v[182:185], v[190:193], v[50:53]
	v_mfma_f32_16x16x32_bf16 v[42:45], v[174:177], v[198:201], v[42:45]
	v_mfma_f32_16x16x32_bf16 v[34:37], v[182:185], v[198:201], v[34:37]
	v_mfma_f32_16x16x32_bf16 v[26:29], v[174:177], v[206:209], v[26:29]
	v_mfma_f32_16x16x32_bf16 v[18:21], v[182:185], v[206:209], v[18:21]
	v_mfma_f32_16x16x32_bf16 v[10:13], v[174:177], v[214:217], v[10:13]
	v_mfma_f32_16x16x32_bf16 v[2:5], v[182:185], v[214:217], v[2:5]
	s_setprio 0
	s_barrier
	ds_read_b128 v[146:149], v155
	ds_read_b128 v[158:161], v155 offset:1024
	ds_read_b128 v[162:165], v155 offset:2048
	ds_read_b128 v[166:169], v155 offset:3072
	ds_read_b128 v[170:173], v156
	ds_read_b128 v[174:177], v156 offset:1024
	ds_read_b128 v[178:181], v156 offset:2048
	ds_read_b128 v[182:185], v156 offset:3072
	s_add_u32 s46, s46, 0x40000
	s_addc_u32 s47, s47, 0
	s_mov_b32 m0, s63
	v_lshl_add_u64 v[226:227], s[46:47], 0, v[136:137]
	ds_read_b128 v[186:189], v154 offset:32768
	ds_read_b128 v[190:193], v154 offset:33792
	ds_read_b128 v[194:197], v154 offset:34816
	ds_read_b128 v[198:201], v154 offset:35840
	ds_read_b128 v[202:205], v154 offset:36864
	ds_read_b128 v[206:209], v154 offset:37888
	ds_read_b128 v[210:213], v154 offset:38912
	ds_read_b128 v[214:217], v154 offset:39936
	global_load_lds_dwordx4 v[226:227], off
	v_lshl_add_u64 v[226:227], s[46:47], 0, v[132:133]
	s_mov_b32 m0, s64
	s_nop 0
	global_load_lds_dwordx4 v[226:227], off
	s_waitcnt vmcnt(8)
	s_waitcnt lgkmcnt(0)
	s_barrier
	s_setprio 1
	s_waitcnt lgkmcnt(0)
	v_mfma_f32_16x16x32_bf16 v[126:129], v[146:149], v[186:189], v[126:129]
	v_mfma_f32_16x16x32_bf16 v[118:121], v[162:165], v[186:189], v[118:121]
	v_mfma_f32_16x16x32_bf16 v[110:113], v[146:149], v[194:197], v[110:113]
	v_mfma_f32_16x16x32_bf16 v[102:105], v[162:165], v[194:197], v[102:105]
	v_mfma_f32_16x16x32_bf16 v[94:97], v[146:149], v[202:205], v[94:97]
	v_mfma_f32_16x16x32_bf16 v[86:89], v[162:165], v[202:205], v[86:89]
	v_mfma_f32_16x16x32_bf16 v[78:81], v[146:149], v[210:213], v[78:81]
	v_mfma_f32_16x16x32_bf16 v[70:73], v[162:165], v[210:213], v[70:73]
	v_mfma_f32_16x16x32_bf16 v[126:129], v[158:161], v[190:193], v[126:129]
	v_mfma_f32_16x16x32_bf16 v[118:121], v[166:169], v[190:193], v[118:121]
	v_mfma_f32_16x16x32_bf16 v[110:113], v[158:161], v[198:201], v[110:113]
	v_mfma_f32_16x16x32_bf16 v[102:105], v[166:169], v[198:201], v[102:105]
	v_mfma_f32_16x16x32_bf16 v[94:97], v[158:161], v[206:209], v[94:97]
	v_mfma_f32_16x16x32_bf16 v[86:89], v[166:169], v[206:209], v[86:89]
	v_mfma_f32_16x16x32_bf16 v[78:81], v[158:161], v[214:217], v[78:81]
	v_mfma_f32_16x16x32_bf16 v[70:73], v[166:169], v[214:217], v[70:73]
	s_setprio 0
	s_setprio 1
	v_mfma_f32_16x16x32_bf16 v[122:125], v[170:173], v[186:189], v[122:125]
	v_mfma_f32_16x16x32_bf16 v[114:117], v[178:181], v[186:189], v[114:117]
	v_mfma_f32_16x16x32_bf16 v[106:109], v[170:173], v[194:197], v[106:109]
	v_mfma_f32_16x16x32_bf16 v[98:101], v[178:181], v[194:197], v[98:101]
	v_mfma_f32_16x16x32_bf16 v[90:93], v[170:173], v[202:205], v[90:93]
	v_mfma_f32_16x16x32_bf16 v[82:85], v[178:181], v[202:205], v[82:85]
	v_mfma_f32_16x16x32_bf16 v[74:77], v[170:173], v[210:213], v[74:77]
	v_mfma_f32_16x16x32_bf16 v[66:69], v[178:181], v[210:213], v[66:69]
	v_mfma_f32_16x16x32_bf16 v[122:125], v[174:177], v[190:193], v[122:125]
	v_mfma_f32_16x16x32_bf16 v[114:117], v[182:185], v[190:193], v[114:117]
	v_mfma_f32_16x16x32_bf16 v[106:109], v[174:177], v[198:201], v[106:109]
	v_mfma_f32_16x16x32_bf16 v[98:101], v[182:185], v[198:201], v[98:101]
	v_mfma_f32_16x16x32_bf16 v[90:93], v[174:177], v[206:209], v[90:93]
	v_mfma_f32_16x16x32_bf16 v[82:85], v[182:185], v[206:209], v[82:85]
	v_mfma_f32_16x16x32_bf16 v[74:77], v[174:177], v[214:217], v[74:77]
	v_mfma_f32_16x16x32_bf16 v[66:69], v[182:185], v[214:217], v[66:69]
	s_setprio 0
	s_barrier
; #define PG8_STAGE(bufoff, gbase, voff) do { _Pragma("unroll") for (int _i = 0; _i < 2; ++_i) \
;         __builtin_amdgcn_global_load_lds((const unsigned*)((const char*)(gbase) + (voff)[_i]), (PG8_LAS unsigned*)(lds + (bufoff) + ldsw + _i * 8192), 16, 0, 0); } while (0)
; #define PG8_LDA(dst, b, h) do { _Pragma("unroll") for (int m = 0; m < 4; ++m) _Pragma("unroll") for (int k = 0; k < 2; ++k) dst[m][k] = *(const PG8_LAS bf16x8*)(lds + PG8_SA(b, h) + aoff + m * 2048 + k * 1024); } while (0)
; #define PG8_MMA(ai, bj, At, Bt) do { __builtin_amdgcn_s_setprio(1); _Pragma("unroll") for (int m = 0; m < 4; ++m) _Pragma("unroll") for (int n = 0; n < 2; ++n) _Pragma("unroll") for (int k = 0; k < 2; ++k) \
;         acc[ai][bj][m][n] = __builtin_amdgcn_mfma_f32_16x16x32_bf16(Bt[n][k], At[m][k], acc[ai][bj][m][n], 0, 0, 0); __builtin_amdgcn_s_setprio(0); } while (0)
; #define PG8_WAIT_V(n) asm volatile("s_waitcnt vmcnt(" #n ")" ::: "memory")
; #define PG8_WAIT_L(n) asm volatile("s_waitcnt lgkmcnt(" #n ")" ::: "memory")
; #define PG8_BAR __builtin_amdgcn_s_barrier()
; #define PG8_SCHED __builtin_amdgcn_sched_barrier(0)
; template <class Epi, class Sched, bool ALIGN_EPI = false, bool SP2 = false>
; __device__ __forceinline__ void gemm_phase(PG8_LAS unsigned char* lds, const Gemm g, const Sched& S, const Epi& E) {
;     ...
;         for (int t = 0; t < nt; t += 2) {
;     ...
;             PG8_LDA(At, 1, 1); PG8_STAGE(PG8_SB(1, 0), b3, voffB); PG8_STAGE(PG8_SB(1, 1), b3 + hstep, voffB); PG8_STAGE(PG8_SA(1, 0), a3, voffA);
;             PG8_WAIT_V(8); PG8_WAIT_L(0); PG8_BAR; PG8_MMA(1, 0, At, B0); PG8_MMA(1, 1, At, B1); PG8_BAR; PG8_SCHED;
	s_mov_b32 m0, s65
	v_lshl_add_u64 v[218:219], v[218:219], 0, s[6:7]
	s_add_u32 s44, s44, 0x40080
	ds_read_b128 v[186:189], v154 offset:49152
	ds_read_b128 v[190:193], v154 offset:50176
	ds_read_b128 v[194:197], v154 offset:51200
	ds_read_b128 v[198:201], v154 offset:52224
	ds_read_b128 v[202:205], v154 offset:53248
	ds_read_b128 v[206:209], v154 offset:54272
	ds_read_b128 v[210:213], v154 offset:55296
	ds_read_b128 v[214:217], v154 offset:56320
	global_load_lds_dwordx4 v[218:219], off
	v_lshl_add_u64 v[218:219], v[220:221], 0, s[6:7]
	s_mov_b32 m0, s66
	s_addc_u32 s45, s45, 0
	global_load_lds_dwordx4 v[218:219], off
	v_lshl_add_u64 v[218:219], s[44:45], 0, v[134:135]
	s_mov_b32 m0, s69
	s_nop 0
	global_load_lds_dwordx4 v[218:219], off
	v_lshl_add_u64 v[218:219], s[44:45], 0, v[130:131]
	s_mov_b32 m0, s70
	s_nop 0
	global_load_lds_dwordx4 v[218:219], off
	v_lshl_add_u64 v[218:219], v[222:223], 0, s[6:7]
	s_mov_b32 m0, s67
	s_nop 0
	global_load_lds_dwordx4 v[218:219], off
	v_lshl_add_u64 v[218:219], v[224:225], 0, s[6:7]
	s_mov_b32 m0, s68
	s_nop 0
	global_load_lds_dwordx4 v[218:219], off
	s_waitcnt vmcnt(8)
	s_waitcnt lgkmcnt(0)
	s_barrier
	s_setprio 1
	s_waitcnt lgkmcnt(0)
	v_mfma_f32_16x16x32_bf16 v[62:65], v[146:149], v[186:189], v[62:65]
	v_mfma_f32_16x16x32_bf16 v[54:57], v[162:165], v[186:189], v[54:57]
	v_mfma_f32_16x16x32_bf16 v[46:49], v[146:149], v[194:197], v[46:49]
	v_mfma_f32_16x16x32_bf16 v[38:41], v[162:165], v[194:197], v[38:41]
	v_mfma_f32_16x16x32_bf16 v[30:33], v[146:149], v[202:205], v[30:33]
	v_mfma_f32_16x16x32_bf16 v[22:25], v[162:165], v[202:205], v[22:25]
	v_mfma_f32_16x16x32_bf16 v[14:17], v[146:149], v[210:213], v[14:17]
	v_mfma_f32_16x16x32_bf16 v[6:9], v[162:165], v[210:213], v[6:9]
	v_mfma_f32_16x16x32_bf16 v[62:65], v[158:161], v[190:193], v[62:65]
	v_mfma_f32_16x16x32_bf16 v[54:57], v[166:169], v[190:193], v[54:57]
	v_mfma_f32_16x16x32_bf16 v[46:49], v[158:161], v[198:201], v[46:49]
	v_mfma_f32_16x16x32_bf16 v[38:41], v[166:169], v[198:201], v[38:41]
	v_mfma_f32_16x16x32_bf16 v[30:33], v[158:161], v[206:209], v[30:33]
	v_mfma_f32_16x16x32_bf16 v[22:25], v[166:169], v[206:209], v[22:25]
	v_mfma_f32_16x16x32_bf16 v[14:17], v[158:161], v[214:217], v[14:17]
	v_mfma_f32_16x16x32_bf16 v[6:9], v[166:169], v[214:217], v[6:9]
	s_setprio 0
	s_setprio 1
	v_mfma_f32_16x16x32_bf16 v[58:61], v[170:173], v[186:189], v[58:61]
	v_mfma_f32_16x16x32_bf16 v[50:53], v[178:181], v[186:189], v[50:53]
	v_mfma_f32_16x16x32_bf16 v[42:45], v[170:173], v[194:197], v[42:45]
	v_mfma_f32_16x16x32_bf16 v[34:37], v[178:181], v[194:197], v[34:37]
	v_mfma_f32_16x16x32_bf16 v[26:29], v[170:173], v[202:205], v[26:29]
	v_mfma_f32_16x16x32_bf16 v[18:21], v[178:181], v[202:205], v[18:21]
	v_mfma_f32_16x16x32_bf16 v[10:13], v[170:173], v[210:213], v[10:13]
	v_mfma_f32_16x16x32_bf16 v[2:5], v[178:181], v[210:213], v[2:5]
	v_mfma_f32_16x16x32_bf16 v[58:61], v[174:177], v[190:193], v[58:61]
	v_mfma_f32_16x16x32_bf16 v[50:53], v[182:185], v[190:193], v[50:53]
	v_mfma_f32_16x16x32_bf16 v[42:45], v[174:177], v[198:201], v[42:45]
	v_mfma_f32_16x16x32_bf16 v[34:37], v[182:185], v[198:201], v[34:37]
	v_mfma_f32_16x16x32_bf16 v[26:29], v[174:177], v[206:209], v[26:29]
	v_mfma_f32_16x16x32_bf16 v[18:21], v[182:185], v[206:209], v[18:21]
	v_mfma_f32_16x16x32_bf16 v[10:13], v[174:177], v[214:217], v[10:13]
	v_mfma_f32_16x16x32_bf16 v[2:5], v[182:185], v[214:217], v[2:5]
	s_setprio 0
	s_barrier
	s_add_i32 s48, s48, 2
	s_add_u32 s40, s40, 0x100
	s_addc_u32 s41, s41, 0
	s_add_u32 s42, s42, 0x100
	s_addc_u32 s43, s43, 0
	s_cmp_gt_u32 s48, 13

; #define PG8_STAGE(bufoff, gbase, voff) do { _Pragma("unroll") for (int _i = 0; _i < 2; ++_i) \
;         __builtin_amdgcn_global_load_lds((const unsigned*)((const char*)(gbase) + (voff)[_i]), (PG8_LAS unsigned*)(lds + (bufoff) + ldsw + _i * 8192), 16, 0, 0); } while (0)
; #define PG8_LDA(dst, b, h) do { _Pragma("unroll") for (int m = 0; m < 4; ++m) _Pragma("unroll") for (int k = 0; k < 2; ++k) dst[m][k] = *(const PG8_LAS bf16x8*)(lds + PG8_SA(b, h) + aoff + m * 2048 + k * 1024); } while (0)
; #define PG8_LDB(dst, b, h) do { _Pragma("unroll") for (int n = 0; n < 2; ++n) _Pragma("unroll") for (int k = 0; k < 2; ++k) dst[n][k] = *(const PG8_LAS bf16x8*)(lds + PG8_SB(b, h) + boff + n * 2048 + k * 1024); } while (0)
; #define PG8_MMA(ai, bj, At, Bt) do { __builtin_amdgcn_s_setprio(1); _Pragma("unroll") for (int m = 0; m < 4; ++m) _Pragma("unroll") for (int n = 0; n < 2; ++n) _Pragma("unroll") for (int k = 0; k < 2; ++k) \
;         acc[ai][bj][m][n] = __builtin_amdgcn_mfma_f32_16x16x32_bf16(Bt[n][k], At[m][k], acc[ai][bj][m][n], 0, 0, 0); __builtin_amdgcn_s_setprio(0); } while (0)
; #define PG8_WAIT_V(n) asm volatile("s_waitcnt vmcnt(" #n ")" ::: "memory")
; #define PG8_WAIT_L(n) asm volatile("s_waitcnt lgkmcnt(" #n ")" ::: "memory")
; #define PG8_BAR __builtin_amdgcn_s_barrier()
; #define PG8_SCHED __builtin_amdgcn_sched_barrier(0)
; template <class Epi, class Sched, bool ALIGN_EPI = false, bool SP2 = false>
; __device__ __forceinline__ void gemm_phase(PG8_LAS unsigned char* lds, const Gemm g, const Sched& S, const Epi& E) {
;     ...
;         for (int t = 0; t < nt; t += 2) {
;             const bool last = (t == nt - 2);
;             const char* a1 = cA + (size_t)(t + 1) * kstep;
;             const char* a2 = last ? nA : cA + (size_t)(t + 2) * kstep; const char* b2 = last ? nB : cB + (size_t)(t + 2) * kstep;
;             const char* a3 = a2 + kstep; const char* b3 = b2 + kstep;
;             if (last && has_next) S.a_ready(nxt);
;             if constexpr (SP2) {
;             PG8_LDB(B0, 0, 0); PG8_LDB(B1, 0, 1); PG8_SCHED; PG8_LDA(At, 0, 0); PG8_STAGE(PG8_SA(1, 1), a1 + hstep, voffA);
;             PG8_WAIT_V(8); PG8_WAIT_L(0); PG8_BAR; PG8_MMA(0, 0, At, B0); PG8_MMA(0, 1, At, B1); PG8_BAR; PG8_SCHED;
;             PG8_LDA(At, 0, 1); PG8_STAGE(PG8_SB(0, 0), b2, voffB); PG8_STAGE(PG8_SB(0, 1), b2 + hstep, voffB); PG8_STAGE(PG8_SA(0, 0), a2, voffA);
.LBB0_345:
	s_add_u32 vcc_lo, s72, 0x100
	s_addc_u32 vcc_hi, s73, 0
	s_mov_b32 s74, 0
	ds_read_b128 v[150:153], v147
	ds_read_b128 v[154:157], v147 offset:1024
	ds_read_b128 v[158:161], v147 offset:2048
	ds_read_b128 v[162:165], v147 offset:3072
	ds_read_b128 v[166:169], v148
	ds_read_b128 v[170:173], v148 offset:1024
	ds_read_b128 v[174:177], v148 offset:2048
	ds_read_b128 v[178:181], v148 offset:3072
	s_add_i32 s38, s74, 2
	s_add_u32 s72, s70, 0x100
	s_addc_u32 s73, s71, 0
	s_cmp_eq_u32 s50, s74
	s_cselect_b32 s74, s68, vcc_lo
	s_cselect_b32 s77, s61, s73
	s_cselect_b32 s76, s60, s72
	s_cselect_b32 s75, s69, vcc_hi
	v_lshl_add_u64 v[214:215], s[70:71], 0, v[140:141]
	s_add_i32 m0, s89, 0xc000
	ds_read_b128 v[182:185], v146
	ds_read_b128 v[186:189], v146 offset:1024
	ds_read_b128 v[190:193], v146 offset:2048
	ds_read_b128 v[194:197], v146 offset:3072
	ds_read_b128 v[198:201], v146 offset:4096
	ds_read_b128 v[202:205], v146 offset:5120
	ds_read_b128 v[206:209], v146 offset:6144
	ds_read_b128 v[210:213], v146 offset:7168
	global_load_lds_dwordx4 v[214:215], off
	v_lshl_add_u64 v[214:215], s[70:71], 0, v[138:139]
	s_add_i32 m0, s89, 0xe000
	s_nop 0
	global_load_lds_dwordx4 v[214:215], off
	s_waitcnt vmcnt(8)
	s_waitcnt lgkmcnt(0)
	s_barrier
	s_setprio 1
	s_waitcnt lgkmcnt(0)
	v_mfma_f32_16x16x32_bf16 v[126:129], v[150:153], v[182:185], 0
	v_mfma_f32_16x16x32_bf16 v[122:125], v[158:161], v[182:185], 0
	v_mfma_f32_16x16x32_bf16 v[118:121], v[150:153], v[190:193], 0
	v_mfma_f32_16x16x32_bf16 v[114:117], v[158:161], v[190:193], 0
	v_mfma_f32_16x16x32_bf16 v[102:105], v[150:153], v[198:201], 0
	v_mfma_f32_16x16x32_bf16 v[98:101], v[158:161], v[198:201], 0
	v_mfma_f32_16x16x32_bf16 v[86:89], v[150:153], v[206:209], 0
	v_mfma_f32_16x16x32_bf16 v[82:85], v[158:161], v[206:209], 0
	v_mfma_f32_16x16x32_bf16 v[126:129], v[154:157], v[186:189], v[126:129]
	v_mfma_f32_16x16x32_bf16 v[122:125], v[162:165], v[186:189], v[122:125]
	v_mfma_f32_16x16x32_bf16 v[118:121], v[154:157], v[194:197], v[118:121]
	v_mfma_f32_16x16x32_bf16 v[114:117], v[162:165], v[194:197], v[114:117]
	v_mfma_f32_16x16x32_bf16 v[102:105], v[154:157], v[202:205], v[102:105]
	v_mfma_f32_16x16x32_bf16 v[98:101], v[162:165], v[202:205], v[98:101]
	v_mfma_f32_16x16x32_bf16 v[86:89], v[154:157], v[210:213], v[86:89]
	v_mfma_f32_16x16x32_bf16 v[82:85], v[162:165], v[210:213], v[82:85]
	s_setprio 0
	s_setprio 1
	v_mfma_f32_16x16x32_bf16 v[110:113], v[166:169], v[182:185], 0
	v_mfma_f32_16x16x32_bf16 v[106:109], v[174:177], v[182:185], 0
	v_mfma_f32_16x16x32_bf16 v[94:97], v[166:169], v[190:193], 0
	v_mfma_f32_16x16x32_bf16 v[90:93], v[174:177], v[190:193], 0
	v_mfma_f32_16x16x32_bf16 v[78:81], v[166:169], v[198:201], 0
	v_mfma_f32_16x16x32_bf16 v[74:77], v[174:177], v[198:201], 0
	v_mfma_f32_16x16x32_bf16 v[70:73], v[166:169], v[206:209], 0
	v_mfma_f32_16x16x32_bf16 v[66:69], v[174:177], v[206:209], 0
	v_mfma_f32_16x16x32_bf16 v[110:113], v[170:173], v[186:189], v[110:113]
	v_mfma_f32_16x16x32_bf16 v[106:109], v[178:181], v[186:189], v[106:109]
	v_mfma_f32_16x16x32_bf16 v[94:97], v[170:173], v[194:197], v[94:97]
	v_mfma_f32_16x16x32_bf16 v[90:93], v[178:181], v[194:197], v[90:93]
	v_mfma_f32_16x16x32_bf16 v[78:81], v[170:173], v[202:205], v[78:81]
	v_mfma_f32_16x16x32_bf16 v[74:77], v[178:181], v[202:205], v[74:77]
	v_mfma_f32_16x16x32_bf16 v[70:73], v[170:173], v[210:213], v[70:73]
	v_mfma_f32_16x16x32_bf16 v[66:69], v[178:181], v[210:213], v[66:69]
	s_setprio 0
	s_barrier
	s_mov_b32 m0, s85
	v_lshl_add_u64 v[214:215], s[74:75], 0, v[130:131]
	s_add_u32 s70, s74, 0xb0000
	ds_read_b128 v[182:185], v146 offset:16384
	ds_read_b128 v[186:189], v146 offset:17408
	ds_read_b128 v[190:193], v146 offset:18432
	ds_read_b128 v[194:197], v146 offset:19456
	ds_read_b128 v[198:201], v146 offset:20480
	ds_read_b128 v[202:205], v146 offset:21504
	ds_read_b128 v[206:209], v146 offset:22528
	ds_read_b128 v[210:213], v146 offset:23552
	global_load_lds_dwordx4 v[214:215], off
	v_lshl_add_u64 v[216:217], s[74:75], 0, v[136:137]
	s_mov_b32 m0, s86
	s_addc_u32 s71, s75, 0
	global_load_lds_dwordx4 v[216:217], off
	v_lshl_add_u64 v[218:219], s[70:71], 0, v[130:131]
	s_mov_b32 m0, s87
	v_lshl_add_u64 v[220:221], s[76:77], 0, v[134:135]
	global_load_lds_dwordx4 v[218:219], off
	v_lshl_add_u64 v[218:219], s[70:71], 0, v[136:137]
	s_mov_b32 m0, s88
	s_nop 0
	global_load_lds_dwordx4 v[218:219], off
	v_lshl_add_u64 v[218:219], s[76:77], 0, v[132:133]
	s_mov_b32 m0, s89
	s_nop 0
	global_load_lds_dwordx4 v[218:219], off
	s_mov_b32 m0, s90
	s_nop 0
	global_load_lds_dwordx4 v[220:221], off
	s_waitcnt vmcnt(8)
	s_waitcnt lgkmcnt(0)
	s_barrier
; #define PG8_STAGE(bufoff, gbase, voff) do { _Pragma("unroll") for (int _i = 0; _i < 2; ++_i) \
;         __builtin_amdgcn_global_load_lds((const unsigned*)((const char*)(gbase) + (voff)[_i]), (PG8_LAS unsigned*)(lds + (bufoff) + ldsw + _i * 8192), 16, 0, 0); } while (0)
; #define PG8_LDA(dst, b, h) do { _Pragma("unroll") for (int m = 0; m < 4; ++m) _Pragma("unroll") for (int k = 0; k < 2; ++k) dst[m][k] = *(const PG8_LAS bf16x8*)(lds + PG8_SA(b, h) + aoff + m * 2048 + k * 1024); } while (0)
; #define PG8_LDB(dst, b, h) do { _Pragma("unroll") for (int n = 0; n < 2; ++n) _Pragma("unroll") for (int k = 0; k < 2; ++k) dst[n][k] = *(const PG8_LAS bf16x8*)(lds + PG8_SB(b, h) + boff + n * 2048 + k * 1024); } while (0)
; #define PG8_MMA(ai, bj, At, Bt) do { __builtin_amdgcn_s_setprio(1); _Pragma("unroll") for (int m = 0; m < 4; ++m) _Pragma("unroll") for (int n = 0; n < 2; ++n) _Pragma("unroll") for (int k = 0; k < 2; ++k) \
;         acc[ai][bj][m][n] = __builtin_amdgcn_mfma_f32_16x16x32_bf16(Bt[n][k], At[m][k], acc[ai][bj][m][n], 0, 0, 0); __builtin_amdgcn_s_setprio(0); } while (0)
; #define PG8_WAIT_V(n) asm volatile("s_waitcnt vmcnt(" #n ")" ::: "memory")
; #define PG8_WAIT_L(n) asm volatile("s_waitcnt lgkmcnt(" #n ")" ::: "memory")
; #define PG8_BAR __builtin_amdgcn_s_barrier()
; #define PG8_SCHED __builtin_amdgcn_sched_barrier(0)
; template <class Epi, class Sched, bool ALIGN_EPI = false, bool SP2 = false>
; __device__ __forceinline__ void gemm_phase(PG8_LAS unsigned char* lds, const Gemm g, const Sched& S, const Epi& E) {
;     ...
;             PG8_WAIT_V(8); PG8_WAIT_L(0); PG8_BAR; PG8_MMA(1, 0, At, B0); PG8_MMA(1, 1, At, B1); PG8_BAR; PG8_SCHED;
;             PG8_LDB(B0, 1, 0); PG8_LDB(B1, 1, 1); PG8_SCHED; PG8_LDA(At, 1, 0); PG8_STAGE(PG8_SA(0, 1), a2 + hstep, voffA);
;             PG8_WAIT_V(8); PG8_WAIT_L(0); PG8_BAR; PG8_MMA(0, 0, At, B0); PG8_MMA(0, 1, At, B1); PG8_BAR; PG8_SCHED;
	s_setprio 1
	s_waitcnt lgkmcnt(0)
	v_mfma_f32_16x16x32_bf16 v[62:65], v[150:153], v[182:185], 0
	v_mfma_f32_16x16x32_bf16 v[58:61], v[158:161], v[182:185], 0
	v_mfma_f32_16x16x32_bf16 v[54:57], v[150:153], v[190:193], 0
	v_mfma_f32_16x16x32_bf16 v[50:53], v[158:161], v[190:193], 0
	v_mfma_f32_16x16x32_bf16 v[38:41], v[150:153], v[198:201], 0
	v_mfma_f32_16x16x32_bf16 v[34:37], v[158:161], v[198:201], 0
	v_mfma_f32_16x16x32_bf16 v[22:25], v[150:153], v[206:209], 0
	v_mfma_f32_16x16x32_bf16 v[18:21], v[158:161], v[206:209], 0
	v_mfma_f32_16x16x32_bf16 v[62:65], v[154:157], v[186:189], v[62:65]
	v_mfma_f32_16x16x32_bf16 v[58:61], v[162:165], v[186:189], v[58:61]
	v_mfma_f32_16x16x32_bf16 v[54:57], v[154:157], v[194:197], v[54:57]
	v_mfma_f32_16x16x32_bf16 v[50:53], v[162:165], v[194:197], v[50:53]
	v_mfma_f32_16x16x32_bf16 v[38:41], v[154:157], v[202:205], v[38:41]
	v_mfma_f32_16x16x32_bf16 v[34:37], v[162:165], v[202:205], v[34:37]
	v_mfma_f32_16x16x32_bf16 v[22:25], v[154:157], v[210:213], v[22:25]
	v_mfma_f32_16x16x32_bf16 v[18:21], v[162:165], v[210:213], v[18:21]
	s_setprio 0
	s_setprio 1
	v_mfma_f32_16x16x32_bf16 v[46:49], v[166:169], v[182:185], 0
	v_mfma_f32_16x16x32_bf16 v[42:45], v[174:177], v[182:185], 0
	v_mfma_f32_16x16x32_bf16 v[30:33], v[166:169], v[190:193], 0
	v_mfma_f32_16x16x32_bf16 v[26:29], v[174:177], v[190:193], 0
	v_mfma_f32_16x16x32_bf16 v[14:17], v[166:169], v[198:201], 0
	v_mfma_f32_16x16x32_bf16 v[10:13], v[174:177], v[198:201], 0
	v_mfma_f32_16x16x32_bf16 v[6:9], v[166:169], v[206:209], 0
	v_mfma_f32_16x16x32_bf16 v[2:5], v[174:177], v[206:209], 0
	v_mfma_f32_16x16x32_bf16 v[46:49], v[170:173], v[186:189], v[46:49]
	v_mfma_f32_16x16x32_bf16 v[42:45], v[178:181], v[186:189], v[42:45]
	v_mfma_f32_16x16x32_bf16 v[30:33], v[170:173], v[194:197], v[30:33]
	v_mfma_f32_16x16x32_bf16 v[26:29], v[178:181], v[194:197], v[26:29]
	v_mfma_f32_16x16x32_bf16 v[14:17], v[170:173], v[202:205], v[14:17]
	v_mfma_f32_16x16x32_bf16 v[10:13], v[178:181], v[202:205], v[10:13]
	v_mfma_f32_16x16x32_bf16 v[6:9], v[170:173], v[210:213], v[6:9]
	v_mfma_f32_16x16x32_bf16 v[2:5], v[178:181], v[210:213], v[2:5]
	s_setprio 0
	s_barrier
	v_add_u32_e32 v178, s78, v144
	ds_read_b128 v[150:153], v149
	ds_read_b128 v[154:157], v149 offset:1024
	ds_read_b128 v[158:161], v149 offset:2048
	ds_read_b128 v[162:165], v149 offset:3072
	ds_read_b128 v[166:169], v178
	ds_read_b128 v[170:173], v178 offset:1024
	ds_read_b128 v[174:177], v178 offset:2048
	ds_read_b128 v[178:181], v178 offset:3072
	s_add_u32 s70, s76, 0xb0000
	s_addc_u32 s71, s77, 0
	s_mov_b32 m0, s91
	v_lshl_add_u64 v[222:223], s[70:71], 0, v[132:133]
	ds_read_b128 v[182:185], v146 offset:32768
	ds_read_b128 v[186:189], v146 offset:33792
	ds_read_b128 v[190:193], v146 offset:34816
	ds_read_b128 v[194:197], v146 offset:35840
	ds_read_b128 v[198:201], v146 offset:36864
	ds_read_b128 v[202:205], v146 offset:37888
	ds_read_b128 v[206:209], v146 offset:38912
	ds_read_b128 v[210:213], v146 offset:39936
	global_load_lds_dwordx4 v[222:223], off
	v_lshl_add_u64 v[222:223], s[70:71], 0, v[134:135]
	s_mov_b32 m0, s92
	s_nop 0
	global_load_lds_dwordx4 v[222:223], off
	s_waitcnt vmcnt(8)
	s_waitcnt lgkmcnt(0)
	s_barrier
	s_setprio 1
	s_waitcnt lgkmcnt(0)
	v_mfma_f32_16x16x32_bf16 v[126:129], v[150:153], v[182:185], v[126:129]
	v_mfma_f32_16x16x32_bf16 v[122:125], v[158:161], v[182:185], v[122:125]
	v_mfma_f32_16x16x32_bf16 v[118:121], v[150:153], v[190:193], v[118:121]
	v_mfma_f32_16x16x32_bf16 v[114:117], v[158:161], v[190:193], v[114:117]
	v_mfma_f32_16x16x32_bf16 v[102:105], v[150:153], v[198:201], v[102:105]
	v_mfma_f32_16x16x32_bf16 v[98:101], v[158:161], v[198:201], v[98:101]
	v_mfma_f32_16x16x32_bf16 v[86:89], v[150:153], v[206:209], v[86:89]
	v_mfma_f32_16x16x32_bf16 v[82:85], v[158:161], v[206:209], v[82:85]
	v_mfma_f32_16x16x32_bf16 v[126:129], v[154:157], v[186:189], v[126:129]
	v_mfma_f32_16x16x32_bf16 v[122:125], v[162:165], v[186:189], v[122:125]
	v_mfma_f32_16x16x32_bf16 v[118:121], v[154:157], v[194:197], v[118:121]
	v_mfma_f32_16x16x32_bf16 v[114:117], v[162:165], v[194:197], v[114:117]
	v_mfma_f32_16x16x32_bf16 v[102:105], v[154:157], v[202:205], v[102:105]
	v_mfma_f32_16x16x32_bf16 v[98:101], v[162:165], v[202:205], v[98:101]
	v_mfma_f32_16x16x32_bf16 v[86:89], v[154:157], v[210:213], v[86:89]
	v_mfma_f32_16x16x32_bf16 v[82:85], v[162:165], v[210:213], v[82:85]
	s_setprio 0
	s_setprio 1
	v_mfma_f32_16x16x32_bf16 v[110:113], v[166:169], v[182:185], v[110:113]
	v_mfma_f32_16x16x32_bf16 v[106:109], v[174:177], v[182:185], v[106:109]
	v_mfma_f32_16x16x32_bf16 v[94:97], v[166:169], v[190:193], v[94:97]
	v_mfma_f32_16x16x32_bf16 v[90:93], v[174:177], v[190:193], v[90:93]
	v_mfma_f32_16x16x32_bf16 v[78:81], v[166:169], v[198:201], v[78:81]
	v_mfma_f32_16x16x32_bf16 v[74:77], v[174:177], v[198:201], v[74:77]
	v_mfma_f32_16x16x32_bf16 v[70:73], v[166:169], v[206:209], v[70:73]
	v_mfma_f32_16x16x32_bf16 v[66:69], v[174:177], v[206:209], v[66:69]
	v_mfma_f32_16x16x32_bf16 v[110:113], v[170:173], v[186:189], v[110:113]
	v_mfma_f32_16x16x32_bf16 v[106:109], v[178:181], v[186:189], v[106:109]
	v_mfma_f32_16x16x32_bf16 v[94:97], v[170:173], v[194:197], v[94:97]
	v_mfma_f32_16x16x32_bf16 v[90:93], v[178:181], v[194:197], v[90:93]
	v_mfma_f32_16x16x32_bf16 v[78:81], v[170:173], v[202:205], v[78:81]
	v_mfma_f32_16x16x32_bf16 v[74:77], v[178:181], v[202:205], v[74:77]
	v_mfma_f32_16x16x32_bf16 v[70:73], v[170:173], v[210:213], v[70:73]
	v_mfma_f32_16x16x32_bf16 v[66:69], v[178:181], v[210:213], v[66:69]
	s_setprio 0
	s_barrier
; #define PG8_STAGE(bufoff, gbase, voff) do { _Pragma("unroll") for (int _i = 0; _i < 2; ++_i) \
;         __builtin_amdgcn_global_load_lds((const unsigned*)((const char*)(gbase) + (voff)[_i]), (PG8_LAS unsigned*)(lds + (bufoff) + ldsw + _i * 8192), 16, 0, 0); } while (0)
; #define PG8_LDA(dst, b, h) do { _Pragma("unroll") for (int m = 0; m < 4; ++m) _Pragma("unroll") for (int k = 0; k < 2; ++k) dst[m][k] = *(const PG8_LAS bf16x8*)(lds + PG8_SA(b, h) + aoff + m * 2048 + k * 1024); } while (0)
; #define PG8_MMA(ai, bj, At, Bt) do { __builtin_amdgcn_s_setprio(1); _Pragma("unroll") for (int m = 0; m < 4; ++m) _Pragma("unroll") for (int n = 0; n < 2; ++n) _Pragma("unroll") for (int k = 0; k < 2; ++k) \
;         acc[ai][bj][m][n] = __builtin_amdgcn_mfma_f32_16x16x32_bf16(Bt[n][k], At[m][k], acc[ai][bj][m][n], 0, 0, 0); __builtin_amdgcn_s_setprio(0); } while (0)
; #define PG8_WAIT_V(n) asm volatile("s_waitcnt vmcnt(" #n ")" ::: "memory")
; #define PG8_WAIT_L(n) asm volatile("s_waitcnt lgkmcnt(" #n ")" ::: "memory")
; #define PG8_BAR __builtin_amdgcn_s_barrier()
; #define PG8_SCHED __builtin_amdgcn_sched_barrier(0)
; template <class Epi, class Sched, bool ALIGN_EPI = false, bool SP2 = false>
; __device__ __forceinline__ void gemm_phase(PG8_LAS unsigned char* lds, const Gemm g, const Sched& S, const Epi& E) {
;     ...
;         for (int t = 0; t < nt; t += 2) {
;     ...
;             PG8_LDA(At, 1, 1); PG8_STAGE(PG8_SB(1, 0), b3, voffB); PG8_STAGE(PG8_SB(1, 1), b3 + hstep, voffB); PG8_STAGE(PG8_SA(1, 0), a3, voffA);
;             PG8_WAIT_V(8); PG8_WAIT_L(0); PG8_BAR; PG8_MMA(1, 0, At, B0); PG8_MMA(1, 1, At, B1); PG8_BAR; PG8_SCHED;
	s_mov_b32 m0, s33
	v_lshl_add_u64 v[214:215], v[214:215], 0, s[24:25]
	s_add_u32 s70, s74, 0xb0080
	ds_read_b128 v[182:185], v146 offset:49152
	ds_read_b128 v[186:189], v146 offset:50176
	ds_read_b128 v[190:193], v146 offset:51200
	ds_read_b128 v[194:197], v146 offset:52224
	ds_read_b128 v[198:201], v146 offset:53248
	ds_read_b128 v[202:205], v146 offset:54272
	ds_read_b128 v[206:209], v146 offset:55296
	ds_read_b128 v[210:213], v146 offset:56320
	global_load_lds_dwordx4 v[214:215], off
	v_lshl_add_u64 v[214:215], v[216:217], 0, s[24:25]
	s_mov_b32 m0, s36
	s_addc_u32 s71, s75, 0
	global_load_lds_dwordx4 v[214:215], off
	v_lshl_add_u64 v[214:215], s[70:71], 0, v[130:131]
	s_mov_b32 m0, s48
	s_nop 0
	global_load_lds_dwordx4 v[214:215], off
	v_lshl_add_u64 v[214:215], s[70:71], 0, v[136:137]
	s_mov_b32 m0, s49
	s_nop 0
	global_load_lds_dwordx4 v[214:215], off
	v_lshl_add_u64 v[214:215], v[218:219], 0, s[24:25]
	s_mov_b32 m0, s37
	s_nop 0
	global_load_lds_dwordx4 v[214:215], off
	v_lshl_add_u64 v[214:215], v[220:221], 0, s[24:25]
	s_mov_b32 m0, s40
	s_nop 0
	global_load_lds_dwordx4 v[214:215], off
	s_waitcnt vmcnt(8)
	s_waitcnt lgkmcnt(0)
	s_barrier
	s_setprio 1
	s_waitcnt lgkmcnt(0)
	v_mfma_f32_16x16x32_bf16 v[62:65], v[150:153], v[182:185], v[62:65]
	v_mfma_f32_16x16x32_bf16 v[58:61], v[158:161], v[182:185], v[58:61]
	v_mfma_f32_16x16x32_bf16 v[54:57], v[150:153], v[190:193], v[54:57]
	v_mfma_f32_16x16x32_bf16 v[50:53], v[158:161], v[190:193], v[50:53]
	v_mfma_f32_16x16x32_bf16 v[38:41], v[150:153], v[198:201], v[38:41]
	v_mfma_f32_16x16x32_bf16 v[34:37], v[158:161], v[198:201], v[34:37]
	v_mfma_f32_16x16x32_bf16 v[22:25], v[150:153], v[206:209], v[22:25]
	v_mfma_f32_16x16x32_bf16 v[18:21], v[158:161], v[206:209], v[18:21]
	v_mfma_f32_16x16x32_bf16 v[62:65], v[154:157], v[186:189], v[62:65]
	v_mfma_f32_16x16x32_bf16 v[58:61], v[162:165], v[186:189], v[58:61]
	v_mfma_f32_16x16x32_bf16 v[54:57], v[154:157], v[194:197], v[54:57]
	v_mfma_f32_16x16x32_bf16 v[50:53], v[162:165], v[194:197], v[50:53]
	v_mfma_f32_16x16x32_bf16 v[38:41], v[154:157], v[202:205], v[38:41]
	v_mfma_f32_16x16x32_bf16 v[34:37], v[162:165], v[202:205], v[34:37]
	v_mfma_f32_16x16x32_bf16 v[22:25], v[154:157], v[210:213], v[22:25]
	v_mfma_f32_16x16x32_bf16 v[18:21], v[162:165], v[210:213], v[18:21]
	s_setprio 0
	s_setprio 1
	v_mfma_f32_16x16x32_bf16 v[46:49], v[166:169], v[182:185], v[46:49]
	v_mfma_f32_16x16x32_bf16 v[42:45], v[174:177], v[182:185], v[42:45]
	v_mfma_f32_16x16x32_bf16 v[30:33], v[166:169], v[190:193], v[30:33]
	v_mfma_f32_16x16x32_bf16 v[26:29], v[174:177], v[190:193], v[26:29]
	v_mfma_f32_16x16x32_bf16 v[14:17], v[166:169], v[198:201], v[14:17]
	v_mfma_f32_16x16x32_bf16 v[10:13], v[174:177], v[198:201], v[10:13]
	v_mfma_f32_16x16x32_bf16 v[6:9], v[166:169], v[206:209], v[6:9]
	v_mfma_f32_16x16x32_bf16 v[2:5], v[174:177], v[206:209], v[2:5]
	v_mfma_f32_16x16x32_bf16 v[46:49], v[170:173], v[186:189], v[46:49]
	v_mfma_f32_16x16x32_bf16 v[42:45], v[178:181], v[186:189], v[42:45]
	v_mfma_f32_16x16x32_bf16 v[30:33], v[170:173], v[194:197], v[30:33]
	v_mfma_f32_16x16x32_bf16 v[26:29], v[178:181], v[194:197], v[26:29]
	v_mfma_f32_16x16x32_bf16 v[14:17], v[170:173], v[202:205], v[14:17]
	v_mfma_f32_16x16x32_bf16 v[10:13], v[178:181], v[202:205], v[10:13]
	v_mfma_f32_16x16x32_bf16 v[6:9], v[170:173], v[210:213], v[6:9]
	v_mfma_f32_16x16x32_bf16 v[2:5], v[178:181], v[210:213], v[2:5]
	s_setprio 0
	s_barrier
	s_add_u32 vcc_lo, vcc_lo, 0x100
	s_addc_u32 vcc_hi, vcc_hi, 0
	s_cmp_ge_u32 s38, s93
	s_mov_b64 s[70:71], s[72:73]
	s_mov_b32 s74, s38

; #define PG8_STAGE(bufoff, gbase, voff) do { _Pragma("unroll") for (int _i = 0; _i < 2; ++_i) \
;         __builtin_amdgcn_global_load_lds((const unsigned*)((const char*)(gbase) + (voff)[_i]), (PG8_LAS unsigned*)(lds + (bufoff) + ldsw + _i * 8192), 16, 0, 0); } while (0)
; #define PG8_LDA(dst, b, h) do { _Pragma("unroll") for (int m = 0; m < 4; ++m) _Pragma("unroll") for (int k = 0; k < 2; ++k) dst[m][k] = *(const PG8_LAS bf16x8*)(lds + PG8_SA(b, h) + aoff + m * 2048 + k * 1024); } while (0)
; #define PG8_LDB(dst, b, h) do { _Pragma("unroll") for (int n = 0; n < 2; ++n) _Pragma("unroll") for (int k = 0; k < 2; ++k) dst[n][k] = *(const PG8_LAS bf16x8*)(lds + PG8_SB(b, h) + boff + n * 2048 + k * 1024); } while (0)
; #define PG8_MMA(ai, bj, At, Bt) do { __builtin_amdgcn_s_setprio(1); _Pragma("unroll") for (int m = 0; m < 4; ++m) _Pragma("unroll") for (int n = 0; n < 2; ++n) _Pragma("unroll") for (int k = 0; k < 2; ++k) \
;         acc[ai][bj][m][n] = __builtin_amdgcn_mfma_f32_16x16x32_bf16(Bt[n][k], At[m][k], acc[ai][bj][m][n], 0, 0, 0); __builtin_amdgcn_s_setprio(0); } while (0)
; template <class Epi, class Sched, bool ALIGN_EPI = false, bool SP2 = false>
; __device__ __forceinline__ void gemm_phase(PG8_LAS unsigned char* lds, const Gemm g, const Sched& S, const Epi& E) {
;     ...
;         const bool has_next = S.next(ui + 1, nxt);
;         const char* nA = has_next ? (const char*)g.A + (size_t)nxt.pm * tstep + (size_t)nxt.ks * K * 2 : cA; const char* nB = has_next ? (const char*)g.Bt + (size_t)nxt.pn * tstep + (size_t)nxt.ks * K * 2 : cB;
;         for (int t = 0; t < nt; t += 2) {
;             const bool last = (t == nt - 2);
;             const char* a1 = cA + (size_t)(t + 1) * kstep;
;             const char* a2 = last ? nA : cA + (size_t)(t + 2) * kstep; const char* b2 = last ? nB : cB + (size_t)(t + 2) * kstep;
;             const char* a3 = a2 + kstep; const char* b3 = b2 + kstep;
;             if (last && has_next) S.a_ready(nxt);
;             if constexpr (SP2) {
;             PG8_LDB(B0, 0, 0); PG8_LDB(B1, 0, 1); PG8_SCHED; PG8_LDA(At, 0, 0); PG8_STAGE(PG8_SA(1, 1), a1 + hstep, voffA);
;             PG8_WAIT_V(8); PG8_WAIT_L(0); PG8_BAR; PG8_MMA(0, 0, At, B0); PG8_MMA(0, 1, At, B1); PG8_BAR; PG8_SCHED;
;             PG8_LDA(At, 0, 1); PG8_STAGE(PG8_SB(0, 0), b2, voffB); PG8_STAGE(PG8_SB(0, 1), b2 + hstep, voffB); PG8_STAGE(PG8_SA(0, 0), a2, voffA);
.LBB0_516:
	s_ashr_i32 s39, s38, 31
	s_lshl_b64 s[40:41], s[38:39], 19
	s_add_u32 s40, s28, s40
	s_addc_u32 s41, s29, s41
	s_and_b64 s[42:43], s[2:3], exec
	s_cselect_b32 s33, s41, s53
	s_cselect_b32 s39, s40, s52
	s_ashr_i32 s37, s36, 31
	s_lshl_b64 s[42:43], s[36:37], 19
	s_add_u32 s42, s30, s42
	s_addc_u32 s43, s31, s43
	s_and_b64 s[48:49], s[2:3], exec
	s_cselect_b32 s37, s43, s47
	s_cselect_b32 s45, s42, s46
	s_add_u32 s48, s46, 0x100
	s_addc_u32 s49, s47, 0
	s_add_u32 s46, s52, 0x40080
	s_addc_u32 s47, s53, 0
	s_mov_b32 s50, -2
	ds_read_b128 v[148:151], v161
	ds_read_b128 v[152:155], v161 offset:1024
	ds_read_b128 v[166:169], v161 offset:2048
	ds_read_b128 v[170:173], v161 offset:3072
	ds_read_b128 v[174:177], v162
	ds_read_b128 v[178:181], v162 offset:1024
	ds_read_b128 v[182:185], v162 offset:2048
	ds_read_b128 v[186:189], v162 offset:3072
	s_add_u32 s51, s46, 0xfffc0080
	s_addc_u32 s52, s47, -1
	s_cmp_eq_u32 s50, 12
	s_cselect_b32 s57, s33, s52
	s_cselect_b32 s56, s39, s51
	s_cselect_b32 s53, s37, s49
	s_cselect_b32 s52, s45, s48
	v_lshl_add_u64 v[156:157], s[46:47], 0, v[142:143]
	s_add_i32 m0, s66, 0xc000
	ds_read_b128 v[190:193], v163
	ds_read_b128 v[194:197], v163 offset:1024
	ds_read_b128 v[198:201], v163 offset:2048
	ds_read_b128 v[202:205], v163 offset:3072
	ds_read_b128 v[206:209], v163 offset:4096
	ds_read_b128 v[210:213], v163 offset:5120
	ds_read_b128 v[214:217], v163 offset:6144
	ds_read_b128 v[218:221], v163 offset:7168
	global_load_lds_dwordx4 v[156:157], off
	v_lshl_add_u64 v[156:157], s[46:47], 0, v[140:141]
	s_add_i32 m0, s66, 0xe000
	s_nop 0
	global_load_lds_dwordx4 v[156:157], off
	s_waitcnt vmcnt(8)
	s_waitcnt lgkmcnt(0)
	s_barrier
	s_setprio 1
	s_waitcnt lgkmcnt(0)
	v_mfma_f32_16x16x32_bf16 v[126:129], v[148:151], v[190:193], 0
	v_mfma_f32_16x16x32_bf16 v[122:125], v[166:169], v[190:193], 0
	v_mfma_f32_16x16x32_bf16 v[118:121], v[148:151], v[198:201], 0
	v_mfma_f32_16x16x32_bf16 v[114:117], v[166:169], v[198:201], 0
	v_mfma_f32_16x16x32_bf16 v[102:105], v[148:151], v[206:209], 0
	v_mfma_f32_16x16x32_bf16 v[98:101], v[166:169], v[206:209], 0
	v_mfma_f32_16x16x32_bf16 v[86:89], v[148:151], v[214:217], 0
	v_mfma_f32_16x16x32_bf16 v[82:85], v[166:169], v[214:217], 0
	v_mfma_f32_16x16x32_bf16 v[126:129], v[152:155], v[194:197], v[126:129]
	v_mfma_f32_16x16x32_bf16 v[122:125], v[170:173], v[194:197], v[122:125]
	v_mfma_f32_16x16x32_bf16 v[118:121], v[152:155], v[202:205], v[118:121]
	v_mfma_f32_16x16x32_bf16 v[114:117], v[170:173], v[202:205], v[114:117]
	v_mfma_f32_16x16x32_bf16 v[102:105], v[152:155], v[210:213], v[102:105]
	v_mfma_f32_16x16x32_bf16 v[98:101], v[170:173], v[210:213], v[98:101]
	v_mfma_f32_16x16x32_bf16 v[86:89], v[152:155], v[218:221], v[86:89]
	v_mfma_f32_16x16x32_bf16 v[82:85], v[170:173], v[218:221], v[82:85]
	s_setprio 0
	s_setprio 1
	v_mfma_f32_16x16x32_bf16 v[110:113], v[174:177], v[190:193], 0
	v_mfma_f32_16x16x32_bf16 v[106:109], v[182:185], v[190:193], 0
	v_mfma_f32_16x16x32_bf16 v[94:97], v[174:177], v[198:201], 0
	v_mfma_f32_16x16x32_bf16 v[90:93], v[182:185], v[198:201], 0
	v_mfma_f32_16x16x32_bf16 v[78:81], v[174:177], v[206:209], 0
	v_mfma_f32_16x16x32_bf16 v[74:77], v[182:185], v[206:209], 0
	v_mfma_f32_16x16x32_bf16 v[70:73], v[174:177], v[214:217], 0
	v_mfma_f32_16x16x32_bf16 v[66:69], v[182:185], v[214:217], 0
	v_mfma_f32_16x16x32_bf16 v[110:113], v[178:181], v[194:197], v[110:113]
	v_mfma_f32_16x16x32_bf16 v[106:109], v[186:189], v[194:197], v[106:109]
	v_mfma_f32_16x16x32_bf16 v[94:97], v[178:181], v[202:205], v[94:97]
	v_mfma_f32_16x16x32_bf16 v[90:93], v[186:189], v[202:205], v[90:93]
	v_mfma_f32_16x16x32_bf16 v[78:81], v[178:181], v[210:213], v[78:81]
	v_mfma_f32_16x16x32_bf16 v[74:77], v[186:189], v[210:213], v[74:77]
	v_mfma_f32_16x16x32_bf16 v[70:73], v[178:181], v[218:221], v[70:73]
	v_mfma_f32_16x16x32_bf16 v[66:69], v[186:189], v[218:221], v[66:69]
	s_setprio 0
	s_barrier
	s_mov_b32 m0, s62
	v_lshl_add_u64 v[156:157], s[52:53], 0, v[134:135]
	s_add_u32 s54, s52, 0x40000
	ds_read_b128 v[190:193], v163 offset:16384
	ds_read_b128 v[194:197], v163 offset:17408
	ds_read_b128 v[198:201], v163 offset:18432
	ds_read_b128 v[202:205], v163 offset:19456
	ds_read_b128 v[206:209], v163 offset:20480
	ds_read_b128 v[210:213], v163 offset:21504
	ds_read_b128 v[214:217], v163 offset:22528
	ds_read_b128 v[218:221], v163 offset:23552
	global_load_lds_dwordx4 v[156:157], off
	v_lshl_add_u64 v[222:223], s[52:53], 0, v[130:131]
	s_mov_b32 m0, s63
	s_addc_u32 s55, s53, 0
	global_load_lds_dwordx4 v[222:223], off
	v_lshl_add_u64 v[224:225], s[54:55], 0, v[134:135]
	s_mov_b32 m0, s64
	v_lshl_add_u64 v[226:227], s[56:57], 0, v[132:133]
	global_load_lds_dwordx4 v[224:225], off
	v_lshl_add_u64 v[224:225], s[54:55], 0, v[130:131]
	s_mov_b32 m0, s65
	s_nop 0
	global_load_lds_dwordx4 v[224:225], off
	v_lshl_add_u64 v[224:225], s[56:57], 0, v[136:137]
	s_mov_b32 m0, s66
	s_nop 0
	global_load_lds_dwordx4 v[224:225], off
	s_mov_b32 m0, s67
	s_nop 0
	global_load_lds_dwordx4 v[226:227], off
	s_waitcnt vmcnt(8)
	s_waitcnt lgkmcnt(0)
	s_barrier
; #define PG8_STAGE(bufoff, gbase, voff) do { _Pragma("unroll") for (int _i = 0; _i < 2; ++_i) \
;         __builtin_amdgcn_global_load_lds((const unsigned*)((const char*)(gbase) + (voff)[_i]), (PG8_LAS unsigned*)(lds + (bufoff) + ldsw + _i * 8192), 16, 0, 0); } while (0)
; #define PG8_LDA(dst, b, h) do { _Pragma("unroll") for (int m = 0; m < 4; ++m) _Pragma("unroll") for (int k = 0; k < 2; ++k) dst[m][k] = *(const PG8_LAS bf16x8*)(lds + PG8_SA(b, h) + aoff + m * 2048 + k * 1024); } while (0)
; #define PG8_LDB(dst, b, h) do { _Pragma("unroll") for (int n = 0; n < 2; ++n) _Pragma("unroll") for (int k = 0; k < 2; ++k) dst[n][k] = *(const PG8_LAS bf16x8*)(lds + PG8_SB(b, h) + boff + n * 2048 + k * 1024); } while (0)
; #define PG8_MMA(ai, bj, At, Bt) do { __builtin_amdgcn_s_setprio(1); _Pragma("unroll") for (int m = 0; m < 4; ++m) _Pragma("unroll") for (int n = 0; n < 2; ++n) _Pragma("unroll") for (int k = 0; k < 2; ++k) \
;         acc[ai][bj][m][n] = __builtin_amdgcn_mfma_f32_16x16x32_bf16(Bt[n][k], At[m][k], acc[ai][bj][m][n], 0, 0, 0); __builtin_amdgcn_s_setprio(0); } while (0)
; #define PG8_WAIT_V(n) asm volatile("s_waitcnt vmcnt(" #n ")" ::: "memory")
; #define PG8_WAIT_L(n) asm volatile("s_waitcnt lgkmcnt(" #n ")" ::: "memory")
; #define PG8_BAR __builtin_amdgcn_s_barrier()
; #define PG8_SCHED __builtin_amdgcn_sched_barrier(0)
; template <class Epi, class Sched, bool ALIGN_EPI = false, bool SP2 = false>
; __device__ __forceinline__ void gemm_phase(PG8_LAS unsigned char* lds, const Gemm g, const Sched& S, const Epi& E) {
;     ...
;             PG8_WAIT_V(8); PG8_WAIT_L(0); PG8_BAR; PG8_MMA(1, 0, At, B0); PG8_MMA(1, 1, At, B1); PG8_BAR; PG8_SCHED;
;             PG8_LDB(B0, 1, 0); PG8_LDB(B1, 1, 1); PG8_SCHED; PG8_LDA(At, 1, 0); PG8_STAGE(PG8_SA(0, 1), a2 + hstep, voffA);
;             PG8_WAIT_V(8); PG8_WAIT_L(0); PG8_BAR; PG8_MMA(0, 0, At, B0); PG8_MMA(0, 1, At, B1); PG8_BAR; PG8_SCHED;
	s_setprio 1
	s_waitcnt lgkmcnt(0)
	v_mfma_f32_16x16x32_bf16 v[62:65], v[148:151], v[190:193], 0
	v_mfma_f32_16x16x32_bf16 v[58:61], v[166:169], v[190:193], 0
	v_mfma_f32_16x16x32_bf16 v[54:57], v[148:151], v[198:201], 0
	v_mfma_f32_16x16x32_bf16 v[50:53], v[166:169], v[198:201], 0
	v_mfma_f32_16x16x32_bf16 v[38:41], v[148:151], v[206:209], 0
	v_mfma_f32_16x16x32_bf16 v[34:37], v[166:169], v[206:209], 0
	v_mfma_f32_16x16x32_bf16 v[22:25], v[148:151], v[214:217], 0
	v_mfma_f32_16x16x32_bf16 v[18:21], v[166:169], v[214:217], 0
	v_mfma_f32_16x16x32_bf16 v[62:65], v[152:155], v[194:197], v[62:65]
	v_mfma_f32_16x16x32_bf16 v[58:61], v[170:173], v[194:197], v[58:61]
	v_mfma_f32_16x16x32_bf16 v[54:57], v[152:155], v[202:205], v[54:57]
	v_mfma_f32_16x16x32_bf16 v[50:53], v[170:173], v[202:205], v[50:53]
	v_mfma_f32_16x16x32_bf16 v[38:41], v[152:155], v[210:213], v[38:41]
	v_mfma_f32_16x16x32_bf16 v[34:37], v[170:173], v[210:213], v[34:37]
	v_mfma_f32_16x16x32_bf16 v[22:25], v[152:155], v[218:221], v[22:25]
	v_mfma_f32_16x16x32_bf16 v[18:21], v[170:173], v[218:221], v[18:21]
	s_setprio 0
	s_setprio 1
	v_mfma_f32_16x16x32_bf16 v[46:49], v[174:177], v[190:193], 0
	v_mfma_f32_16x16x32_bf16 v[42:45], v[182:185], v[190:193], 0
	v_mfma_f32_16x16x32_bf16 v[30:33], v[174:177], v[198:201], 0
	v_mfma_f32_16x16x32_bf16 v[26:29], v[182:185], v[198:201], 0
	v_mfma_f32_16x16x32_bf16 v[14:17], v[174:177], v[206:209], 0
	v_mfma_f32_16x16x32_bf16 v[10:13], v[182:185], v[206:209], 0
	v_mfma_f32_16x16x32_bf16 v[6:9], v[174:177], v[214:217], 0
	v_mfma_f32_16x16x32_bf16 v[2:5], v[182:185], v[214:217], 0
	v_mfma_f32_16x16x32_bf16 v[46:49], v[178:181], v[194:197], v[46:49]
	v_mfma_f32_16x16x32_bf16 v[42:45], v[186:189], v[194:197], v[42:45]
	v_mfma_f32_16x16x32_bf16 v[30:33], v[178:181], v[202:205], v[30:33]
	v_mfma_f32_16x16x32_bf16 v[26:29], v[186:189], v[202:205], v[26:29]
	v_mfma_f32_16x16x32_bf16 v[14:17], v[178:181], v[210:213], v[14:17]
	v_mfma_f32_16x16x32_bf16 v[10:13], v[186:189], v[210:213], v[10:13]
	v_mfma_f32_16x16x32_bf16 v[6:9], v[178:181], v[218:221], v[6:9]
	v_mfma_f32_16x16x32_bf16 v[2:5], v[186:189], v[218:221], v[2:5]
	s_setprio 0
	s_barrier
	ds_read_b128 v[148:151], v164
	ds_read_b128 v[152:155], v164 offset:1024
	ds_read_b128 v[166:169], v164 offset:2048
	ds_read_b128 v[170:173], v164 offset:3072
	ds_read_b128 v[174:177], v165
	ds_read_b128 v[178:181], v165 offset:1024
	ds_read_b128 v[182:185], v165 offset:2048
	ds_read_b128 v[186:189], v165 offset:3072
	s_add_u32 s54, s56, 0x40000
	s_addc_u32 s55, s57, 0
	s_mov_b32 m0, s68
	v_lshl_add_u64 v[228:229], s[54:55], 0, v[136:137]
	ds_read_b128 v[190:193], v163 offset:32768
	ds_read_b128 v[194:197], v163 offset:33792
	ds_read_b128 v[198:201], v163 offset:34816
	ds_read_b128 v[202:205], v163 offset:35840
	ds_read_b128 v[206:209], v163 offset:36864
	ds_read_b128 v[210:213], v163 offset:37888
	ds_read_b128 v[214:217], v163 offset:38912
	ds_read_b128 v[218:221], v163 offset:39936
	global_load_lds_dwordx4 v[228:229], off
	v_lshl_add_u64 v[228:229], s[54:55], 0, v[132:133]
	s_mov_b32 m0, s69
	s_nop 0
	global_load_lds_dwordx4 v[228:229], off
	s_waitcnt vmcnt(8)
	s_waitcnt lgkmcnt(0)
	s_barrier
	s_setprio 1
	s_waitcnt lgkmcnt(0)
	v_mfma_f32_16x16x32_bf16 v[126:129], v[148:151], v[190:193], v[126:129]
	v_mfma_f32_16x16x32_bf16 v[122:125], v[166:169], v[190:193], v[122:125]
	v_mfma_f32_16x16x32_bf16 v[118:121], v[148:151], v[198:201], v[118:121]
	v_mfma_f32_16x16x32_bf16 v[114:117], v[166:169], v[198:201], v[114:117]
	v_mfma_f32_16x16x32_bf16 v[102:105], v[148:151], v[206:209], v[102:105]
	v_mfma_f32_16x16x32_bf16 v[98:101], v[166:169], v[206:209], v[98:101]
	v_mfma_f32_16x16x32_bf16 v[86:89], v[148:151], v[214:217], v[86:89]
	v_mfma_f32_16x16x32_bf16 v[82:85], v[166:169], v[214:217], v[82:85]
	v_mfma_f32_16x16x32_bf16 v[126:129], v[152:155], v[194:197], v[126:129]
	v_mfma_f32_16x16x32_bf16 v[122:125], v[170:173], v[194:197], v[122:125]
	v_mfma_f32_16x16x32_bf16 v[118:121], v[152:155], v[202:205], v[118:121]
	v_mfma_f32_16x16x32_bf16 v[114:117], v[170:173], v[202:205], v[114:117]
	v_mfma_f32_16x16x32_bf16 v[102:105], v[152:155], v[210:213], v[102:105]
	v_mfma_f32_16x16x32_bf16 v[98:101], v[170:173], v[210:213], v[98:101]
	v_mfma_f32_16x16x32_bf16 v[86:89], v[152:155], v[218:221], v[86:89]
	v_mfma_f32_16x16x32_bf16 v[82:85], v[170:173], v[218:221], v[82:85]
	s_setprio 0
	s_setprio 1
	v_mfma_f32_16x16x32_bf16 v[110:113], v[174:177], v[190:193], v[110:113]
	v_mfma_f32_16x16x32_bf16 v[106:109], v[182:185], v[190:193], v[106:109]
	v_mfma_f32_16x16x32_bf16 v[94:97], v[174:177], v[198:201], v[94:97]
	v_mfma_f32_16x16x32_bf16 v[90:93], v[182:185], v[198:201], v[90:93]
	v_mfma_f32_16x16x32_bf16 v[78:81], v[174:177], v[206:209], v[78:81]
	v_mfma_f32_16x16x32_bf16 v[74:77], v[182:185], v[206:209], v[74:77]
	v_mfma_f32_16x16x32_bf16 v[70:73], v[174:177], v[214:217], v[70:73]
	v_mfma_f32_16x16x32_bf16 v[66:69], v[182:185], v[214:217], v[66:69]
	v_mfma_f32_16x16x32_bf16 v[110:113], v[178:181], v[194:197], v[110:113]
	v_mfma_f32_16x16x32_bf16 v[106:109], v[186:189], v[194:197], v[106:109]
	v_mfma_f32_16x16x32_bf16 v[94:97], v[178:181], v[202:205], v[94:97]
	v_mfma_f32_16x16x32_bf16 v[90:93], v[186:189], v[202:205], v[90:93]
	v_mfma_f32_16x16x32_bf16 v[78:81], v[178:181], v[210:213], v[78:81]
	v_mfma_f32_16x16x32_bf16 v[74:77], v[186:189], v[210:213], v[74:77]
	v_mfma_f32_16x16x32_bf16 v[70:73], v[178:181], v[218:221], v[70:73]
	v_mfma_f32_16x16x32_bf16 v[66:69], v[186:189], v[218:221], v[66:69]
	s_setprio 0
	s_barrier
; #define PG8_STAGE(bufoff, gbase, voff) do { _Pragma("unroll") for (int _i = 0; _i < 2; ++_i) \
;         __builtin_amdgcn_global_load_lds((const unsigned*)((const char*)(gbase) + (voff)[_i]), (PG8_LAS unsigned*)(lds + (bufoff) + ldsw + _i * 8192), 16, 0, 0); } while (0)
; #define PG8_LDA(dst, b, h) do { _Pragma("unroll") for (int m = 0; m < 4; ++m) _Pragma("unroll") for (int k = 0; k < 2; ++k) dst[m][k] = *(const PG8_LAS bf16x8*)(lds + PG8_SA(b, h) + aoff + m * 2048 + k * 1024); } while (0)
; #define PG8_MMA(ai, bj, At, Bt) do { __builtin_amdgcn_s_setprio(1); _Pragma("unroll") for (int m = 0; m < 4; ++m) _Pragma("unroll") for (int n = 0; n < 2; ++n) _Pragma("unroll") for (int k = 0; k < 2; ++k) \
;         acc[ai][bj][m][n] = __builtin_amdgcn_mfma_f32_16x16x32_bf16(Bt[n][k], At[m][k], acc[ai][bj][m][n], 0, 0, 0); __builtin_amdgcn_s_setprio(0); } while (0)
; #define PG8_WAIT_V(n) asm volatile("s_waitcnt vmcnt(" #n ")" ::: "memory")
; #define PG8_WAIT_L(n) asm volatile("s_waitcnt lgkmcnt(" #n ")" ::: "memory")
; #define PG8_BAR __builtin_amdgcn_s_barrier()
; #define PG8_SCHED __builtin_amdgcn_sched_barrier(0)
; template <class Epi, class Sched, bool ALIGN_EPI = false, bool SP2 = false>
; __device__ __forceinline__ void gemm_phase(PG8_LAS unsigned char* lds, const Gemm g, const Sched& S, const Epi& E) {
;     ...
;         for (int t = 0; t < nt; t += 2) {
;     ...
;             PG8_LDA(At, 1, 1); PG8_STAGE(PG8_SB(1, 0), b3, voffB); PG8_STAGE(PG8_SB(1, 1), b3 + hstep, voffB); PG8_STAGE(PG8_SA(1, 0), a3, voffA);
;             PG8_WAIT_V(8); PG8_WAIT_L(0); PG8_BAR; PG8_MMA(1, 0, At, B0); PG8_MMA(1, 1, At, B1); PG8_BAR; PG8_SCHED;
	s_mov_b32 m0, s70
	v_lshl_add_u64 v[156:157], v[156:157], 0, s[8:9]
	s_add_u32 s52, s52, 0x40080
	ds_read_b128 v[190:193], v163 offset:49152
	ds_read_b128 v[194:197], v163 offset:50176
	ds_read_b128 v[198:201], v163 offset:51200
	ds_read_b128 v[202:205], v163 offset:52224
	ds_read_b128 v[206:209], v163 offset:53248
	ds_read_b128 v[210:213], v163 offset:54272
	ds_read_b128 v[214:217], v163 offset:55296
	ds_read_b128 v[218:221], v163 offset:56320
	global_load_lds_dwordx4 v[156:157], off
	v_lshl_add_u64 v[156:157], v[222:223], 0, s[8:9]
	s_mov_b32 m0, s71
	s_addc_u32 s53, s53, 0
	global_load_lds_dwordx4 v[156:157], off
	v_lshl_add_u64 v[156:157], s[52:53], 0, v[134:135]
	s_mov_b32 m0, s74
	s_nop 0
	global_load_lds_dwordx4 v[156:157], off
	v_lshl_add_u64 v[156:157], s[52:53], 0, v[130:131]
	s_mov_b32 m0, s75
	s_nop 0
	global_load_lds_dwordx4 v[156:157], off
	v_lshl_add_u64 v[156:157], v[224:225], 0, s[8:9]
	s_mov_b32 m0, s72
	s_nop 0
	global_load_lds_dwordx4 v[156:157], off
	v_lshl_add_u64 v[156:157], v[226:227], 0, s[8:9]
	s_mov_b32 m0, s73
	s_nop 0
	global_load_lds_dwordx4 v[156:157], off
	s_waitcnt vmcnt(8)
	s_waitcnt lgkmcnt(0)
	s_barrier
	s_setprio 1
	s_waitcnt lgkmcnt(0)
	v_mfma_f32_16x16x32_bf16 v[62:65], v[148:151], v[190:193], v[62:65]
	v_mfma_f32_16x16x32_bf16 v[58:61], v[166:169], v[190:193], v[58:61]
	v_mfma_f32_16x16x32_bf16 v[54:57], v[148:151], v[198:201], v[54:57]
	v_mfma_f32_16x16x32_bf16 v[50:53], v[166:169], v[198:201], v[50:53]
	v_mfma_f32_16x16x32_bf16 v[38:41], v[148:151], v[206:209], v[38:41]
	v_mfma_f32_16x16x32_bf16 v[34:37], v[166:169], v[206:209], v[34:37]
	v_mfma_f32_16x16x32_bf16 v[22:25], v[148:151], v[214:217], v[22:25]
	v_mfma_f32_16x16x32_bf16 v[18:21], v[166:169], v[214:217], v[18:21]
	v_mfma_f32_16x16x32_bf16 v[62:65], v[152:155], v[194:197], v[62:65]
	v_mfma_f32_16x16x32_bf16 v[58:61], v[170:173], v[194:197], v[58:61]
	v_mfma_f32_16x16x32_bf16 v[54:57], v[152:155], v[202:205], v[54:57]
	v_mfma_f32_16x16x32_bf16 v[50:53], v[170:173], v[202:205], v[50:53]
	v_mfma_f32_16x16x32_bf16 v[38:41], v[152:155], v[210:213], v[38:41]
	v_mfma_f32_16x16x32_bf16 v[34:37], v[170:173], v[210:213], v[34:37]
	v_mfma_f32_16x16x32_bf16 v[22:25], v[152:155], v[218:221], v[22:25]
	v_mfma_f32_16x16x32_bf16 v[18:21], v[170:173], v[218:221], v[18:21]
	s_setprio 0
	s_setprio 1
	v_mfma_f32_16x16x32_bf16 v[46:49], v[174:177], v[190:193], v[46:49]
	v_mfma_f32_16x16x32_bf16 v[42:45], v[182:185], v[190:193], v[42:45]
	v_mfma_f32_16x16x32_bf16 v[30:33], v[174:177], v[198:201], v[30:33]
	v_mfma_f32_16x16x32_bf16 v[26:29], v[182:185], v[198:201], v[26:29]
	v_mfma_f32_16x16x32_bf16 v[14:17], v[174:177], v[206:209], v[14:17]
	v_mfma_f32_16x16x32_bf16 v[10:13], v[182:185], v[206:209], v[10:13]
	v_mfma_f32_16x16x32_bf16 v[6:9], v[174:177], v[214:217], v[6:9]
	v_mfma_f32_16x16x32_bf16 v[2:5], v[182:185], v[214:217], v[2:5]
	v_mfma_f32_16x16x32_bf16 v[46:49], v[178:181], v[194:197], v[46:49]
	v_mfma_f32_16x16x32_bf16 v[42:45], v[186:189], v[194:197], v[42:45]
	v_mfma_f32_16x16x32_bf16 v[30:33], v[178:181], v[202:205], v[30:33]
	v_mfma_f32_16x16x32_bf16 v[26:29], v[186:189], v[202:205], v[26:29]
	v_mfma_f32_16x16x32_bf16 v[14:17], v[178:181], v[210:213], v[14:17]
	v_mfma_f32_16x16x32_bf16 v[10:13], v[186:189], v[210:213], v[10:13]
	v_mfma_f32_16x16x32_bf16 v[6:9], v[178:181], v[218:221], v[6:9]
	v_mfma_f32_16x16x32_bf16 v[2:5], v[186:189], v[218:221], v[2:5]
	s_setprio 0
	s_barrier
	s_add_i32 s50, s50, 2
	s_add_u32 s48, s48, 0x100
	s_addc_u32 s49, s49, 0
	s_add_u32 s46, s46, 0x100
	s_addc_u32 s47, s47, 0
	s_cmp_gt_u32 s50, 13

; #define PG8_STAGE(bufoff, gbase, voff) do { _Pragma("unroll") for (int _i = 0; _i < 2; ++_i) \
;         __builtin_amdgcn_global_load_lds((const unsigned*)((const char*)(gbase) + (voff)[_i]), (PG8_LAS unsigned*)(lds + (bufoff) + ldsw + _i * 8192), 16, 0, 0); } while (0)
; #define PG8_LDA(dst, b, h) do { _Pragma("unroll") for (int m = 0; m < 4; ++m) _Pragma("unroll") for (int k = 0; k < 2; ++k) dst[m][k] = *(const PG8_LAS bf16x8*)(lds + PG8_SA(b, h) + aoff + m * 2048 + k * 1024); } while (0)
; #define PG8_LDB(dst, b, h) do { _Pragma("unroll") for (int n = 0; n < 2; ++n) _Pragma("unroll") for (int k = 0; k < 2; ++k) dst[n][k] = *(const PG8_LAS bf16x8*)(lds + PG8_SB(b, h) + boff + n * 2048 + k * 1024); } while (0)
; #define PG8_MMA(ai, bj, At, Bt) do { __builtin_amdgcn_s_setprio(1); _Pragma("unroll") for (int m = 0; m < 4; ++m) _Pragma("unroll") for (int n = 0; n < 2; ++n) _Pragma("unroll") for (int k = 0; k < 2; ++k) \
;         acc[ai][bj][m][n] = __builtin_amdgcn_mfma_f32_16x16x32_bf16(Bt[n][k], At[m][k], acc[ai][bj][m][n], 0, 0, 0); __builtin_amdgcn_s_setprio(0); } while (0)
; #define PG8_WAIT_V(n) asm volatile("s_waitcnt vmcnt(" #n ")" ::: "memory")
; #define PG8_WAIT_L(n) asm volatile("s_waitcnt lgkmcnt(" #n ")" ::: "memory")
; #define PG8_BAR __builtin_amdgcn_s_barrier()
; #define PG8_SCHED __builtin_amdgcn_sched_barrier(0)
; template <class Epi, class Sched, bool ALIGN_EPI = false, bool SP2 = false>
; __device__ __forceinline__ void gemm_phase(PG8_LAS unsigned char* lds, const Gemm g, const Sched& S, const Epi& E) {
;     ...
;         for (int t = 0; t < nt; t += 2) {
;             const bool last = (t == nt - 2);
;             const char* a1 = cA + (size_t)(t + 1) * kstep;
;             const char* a2 = last ? nA : cA + (size_t)(t + 2) * kstep; const char* b2 = last ? nB : cB + (size_t)(t + 2) * kstep;
;             const char* a3 = a2 + kstep; const char* b3 = b2 + kstep;
;             if (last && has_next) S.a_ready(nxt);
;             if constexpr (SP2) {
;             PG8_LDB(B0, 0, 0); PG8_LDB(B1, 0, 1); PG8_SCHED; PG8_LDA(At, 0, 0); PG8_STAGE(PG8_SA(1, 1), a1 + hstep, voffA);
;             PG8_WAIT_V(8); PG8_WAIT_L(0); PG8_BAR; PG8_MMA(0, 0, At, B0); PG8_MMA(0, 1, At, B1); PG8_BAR; PG8_SCHED;
;             PG8_LDA(At, 0, 1); PG8_STAGE(PG8_SB(0, 0), b2, voffB); PG8_STAGE(PG8_SB(0, 1), b2 + hstep, voffB); PG8_STAGE(PG8_SA(0, 0), a2, voffA);
.LBB0_702:
	s_add_u32 s58, s70, 0x100
	s_addc_u32 s59, s71, 0
	s_add_u32 s70, s72, 0x80
	s_addc_u32 s71, s73, 0
	s_mov_b32 s72, 0
	ds_read_b128 v[152:155], v149
	ds_read_b128 v[156:159], v149 offset:1024
	ds_read_b128 v[160:163], v149 offset:2048
	ds_read_b128 v[164:167], v149 offset:3072
	ds_read_b128 v[168:171], v150
	ds_read_b128 v[172:175], v150 offset:1024
	ds_read_b128 v[176:179], v150 offset:2048
	ds_read_b128 v[180:183], v150 offset:3072
	s_add_i32 vcc_lo, s72, 2
	s_add_u32 s30, s70, 0x80
	s_addc_u32 s31, s71, 0
	s_cmp_eq_u32 s95, s72
	s_cselect_b32 s72, s60, s30
	s_cselect_b32 s73, s61, s31
	s_cselect_b32 s31, s69, s59
	s_cselect_b32 s30, s68, s58
	v_lshl_add_u64 v[142:143], s[70:71], 0, v[140:141]
	s_add_i32 m0, s83, 0xc000
	ds_read_b128 v[184:187], v148
	ds_read_b128 v[188:191], v148 offset:1024
	ds_read_b128 v[192:195], v148 offset:2048
	ds_read_b128 v[196:199], v148 offset:3072
	ds_read_b128 v[200:203], v148 offset:4096
	ds_read_b128 v[204:207], v148 offset:5120
	ds_read_b128 v[208:211], v148 offset:6144
	ds_read_b128 v[212:215], v148 offset:7168
	global_load_lds_dwordx4 v[142:143], off
	v_lshl_add_u64 v[142:143], s[70:71], 0, v[138:139]
	s_add_i32 m0, s83, 0xe000
	s_nop 0
	global_load_lds_dwordx4 v[142:143], off
	s_waitcnt vmcnt(8)
	s_waitcnt lgkmcnt(0)
	s_barrier
	s_setprio 1
	s_waitcnt lgkmcnt(0)
	v_mfma_f32_16x16x32_bf16 v[126:129], v[152:155], v[184:187], 0
	v_mfma_f32_16x16x32_bf16 v[122:125], v[160:163], v[184:187], 0
	v_mfma_f32_16x16x32_bf16 v[118:121], v[152:155], v[192:195], 0
	v_mfma_f32_16x16x32_bf16 v[110:113], v[160:163], v[192:195], 0
	v_mfma_f32_16x16x32_bf16 v[102:105], v[152:155], v[200:203], 0
	v_mfma_f32_16x16x32_bf16 v[94:97], v[160:163], v[200:203], 0
	v_mfma_f32_16x16x32_bf16 v[86:89], v[152:155], v[208:211], 0
	v_mfma_f32_16x16x32_bf16 v[78:81], v[160:163], v[208:211], 0
	v_mfma_f32_16x16x32_bf16 v[126:129], v[156:159], v[188:191], v[126:129]
	v_mfma_f32_16x16x32_bf16 v[122:125], v[164:167], v[188:191], v[122:125]
	v_mfma_f32_16x16x32_bf16 v[118:121], v[156:159], v[196:199], v[118:121]
	v_mfma_f32_16x16x32_bf16 v[110:113], v[164:167], v[196:199], v[110:113]
	v_mfma_f32_16x16x32_bf16 v[102:105], v[156:159], v[204:207], v[102:105]
	v_mfma_f32_16x16x32_bf16 v[94:97], v[164:167], v[204:207], v[94:97]
	v_mfma_f32_16x16x32_bf16 v[86:89], v[156:159], v[212:215], v[86:89]
	v_mfma_f32_16x16x32_bf16 v[78:81], v[164:167], v[212:215], v[78:81]
	s_setprio 0
	s_setprio 1
	v_mfma_f32_16x16x32_bf16 v[114:117], v[168:171], v[184:187], 0
	v_mfma_f32_16x16x32_bf16 v[106:109], v[176:179], v[184:187], 0
	v_mfma_f32_16x16x32_bf16 v[98:101], v[168:171], v[192:195], 0
	v_mfma_f32_16x16x32_bf16 v[90:93], v[176:179], v[192:195], 0
	v_mfma_f32_16x16x32_bf16 v[82:85], v[168:171], v[200:203], 0
	v_mfma_f32_16x16x32_bf16 v[74:77], v[176:179], v[200:203], 0
	v_mfma_f32_16x16x32_bf16 v[70:73], v[168:171], v[208:211], 0
	v_mfma_f32_16x16x32_bf16 v[66:69], v[176:179], v[208:211], 0
	v_mfma_f32_16x16x32_bf16 v[114:117], v[172:175], v[188:191], v[114:117]
	v_mfma_f32_16x16x32_bf16 v[106:109], v[180:183], v[188:191], v[106:109]
	v_mfma_f32_16x16x32_bf16 v[98:101], v[172:175], v[196:199], v[98:101]
	v_mfma_f32_16x16x32_bf16 v[90:93], v[180:183], v[196:199], v[90:93]
	v_mfma_f32_16x16x32_bf16 v[82:85], v[172:175], v[204:207], v[82:85]
	v_mfma_f32_16x16x32_bf16 v[74:77], v[180:183], v[204:207], v[74:77]
	v_mfma_f32_16x16x32_bf16 v[70:73], v[172:175], v[212:215], v[70:73]
	v_mfma_f32_16x16x32_bf16 v[66:69], v[180:183], v[212:215], v[66:69]
	s_setprio 0
	s_barrier
	s_mov_b32 m0, s79
	v_lshl_add_u64 v[142:143], s[30:31], 0, v[130:131]
	v_lshl_add_u64 v[216:217], s[30:31], 0, v[136:137]
	s_add_u32 s30, s30, s0
	ds_read_b128 v[184:187], v148 offset:16384
	ds_read_b128 v[188:191], v148 offset:17408
	ds_read_b128 v[192:195], v148 offset:18432
	ds_read_b128 v[196:199], v148 offset:19456
	ds_read_b128 v[200:203], v148 offset:20480
	ds_read_b128 v[204:207], v148 offset:21504
	ds_read_b128 v[208:211], v148 offset:22528
	ds_read_b128 v[212:215], v148 offset:23552
	global_load_lds_dwordx4 v[142:143], off
	s_mov_b32 m0, s80
	s_addc_u32 s31, s31, 0
	global_load_lds_dwordx4 v[216:217], off
	v_lshl_add_u64 v[218:219], s[30:31], 0, v[130:131]
	s_mov_b32 m0, s81
	v_lshl_add_u64 v[220:221], s[30:31], 0, v[136:137]
	global_load_lds_dwordx4 v[218:219], off
	s_mov_b32 m0, s82
	v_lshl_add_u64 v[222:223], s[72:73], 0, v[132:133]
	global_load_lds_dwordx4 v[220:221], off
	s_mov_b32 m0, s83
	v_lshl_add_u64 v[224:225], s[72:73], 0, v[134:135]
	global_load_lds_dwordx4 v[222:223], off
	s_mov_b32 m0, s84
	s_nop 0
	global_load_lds_dwordx4 v[224:225], off
	s_waitcnt vmcnt(8)
	s_waitcnt lgkmcnt(0)
	s_barrier
; #define PG8_STAGE(bufoff, gbase, voff) do { _Pragma("unroll") for (int _i = 0; _i < 2; ++_i) \
;         __builtin_amdgcn_global_load_lds((const unsigned*)((const char*)(gbase) + (voff)[_i]), (PG8_LAS unsigned*)(lds + (bufoff) + ldsw + _i * 8192), 16, 0, 0); } while (0)
; #define PG8_LDA(dst, b, h) do { _Pragma("unroll") for (int m = 0; m < 4; ++m) _Pragma("unroll") for (int k = 0; k < 2; ++k) dst[m][k] = *(const PG8_LAS bf16x8*)(lds + PG8_SA(b, h) + aoff + m * 2048 + k * 1024); } while (0)
; #define PG8_LDB(dst, b, h) do { _Pragma("unroll") for (int n = 0; n < 2; ++n) _Pragma("unroll") for (int k = 0; k < 2; ++k) dst[n][k] = *(const PG8_LAS bf16x8*)(lds + PG8_SB(b, h) + boff + n * 2048 + k * 1024); } while (0)
; #define PG8_MMA(ai, bj, At, Bt) do { __builtin_amdgcn_s_setprio(1); _Pragma("unroll") for (int m = 0; m < 4; ++m) _Pragma("unroll") for (int n = 0; n < 2; ++n) _Pragma("unroll") for (int k = 0; k < 2; ++k) \
;         acc[ai][bj][m][n] = __builtin_amdgcn_mfma_f32_16x16x32_bf16(Bt[n][k], At[m][k], acc[ai][bj][m][n], 0, 0, 0); __builtin_amdgcn_s_setprio(0); } while (0)
; #define PG8_WAIT_V(n) asm volatile("s_waitcnt vmcnt(" #n ")" ::: "memory")
; #define PG8_WAIT_L(n) asm volatile("s_waitcnt lgkmcnt(" #n ")" ::: "memory")
; #define PG8_BAR __builtin_amdgcn_s_barrier()
; #define PG8_SCHED __builtin_amdgcn_sched_barrier(0)
; template <class Epi, class Sched, bool ALIGN_EPI = false, bool SP2 = false>
; __device__ __forceinline__ void gemm_phase(PG8_LAS unsigned char* lds, const Gemm g, const Sched& S, const Epi& E) {
;     ...
;             PG8_WAIT_V(8); PG8_WAIT_L(0); PG8_BAR; PG8_MMA(1, 0, At, B0); PG8_MMA(1, 1, At, B1); PG8_BAR; PG8_SCHED;
;             PG8_LDB(B0, 1, 0); PG8_LDB(B1, 1, 1); PG8_SCHED; PG8_LDA(At, 1, 0); PG8_STAGE(PG8_SA(0, 1), a2 + hstep, voffA);
;             PG8_WAIT_V(8); PG8_WAIT_L(0); PG8_BAR; PG8_MMA(0, 0, At, B0); PG8_MMA(0, 1, At, B1); PG8_BAR; PG8_SCHED;
	s_setprio 1
	s_waitcnt lgkmcnt(0)
	v_mfma_f32_16x16x32_bf16 v[62:65], v[152:155], v[184:187], 0
	v_mfma_f32_16x16x32_bf16 v[58:61], v[160:163], v[184:187], 0
	v_mfma_f32_16x16x32_bf16 v[54:57], v[152:155], v[192:195], 0
	v_mfma_f32_16x16x32_bf16 v[46:49], v[160:163], v[192:195], 0
	v_mfma_f32_16x16x32_bf16 v[38:41], v[152:155], v[200:203], 0
	v_mfma_f32_16x16x32_bf16 v[30:33], v[160:163], v[200:203], 0
	v_mfma_f32_16x16x32_bf16 v[22:25], v[152:155], v[208:211], 0
	v_mfma_f32_16x16x32_bf16 v[14:17], v[160:163], v[208:211], 0
	v_mfma_f32_16x16x32_bf16 v[62:65], v[156:159], v[188:191], v[62:65]
	v_mfma_f32_16x16x32_bf16 v[58:61], v[164:167], v[188:191], v[58:61]
	v_mfma_f32_16x16x32_bf16 v[54:57], v[156:159], v[196:199], v[54:57]
	v_mfma_f32_16x16x32_bf16 v[46:49], v[164:167], v[196:199], v[46:49]
	v_mfma_f32_16x16x32_bf16 v[38:41], v[156:159], v[204:207], v[38:41]
	v_mfma_f32_16x16x32_bf16 v[30:33], v[164:167], v[204:207], v[30:33]
	v_mfma_f32_16x16x32_bf16 v[22:25], v[156:159], v[212:215], v[22:25]
	v_mfma_f32_16x16x32_bf16 v[14:17], v[164:167], v[212:215], v[14:17]
	s_setprio 0
	s_setprio 1
	v_mfma_f32_16x16x32_bf16 v[50:53], v[168:171], v[184:187], 0
	v_mfma_f32_16x16x32_bf16 v[42:45], v[176:179], v[184:187], 0
	v_mfma_f32_16x16x32_bf16 v[34:37], v[168:171], v[192:195], 0
	v_mfma_f32_16x16x32_bf16 v[26:29], v[176:179], v[192:195], 0
	v_mfma_f32_16x16x32_bf16 v[18:21], v[168:171], v[200:203], 0
	v_mfma_f32_16x16x32_bf16 v[10:13], v[176:179], v[200:203], 0
	v_mfma_f32_16x16x32_bf16 v[6:9], v[168:171], v[208:211], 0
	v_mfma_f32_16x16x32_bf16 v[2:5], v[176:179], v[208:211], 0
	v_mfma_f32_16x16x32_bf16 v[50:53], v[172:175], v[188:191], v[50:53]
	v_mfma_f32_16x16x32_bf16 v[42:45], v[180:183], v[188:191], v[42:45]
	v_mfma_f32_16x16x32_bf16 v[34:37], v[172:175], v[196:199], v[34:37]
	v_mfma_f32_16x16x32_bf16 v[26:29], v[180:183], v[196:199], v[26:29]
	v_mfma_f32_16x16x32_bf16 v[18:21], v[172:175], v[204:207], v[18:21]
	v_mfma_f32_16x16x32_bf16 v[10:13], v[180:183], v[204:207], v[10:13]
	v_mfma_f32_16x16x32_bf16 v[6:9], v[172:175], v[212:215], v[6:9]
	v_mfma_f32_16x16x32_bf16 v[2:5], v[180:183], v[212:215], v[2:5]
	s_setprio 0
	s_barrier
	v_add_u32_e32 v180, s66, v146
	ds_read_b128 v[152:155], v151
	ds_read_b128 v[156:159], v151 offset:1024
	ds_read_b128 v[160:163], v151 offset:2048
	ds_read_b128 v[164:167], v151 offset:3072
	ds_read_b128 v[168:171], v180
	ds_read_b128 v[172:175], v180 offset:1024
	ds_read_b128 v[176:179], v180 offset:2048
	ds_read_b128 v[180:183], v180 offset:3072
	s_add_u32 s30, s72, s0
	s_addc_u32 s31, s73, 0
	s_mov_b32 m0, s85
	v_lshl_add_u64 v[226:227], s[30:31], 0, v[132:133]
	ds_read_b128 v[184:187], v148 offset:32768
	ds_read_b128 v[188:191], v148 offset:33792
	ds_read_b128 v[192:195], v148 offset:34816
	ds_read_b128 v[196:199], v148 offset:35840
	ds_read_b128 v[200:203], v148 offset:36864
	ds_read_b128 v[204:207], v148 offset:37888
	ds_read_b128 v[208:211], v148 offset:38912
	ds_read_b128 v[212:215], v148 offset:39936
	global_load_lds_dwordx4 v[226:227], off
	v_lshl_add_u64 v[226:227], s[30:31], 0, v[134:135]
	s_mov_b32 m0, s86
	s_nop 0
	global_load_lds_dwordx4 v[226:227], off
	s_waitcnt vmcnt(8)
	s_waitcnt lgkmcnt(0)
	s_barrier
	s_setprio 1
	s_waitcnt lgkmcnt(0)
	v_mfma_f32_16x16x32_bf16 v[126:129], v[152:155], v[184:187], v[126:129]
	v_mfma_f32_16x16x32_bf16 v[122:125], v[160:163], v[184:187], v[122:125]
	v_mfma_f32_16x16x32_bf16 v[118:121], v[152:155], v[192:195], v[118:121]
	v_mfma_f32_16x16x32_bf16 v[110:113], v[160:163], v[192:195], v[110:113]
	v_mfma_f32_16x16x32_bf16 v[102:105], v[152:155], v[200:203], v[102:105]
	v_mfma_f32_16x16x32_bf16 v[94:97], v[160:163], v[200:203], v[94:97]
	v_mfma_f32_16x16x32_bf16 v[86:89], v[152:155], v[208:211], v[86:89]
	v_mfma_f32_16x16x32_bf16 v[78:81], v[160:163], v[208:211], v[78:81]
	v_mfma_f32_16x16x32_bf16 v[126:129], v[156:159], v[188:191], v[126:129]
	v_mfma_f32_16x16x32_bf16 v[122:125], v[164:167], v[188:191], v[122:125]
	v_mfma_f32_16x16x32_bf16 v[118:121], v[156:159], v[196:199], v[118:121]
	v_mfma_f32_16x16x32_bf16 v[110:113], v[164:167], v[196:199], v[110:113]
	v_mfma_f32_16x16x32_bf16 v[102:105], v[156:159], v[204:207], v[102:105]
	v_mfma_f32_16x16x32_bf16 v[94:97], v[164:167], v[204:207], v[94:97]
	v_mfma_f32_16x16x32_bf16 v[86:89], v[156:159], v[212:215], v[86:89]
	v_mfma_f32_16x16x32_bf16 v[78:81], v[164:167], v[212:215], v[78:81]
	s_setprio 0
	s_setprio 1
	v_mfma_f32_16x16x32_bf16 v[114:117], v[168:171], v[184:187], v[114:117]
	v_mfma_f32_16x16x32_bf16 v[106:109], v[176:179], v[184:187], v[106:109]
	v_mfma_f32_16x16x32_bf16 v[98:101], v[168:171], v[192:195], v[98:101]
	v_mfma_f32_16x16x32_bf16 v[90:93], v[176:179], v[192:195], v[90:93]
	v_mfma_f32_16x16x32_bf16 v[82:85], v[168:171], v[200:203], v[82:85]
	v_mfma_f32_16x16x32_bf16 v[74:77], v[176:179], v[200:203], v[74:77]
	v_mfma_f32_16x16x32_bf16 v[70:73], v[168:171], v[208:211], v[70:73]
	v_mfma_f32_16x16x32_bf16 v[66:69], v[176:179], v[208:211], v[66:69]
	v_mfma_f32_16x16x32_bf16 v[114:117], v[172:175], v[188:191], v[114:117]
	v_mfma_f32_16x16x32_bf16 v[106:109], v[180:183], v[188:191], v[106:109]
	v_mfma_f32_16x16x32_bf16 v[98:101], v[172:175], v[196:199], v[98:101]
	v_mfma_f32_16x16x32_bf16 v[90:93], v[180:183], v[196:199], v[90:93]
	v_mfma_f32_16x16x32_bf16 v[82:85], v[172:175], v[204:207], v[82:85]
	v_mfma_f32_16x16x32_bf16 v[74:77], v[180:183], v[204:207], v[74:77]
	v_mfma_f32_16x16x32_bf16 v[70:73], v[172:175], v[212:215], v[70:73]
	v_mfma_f32_16x16x32_bf16 v[66:69], v[180:183], v[212:215], v[66:69]
	s_setprio 0
	s_barrier
; #define PG8_STAGE(bufoff, gbase, voff) do { _Pragma("unroll") for (int _i = 0; _i < 2; ++_i) \
;         __builtin_amdgcn_global_load_lds((const unsigned*)((const char*)(gbase) + (voff)[_i]), (PG8_LAS unsigned*)(lds + (bufoff) + ldsw + _i * 8192), 16, 0, 0); } while (0)
; #define PG8_LDA(dst, b, h) do { _Pragma("unroll") for (int m = 0; m < 4; ++m) _Pragma("unroll") for (int k = 0; k < 2; ++k) dst[m][k] = *(const PG8_LAS bf16x8*)(lds + PG8_SA(b, h) + aoff + m * 2048 + k * 1024); } while (0)
; #define PG8_MMA(ai, bj, At, Bt) do { __builtin_amdgcn_s_setprio(1); _Pragma("unroll") for (int m = 0; m < 4; ++m) _Pragma("unroll") for (int n = 0; n < 2; ++n) _Pragma("unroll") for (int k = 0; k < 2; ++k) \
;         acc[ai][bj][m][n] = __builtin_amdgcn_mfma_f32_16x16x32_bf16(Bt[n][k], At[m][k], acc[ai][bj][m][n], 0, 0, 0); __builtin_amdgcn_s_setprio(0); } while (0)
; #define PG8_WAIT_V(n) asm volatile("s_waitcnt vmcnt(" #n ")" ::: "memory")
; #define PG8_WAIT_L(n) asm volatile("s_waitcnt lgkmcnt(" #n ")" ::: "memory")
; #define PG8_BAR __builtin_amdgcn_s_barrier()
; #define PG8_SCHED __builtin_amdgcn_sched_barrier(0)
; template <class Epi, class Sched, bool ALIGN_EPI = false, bool SP2 = false>
; __device__ __forceinline__ void gemm_phase(PG8_LAS unsigned char* lds, const Gemm g, const Sched& S, const Epi& E) {
;     ...
;         for (int t = 0; t < nt; t += 2) {
;     ...
;             PG8_LDA(At, 1, 1); PG8_STAGE(PG8_SB(1, 0), b3, voffB); PG8_STAGE(PG8_SB(1, 1), b3 + hstep, voffB); PG8_STAGE(PG8_SA(1, 0), a3, voffA);
;             PG8_WAIT_V(8); PG8_WAIT_L(0); PG8_BAR; PG8_MMA(1, 0, At, B0); PG8_MMA(1, 1, At, B1); PG8_BAR; PG8_SCHED;
	s_mov_b32 m0, s88
	v_lshl_add_u64 v[142:143], v[142:143], 0, s[18:19]
	ds_read_b128 v[184:187], v148 offset:49152
	ds_read_b128 v[188:191], v148 offset:50176
	ds_read_b128 v[192:195], v148 offset:51200
	ds_read_b128 v[196:199], v148 offset:52224
	ds_read_b128 v[200:203], v148 offset:53248
	ds_read_b128 v[204:207], v148 offset:54272
	ds_read_b128 v[208:211], v148 offset:55296
	ds_read_b128 v[212:215], v148 offset:56320
	global_load_lds_dwordx4 v[142:143], off
	v_lshl_add_u64 v[142:143], v[216:217], 0, s[18:19]
	s_mov_b32 m0, s89
	s_nop 0
	global_load_lds_dwordx4 v[142:143], off
	v_lshl_add_u64 v[142:143], v[218:219], 0, s[18:19]
	s_mov_b32 m0, s92
	s_nop 0
	global_load_lds_dwordx4 v[142:143], off
	v_lshl_add_u64 v[142:143], v[220:221], 0, s[18:19]
	s_mov_b32 m0, s93
	s_nop 0
	global_load_lds_dwordx4 v[142:143], off
	v_lshl_add_u64 v[142:143], v[222:223], 0, s[18:19]
	s_mov_b32 m0, s90
	s_nop 0
	global_load_lds_dwordx4 v[142:143], off
	v_lshl_add_u64 v[142:143], v[224:225], 0, s[18:19]
	s_mov_b32 m0, s91
	s_nop 0
	global_load_lds_dwordx4 v[142:143], off
	s_waitcnt vmcnt(8)
	s_waitcnt lgkmcnt(0)
	s_barrier
	s_setprio 1
	s_waitcnt lgkmcnt(0)
	v_mfma_f32_16x16x32_bf16 v[62:65], v[152:155], v[184:187], v[62:65]
	v_mfma_f32_16x16x32_bf16 v[58:61], v[160:163], v[184:187], v[58:61]
	v_mfma_f32_16x16x32_bf16 v[54:57], v[152:155], v[192:195], v[54:57]
	v_mfma_f32_16x16x32_bf16 v[46:49], v[160:163], v[192:195], v[46:49]
	v_mfma_f32_16x16x32_bf16 v[38:41], v[152:155], v[200:203], v[38:41]
	v_mfma_f32_16x16x32_bf16 v[30:33], v[160:163], v[200:203], v[30:33]
	v_mfma_f32_16x16x32_bf16 v[22:25], v[152:155], v[208:211], v[22:25]
	v_mfma_f32_16x16x32_bf16 v[14:17], v[160:163], v[208:211], v[14:17]
	v_mfma_f32_16x16x32_bf16 v[62:65], v[156:159], v[188:191], v[62:65]
	v_mfma_f32_16x16x32_bf16 v[58:61], v[164:167], v[188:191], v[58:61]
	v_mfma_f32_16x16x32_bf16 v[54:57], v[156:159], v[196:199], v[54:57]
	v_mfma_f32_16x16x32_bf16 v[46:49], v[164:167], v[196:199], v[46:49]
	v_mfma_f32_16x16x32_bf16 v[38:41], v[156:159], v[204:207], v[38:41]
	v_mfma_f32_16x16x32_bf16 v[30:33], v[164:167], v[204:207], v[30:33]
	v_mfma_f32_16x16x32_bf16 v[22:25], v[156:159], v[212:215], v[22:25]
	v_mfma_f32_16x16x32_bf16 v[14:17], v[164:167], v[212:215], v[14:17]
	s_setprio 0
	s_setprio 1
	v_mfma_f32_16x16x32_bf16 v[50:53], v[168:171], v[184:187], v[50:53]
	v_mfma_f32_16x16x32_bf16 v[42:45], v[176:179], v[184:187], v[42:45]
	v_mfma_f32_16x16x32_bf16 v[34:37], v[168:171], v[192:195], v[34:37]
	v_mfma_f32_16x16x32_bf16 v[26:29], v[176:179], v[192:195], v[26:29]
	v_mfma_f32_16x16x32_bf16 v[18:21], v[168:171], v[200:203], v[18:21]
	v_mfma_f32_16x16x32_bf16 v[10:13], v[176:179], v[200:203], v[10:13]
	v_mfma_f32_16x16x32_bf16 v[6:9], v[168:171], v[208:211], v[6:9]
	v_mfma_f32_16x16x32_bf16 v[2:5], v[176:179], v[208:211], v[2:5]
	v_mfma_f32_16x16x32_bf16 v[50:53], v[172:175], v[188:191], v[50:53]
	v_mfma_f32_16x16x32_bf16 v[42:45], v[180:183], v[188:191], v[42:45]
	v_mfma_f32_16x16x32_bf16 v[34:37], v[172:175], v[196:199], v[34:37]
	v_mfma_f32_16x16x32_bf16 v[26:29], v[180:183], v[196:199], v[26:29]
	v_mfma_f32_16x16x32_bf16 v[18:21], v[172:175], v[204:207], v[18:21]
	v_mfma_f32_16x16x32_bf16 v[10:13], v[180:183], v[204:207], v[10:13]
	v_mfma_f32_16x16x32_bf16 v[6:9], v[172:175], v[212:215], v[6:9]
	v_mfma_f32_16x16x32_bf16 v[2:5], v[180:183], v[212:215], v[2:5]
	s_setprio 0
	s_barrier
	s_add_u32 s58, s58, 0x100
	s_addc_u32 s59, s59, 0
	s_add_u32 s70, s70, 0x100
	s_addc_u32 s71, s71, 0
	s_cmp_ge_u32 vcc_lo, s87
	s_mov_b32 s72, vcc_lo

; #define PG8_STAGE(bufoff, gbase, voff) do { _Pragma("unroll") for (int _i = 0; _i < 2; ++_i) \
;         __builtin_amdgcn_global_load_lds((const unsigned*)((const char*)(gbase) + (voff)[_i]), (PG8_LAS unsigned*)(lds + (bufoff) + ldsw + _i * 8192), 16, 0, 0); } while (0)
; #define PG8_LDA(dst, b, h) do { _Pragma("unroll") for (int m = 0; m < 4; ++m) _Pragma("unroll") for (int k = 0; k < 2; ++k) dst[m][k] = *(const PG8_LAS bf16x8*)(lds + PG8_SA(b, h) + aoff + m * 2048 + k * 1024); } while (0)
; #define PG8_LDB(dst, b, h) do { _Pragma("unroll") for (int n = 0; n < 2; ++n) _Pragma("unroll") for (int k = 0; k < 2; ++k) dst[n][k] = *(const PG8_LAS bf16x8*)(lds + PG8_SB(b, h) + boff + n * 2048 + k * 1024); } while (0)
; #define PG8_MMA(ai, bj, At, Bt) do { __builtin_amdgcn_s_setprio(1); _Pragma("unroll") for (int m = 0; m < 4; ++m) _Pragma("unroll") for (int n = 0; n < 2; ++n) _Pragma("unroll") for (int k = 0; k < 2; ++k) \
;         acc[ai][bj][m][n] = __builtin_amdgcn_mfma_f32_16x16x32_bf16(Bt[n][k], At[m][k], acc[ai][bj][m][n], 0, 0, 0); __builtin_amdgcn_s_setprio(0); } while (0)
; #define PG8_WAIT_V(n) asm volatile("s_waitcnt vmcnt(" #n ")" ::: "memory")
; #define PG8_WAIT_L(n) asm volatile("s_waitcnt lgkmcnt(" #n ")" ::: "memory")
; #define PG8_BAR __builtin_amdgcn_s_barrier()
; #define PG8_SCHED __builtin_amdgcn_sched_barrier(0)
; template <class Epi, class Sched, bool ALIGN_EPI = false, bool SP2 = false>
; __device__ __forceinline__ void gemm_phase(PG8_LAS unsigned char* lds, const Gemm g, const Sched& S, const Epi& E) {
;     ...
;         for (int t = 0; t < nt; t += 2) {
;             const bool last = (t == nt - 2);
;             const char* a1 = cA + (size_t)(t + 1) * kstep;
;             const char* a2 = last ? nA : cA + (size_t)(t + 2) * kstep; const char* b2 = last ? nB : cB + (size_t)(t + 2) * kstep;
;             const char* a3 = a2 + kstep; const char* b3 = b2 + kstep;
;             if (last && has_next) S.a_ready(nxt);
;             if constexpr (SP2) {
;             PG8_LDB(B0, 0, 0); PG8_LDB(B1, 0, 1); PG8_SCHED; PG8_LDA(At, 0, 0); PG8_STAGE(PG8_SA(1, 1), a1 + hstep, voffA);
;             PG8_WAIT_V(8); PG8_WAIT_L(0); PG8_BAR; PG8_MMA(0, 0, At, B0); PG8_MMA(0, 1, At, B1); PG8_BAR; PG8_SCHED;
;             PG8_LDA(At, 0, 1); PG8_STAGE(PG8_SB(0, 0), b2, voffB); PG8_STAGE(PG8_SB(0, 1), b2 + hstep, voffB); PG8_STAGE(PG8_SA(0, 0), a2, voffA);
.LBB0_858:
	s_add_u32 s43, s56, 0x100
	s_addc_u32 s45, s57, 0
	s_add_u32 s56, s60, 0x40080
	s_addc_u32 s57, s61, 0
	s_mov_b32 s59, 0
	ds_read_b128 v[150:153], v146
	ds_read_b128 v[154:157], v146 offset:1024
	ds_read_b128 v[158:161], v146 offset:2048
	ds_read_b128 v[162:165], v146 offset:3072
	ds_read_b128 v[166:169], v147
	ds_read_b128 v[170:173], v147 offset:1024
	ds_read_b128 v[174:177], v147 offset:2048
	ds_read_b128 v[178:181], v147 offset:3072
	s_add_i32 s88, s59, 2
	s_add_u32 s60, s56, 0xfffc0080
	s_addc_u32 s61, s57, -1
	s_cmp_eq_u32 s84, s59
	s_cselect_b32 s69, s47, s61
	s_cselect_b32 s68, s46, s60
	s_cselect_b32 s61, s53, s45
	s_cselect_b32 s60, s52, s43
	v_lshl_add_u64 v[214:215], s[56:57], 0, v[140:141]
	s_add_i32 m0, s77, 0xc000
	ds_read_b128 v[182:185], v145
	ds_read_b128 v[186:189], v145 offset:1024
	ds_read_b128 v[190:193], v145 offset:2048
	ds_read_b128 v[194:197], v145 offset:3072
	ds_read_b128 v[198:201], v145 offset:4096
	ds_read_b128 v[202:205], v145 offset:5120
	ds_read_b128 v[206:209], v145 offset:6144
	ds_read_b128 v[210:213], v145 offset:7168
	global_load_lds_dwordx4 v[214:215], off
	v_lshl_add_u64 v[214:215], s[56:57], 0, v[138:139]
	s_add_i32 m0, s77, 0xe000
	s_nop 0
	global_load_lds_dwordx4 v[214:215], off
	s_waitcnt vmcnt(8)
	s_waitcnt lgkmcnt(0)
	s_barrier
	s_setprio 1
	s_waitcnt lgkmcnt(0)
	v_mfma_f32_16x16x32_bf16 v[126:129], v[150:153], v[182:185], 0
	v_mfma_f32_16x16x32_bf16 v[122:125], v[158:161], v[182:185], 0
	v_mfma_f32_16x16x32_bf16 v[118:121], v[150:153], v[190:193], 0
	v_mfma_f32_16x16x32_bf16 v[114:117], v[158:161], v[190:193], 0
	v_mfma_f32_16x16x32_bf16 v[102:105], v[150:153], v[198:201], 0
	v_mfma_f32_16x16x32_bf16 v[98:101], v[158:161], v[198:201], 0
	v_mfma_f32_16x16x32_bf16 v[86:89], v[150:153], v[206:209], 0
	v_mfma_f32_16x16x32_bf16 v[82:85], v[158:161], v[206:209], 0
	v_mfma_f32_16x16x32_bf16 v[126:129], v[154:157], v[186:189], v[126:129]
	v_mfma_f32_16x16x32_bf16 v[122:125], v[162:165], v[186:189], v[122:125]
	v_mfma_f32_16x16x32_bf16 v[118:121], v[154:157], v[194:197], v[118:121]
	v_mfma_f32_16x16x32_bf16 v[114:117], v[162:165], v[194:197], v[114:117]
	v_mfma_f32_16x16x32_bf16 v[102:105], v[154:157], v[202:205], v[102:105]
	v_mfma_f32_16x16x32_bf16 v[98:101], v[162:165], v[202:205], v[98:101]
	v_mfma_f32_16x16x32_bf16 v[86:89], v[154:157], v[210:213], v[86:89]
	v_mfma_f32_16x16x32_bf16 v[82:85], v[162:165], v[210:213], v[82:85]
	s_setprio 0
	s_setprio 1
	v_mfma_f32_16x16x32_bf16 v[110:113], v[166:169], v[182:185], 0
	v_mfma_f32_16x16x32_bf16 v[106:109], v[174:177], v[182:185], 0
	v_mfma_f32_16x16x32_bf16 v[94:97], v[166:169], v[190:193], 0
	v_mfma_f32_16x16x32_bf16 v[90:93], v[174:177], v[190:193], 0
	v_mfma_f32_16x16x32_bf16 v[78:81], v[166:169], v[198:201], 0
	v_mfma_f32_16x16x32_bf16 v[74:77], v[174:177], v[198:201], 0
	v_mfma_f32_16x16x32_bf16 v[70:73], v[166:169], v[206:209], 0
	v_mfma_f32_16x16x32_bf16 v[66:69], v[174:177], v[206:209], 0
	v_mfma_f32_16x16x32_bf16 v[110:113], v[170:173], v[186:189], v[110:113]
	v_mfma_f32_16x16x32_bf16 v[106:109], v[178:181], v[186:189], v[106:109]
	v_mfma_f32_16x16x32_bf16 v[94:97], v[170:173], v[194:197], v[94:97]
	v_mfma_f32_16x16x32_bf16 v[90:93], v[178:181], v[194:197], v[90:93]
	v_mfma_f32_16x16x32_bf16 v[78:81], v[170:173], v[202:205], v[78:81]
	v_mfma_f32_16x16x32_bf16 v[74:77], v[178:181], v[202:205], v[74:77]
	v_mfma_f32_16x16x32_bf16 v[70:73], v[170:173], v[210:213], v[70:73]
	v_mfma_f32_16x16x32_bf16 v[66:69], v[178:181], v[210:213], v[66:69]
	s_setprio 0
	s_barrier
	s_mov_b32 m0, s37
	v_lshl_add_u64 v[214:215], s[60:61], 0, v[130:131]
	s_add_u32 s90, s60, 0x40000
	ds_read_b128 v[182:185], v145 offset:16384
	ds_read_b128 v[186:189], v145 offset:17408
	ds_read_b128 v[190:193], v145 offset:18432
	ds_read_b128 v[194:197], v145 offset:19456
	ds_read_b128 v[198:201], v145 offset:20480
	ds_read_b128 v[202:205], v145 offset:21504
	ds_read_b128 v[206:209], v145 offset:22528
	ds_read_b128 v[210:213], v145 offset:23552
	global_load_lds_dwordx4 v[214:215], off
	v_lshl_add_u64 v[216:217], s[60:61], 0, v[136:137]
	s_mov_b32 m0, s39
	s_addc_u32 s91, s61, 0
	global_load_lds_dwordx4 v[216:217], off
	v_lshl_add_u64 v[218:219], s[90:91], 0, v[130:131]
	s_mov_b32 m0, s75
	v_lshl_add_u64 v[220:221], s[68:69], 0, v[134:135]
	global_load_lds_dwordx4 v[218:219], off
	v_lshl_add_u64 v[218:219], s[90:91], 0, v[136:137]
	s_mov_b32 m0, s76
	s_nop 0
	global_load_lds_dwordx4 v[218:219], off
	v_lshl_add_u64 v[218:219], s[68:69], 0, v[132:133]
	s_mov_b32 m0, s77
	s_nop 0
	global_load_lds_dwordx4 v[218:219], off
	s_mov_b32 m0, s78
	s_nop 0
	global_load_lds_dwordx4 v[220:221], off
	s_waitcnt vmcnt(8)
	s_waitcnt lgkmcnt(0)
	s_barrier
; #define PG8_STAGE(bufoff, gbase, voff) do { _Pragma("unroll") for (int _i = 0; _i < 2; ++_i) \
;         __builtin_amdgcn_global_load_lds((const unsigned*)((const char*)(gbase) + (voff)[_i]), (PG8_LAS unsigned*)(lds + (bufoff) + ldsw + _i * 8192), 16, 0, 0); } while (0)
; #define PG8_LDA(dst, b, h) do { _Pragma("unroll") for (int m = 0; m < 4; ++m) _Pragma("unroll") for (int k = 0; k < 2; ++k) dst[m][k] = *(const PG8_LAS bf16x8*)(lds + PG8_SA(b, h) + aoff + m * 2048 + k * 1024); } while (0)
; #define PG8_LDB(dst, b, h) do { _Pragma("unroll") for (int n = 0; n < 2; ++n) _Pragma("unroll") for (int k = 0; k < 2; ++k) dst[n][k] = *(const PG8_LAS bf16x8*)(lds + PG8_SB(b, h) + boff + n * 2048 + k * 1024); } while (0)
; #define PG8_MMA(ai, bj, At, Bt) do { __builtin_amdgcn_s_setprio(1); _Pragma("unroll") for (int m = 0; m < 4; ++m) _Pragma("unroll") for (int n = 0; n < 2; ++n) _Pragma("unroll") for (int k = 0; k < 2; ++k) \
;         acc[ai][bj][m][n] = __builtin_amdgcn_mfma_f32_16x16x32_bf16(Bt[n][k], At[m][k], acc[ai][bj][m][n], 0, 0, 0); __builtin_amdgcn_s_setprio(0); } while (0)
; #define PG8_WAIT_V(n) asm volatile("s_waitcnt vmcnt(" #n ")" ::: "memory")
; #define PG8_WAIT_L(n) asm volatile("s_waitcnt lgkmcnt(" #n ")" ::: "memory")
; #define PG8_BAR __builtin_amdgcn_s_barrier()
; #define PG8_SCHED __builtin_amdgcn_sched_barrier(0)
; template <class Epi, class Sched, bool ALIGN_EPI = false, bool SP2 = false>
; __device__ __forceinline__ void gemm_phase(PG8_LAS unsigned char* lds, const Gemm g, const Sched& S, const Epi& E) {
;     ...
;             PG8_WAIT_V(8); PG8_WAIT_L(0); PG8_BAR; PG8_MMA(1, 0, At, B0); PG8_MMA(1, 1, At, B1); PG8_BAR; PG8_SCHED;
;             PG8_LDB(B0, 1, 0); PG8_LDB(B1, 1, 1); PG8_SCHED; PG8_LDA(At, 1, 0); PG8_STAGE(PG8_SA(0, 1), a2 + hstep, voffA);
;             PG8_WAIT_V(8); PG8_WAIT_L(0); PG8_BAR; PG8_MMA(0, 0, At, B0); PG8_MMA(0, 1, At, B1); PG8_BAR; PG8_SCHED;
	s_setprio 1
	s_waitcnt lgkmcnt(0)
	v_mfma_f32_16x16x32_bf16 v[62:65], v[150:153], v[182:185], 0
	v_mfma_f32_16x16x32_bf16 v[58:61], v[158:161], v[182:185], 0
	v_mfma_f32_16x16x32_bf16 v[54:57], v[150:153], v[190:193], 0
	v_mfma_f32_16x16x32_bf16 v[50:53], v[158:161], v[190:193], 0
	v_mfma_f32_16x16x32_bf16 v[38:41], v[150:153], v[198:201], 0
	v_mfma_f32_16x16x32_bf16 v[34:37], v[158:161], v[198:201], 0
	v_mfma_f32_16x16x32_bf16 v[22:25], v[150:153], v[206:209], 0
	v_mfma_f32_16x16x32_bf16 v[18:21], v[158:161], v[206:209], 0
	v_mfma_f32_16x16x32_bf16 v[62:65], v[154:157], v[186:189], v[62:65]
	v_mfma_f32_16x16x32_bf16 v[58:61], v[162:165], v[186:189], v[58:61]
	v_mfma_f32_16x16x32_bf16 v[54:57], v[154:157], v[194:197], v[54:57]
	v_mfma_f32_16x16x32_bf16 v[50:53], v[162:165], v[194:197], v[50:53]
	v_mfma_f32_16x16x32_bf16 v[38:41], v[154:157], v[202:205], v[38:41]
	v_mfma_f32_16x16x32_bf16 v[34:37], v[162:165], v[202:205], v[34:37]
	v_mfma_f32_16x16x32_bf16 v[22:25], v[154:157], v[210:213], v[22:25]
	v_mfma_f32_16x16x32_bf16 v[18:21], v[162:165], v[210:213], v[18:21]
	s_setprio 0
	s_setprio 1
	v_mfma_f32_16x16x32_bf16 v[46:49], v[166:169], v[182:185], 0
	v_mfma_f32_16x16x32_bf16 v[42:45], v[174:177], v[182:185], 0
	v_mfma_f32_16x16x32_bf16 v[30:33], v[166:169], v[190:193], 0
	v_mfma_f32_16x16x32_bf16 v[26:29], v[174:177], v[190:193], 0
	v_mfma_f32_16x16x32_bf16 v[14:17], v[166:169], v[198:201], 0
	v_mfma_f32_16x16x32_bf16 v[10:13], v[174:177], v[198:201], 0
	v_mfma_f32_16x16x32_bf16 v[6:9], v[166:169], v[206:209], 0
	v_mfma_f32_16x16x32_bf16 v[2:5], v[174:177], v[206:209], 0
	v_mfma_f32_16x16x32_bf16 v[46:49], v[170:173], v[186:189], v[46:49]
	v_mfma_f32_16x16x32_bf16 v[42:45], v[178:181], v[186:189], v[42:45]
	v_mfma_f32_16x16x32_bf16 v[30:33], v[170:173], v[194:197], v[30:33]
	v_mfma_f32_16x16x32_bf16 v[26:29], v[178:181], v[194:197], v[26:29]
	v_mfma_f32_16x16x32_bf16 v[14:17], v[170:173], v[202:205], v[14:17]
	v_mfma_f32_16x16x32_bf16 v[10:13], v[178:181], v[202:205], v[10:13]
	v_mfma_f32_16x16x32_bf16 v[6:9], v[170:173], v[210:213], v[6:9]
	v_mfma_f32_16x16x32_bf16 v[2:5], v[178:181], v[210:213], v[2:5]
	s_setprio 0
	s_barrier
	ds_read_b128 v[150:153], v148
	ds_read_b128 v[154:157], v148 offset:1024
	ds_read_b128 v[158:161], v148 offset:2048
	ds_read_b128 v[162:165], v148 offset:3072
	ds_read_b128 v[166:169], v149
	ds_read_b128 v[170:173], v149 offset:1024
	ds_read_b128 v[174:177], v149 offset:2048
	ds_read_b128 v[178:181], v149 offset:3072
	s_add_u32 s68, s68, 0x40000
	s_addc_u32 s69, s69, 0
	s_mov_b32 m0, s79
	v_lshl_add_u64 v[222:223], s[68:69], 0, v[132:133]
	ds_read_b128 v[182:185], v145 offset:32768
	ds_read_b128 v[186:189], v145 offset:33792
	ds_read_b128 v[190:193], v145 offset:34816
	ds_read_b128 v[194:197], v145 offset:35840
	ds_read_b128 v[198:201], v145 offset:36864
	ds_read_b128 v[202:205], v145 offset:37888
	ds_read_b128 v[206:209], v145 offset:38912
	ds_read_b128 v[210:213], v145 offset:39936
	global_load_lds_dwordx4 v[222:223], off
	v_lshl_add_u64 v[222:223], s[68:69], 0, v[134:135]
	s_mov_b32 m0, s80
	s_nop 0
	global_load_lds_dwordx4 v[222:223], off
	s_waitcnt vmcnt(8)
	s_waitcnt lgkmcnt(0)
	s_barrier
	s_setprio 1
	s_waitcnt lgkmcnt(0)
	v_mfma_f32_16x16x32_bf16 v[126:129], v[150:153], v[182:185], v[126:129]
	v_mfma_f32_16x16x32_bf16 v[122:125], v[158:161], v[182:185], v[122:125]
	v_mfma_f32_16x16x32_bf16 v[118:121], v[150:153], v[190:193], v[118:121]
	v_mfma_f32_16x16x32_bf16 v[114:117], v[158:161], v[190:193], v[114:117]
	v_mfma_f32_16x16x32_bf16 v[102:105], v[150:153], v[198:201], v[102:105]
	v_mfma_f32_16x16x32_bf16 v[98:101], v[158:161], v[198:201], v[98:101]
	v_mfma_f32_16x16x32_bf16 v[86:89], v[150:153], v[206:209], v[86:89]
	v_mfma_f32_16x16x32_bf16 v[82:85], v[158:161], v[206:209], v[82:85]
	v_mfma_f32_16x16x32_bf16 v[126:129], v[154:157], v[186:189], v[126:129]
	v_mfma_f32_16x16x32_bf16 v[122:125], v[162:165], v[186:189], v[122:125]
	v_mfma_f32_16x16x32_bf16 v[118:121], v[154:157], v[194:197], v[118:121]
	v_mfma_f32_16x16x32_bf16 v[114:117], v[162:165], v[194:197], v[114:117]
	v_mfma_f32_16x16x32_bf16 v[102:105], v[154:157], v[202:205], v[102:105]
	v_mfma_f32_16x16x32_bf16 v[98:101], v[162:165], v[202:205], v[98:101]
	v_mfma_f32_16x16x32_bf16 v[86:89], v[154:157], v[210:213], v[86:89]
	v_mfma_f32_16x16x32_bf16 v[82:85], v[162:165], v[210:213], v[82:85]
	s_setprio 0
	s_setprio 1
	v_mfma_f32_16x16x32_bf16 v[110:113], v[166:169], v[182:185], v[110:113]
	v_mfma_f32_16x16x32_bf16 v[106:109], v[174:177], v[182:185], v[106:109]
	v_mfma_f32_16x16x32_bf16 v[94:97], v[166:169], v[190:193], v[94:97]
	v_mfma_f32_16x16x32_bf16 v[90:93], v[174:177], v[190:193], v[90:93]
	v_mfma_f32_16x16x32_bf16 v[78:81], v[166:169], v[198:201], v[78:81]
	v_mfma_f32_16x16x32_bf16 v[74:77], v[174:177], v[198:201], v[74:77]
	v_mfma_f32_16x16x32_bf16 v[70:73], v[166:169], v[206:209], v[70:73]
	v_mfma_f32_16x16x32_bf16 v[66:69], v[174:177], v[206:209], v[66:69]
	v_mfma_f32_16x16x32_bf16 v[110:113], v[170:173], v[186:189], v[110:113]
	v_mfma_f32_16x16x32_bf16 v[106:109], v[178:181], v[186:189], v[106:109]
	v_mfma_f32_16x16x32_bf16 v[94:97], v[170:173], v[194:197], v[94:97]
	v_mfma_f32_16x16x32_bf16 v[90:93], v[178:181], v[194:197], v[90:93]
	v_mfma_f32_16x16x32_bf16 v[78:81], v[170:173], v[202:205], v[78:81]
	v_mfma_f32_16x16x32_bf16 v[74:77], v[178:181], v[202:205], v[74:77]
	v_mfma_f32_16x16x32_bf16 v[70:73], v[170:173], v[210:213], v[70:73]
	v_mfma_f32_16x16x32_bf16 v[66:69], v[178:181], v[210:213], v[66:69]
	s_setprio 0
	s_barrier
; #define PG8_STAGE(bufoff, gbase, voff) do { _Pragma("unroll") for (int _i = 0; _i < 2; ++_i) \
;         __builtin_amdgcn_global_load_lds((const unsigned*)((const char*)(gbase) + (voff)[_i]), (PG8_LAS unsigned*)(lds + (bufoff) + ldsw + _i * 8192), 16, 0, 0); } while (0)
; #define PG8_LDA(dst, b, h) do { _Pragma("unroll") for (int m = 0; m < 4; ++m) _Pragma("unroll") for (int k = 0; k < 2; ++k) dst[m][k] = *(const PG8_LAS bf16x8*)(lds + PG8_SA(b, h) + aoff + m * 2048 + k * 1024); } while (0)
; #define PG8_MMA(ai, bj, At, Bt) do { __builtin_amdgcn_s_setprio(1); _Pragma("unroll") for (int m = 0; m < 4; ++m) _Pragma("unroll") for (int n = 0; n < 2; ++n) _Pragma("unroll") for (int k = 0; k < 2; ++k) \
;         acc[ai][bj][m][n] = __builtin_amdgcn_mfma_f32_16x16x32_bf16(Bt[n][k], At[m][k], acc[ai][bj][m][n], 0, 0, 0); __builtin_amdgcn_s_setprio(0); } while (0)
; #define PG8_WAIT_V(n) asm volatile("s_waitcnt vmcnt(" #n ")" ::: "memory")
; #define PG8_WAIT_L(n) asm volatile("s_waitcnt lgkmcnt(" #n ")" ::: "memory")
; #define PG8_BAR __builtin_amdgcn_s_barrier()
; #define PG8_SCHED __builtin_amdgcn_sched_barrier(0)
; template <class Epi, class Sched, bool ALIGN_EPI = false, bool SP2 = false>
; __device__ __forceinline__ void gemm_phase(PG8_LAS unsigned char* lds, const Gemm g, const Sched& S, const Epi& E) {
;     ...
;         for (int t = 0; t < nt; t += 2) {
;     ...
;             PG8_LDA(At, 1, 1); PG8_STAGE(PG8_SB(1, 0), b3, voffB); PG8_STAGE(PG8_SB(1, 1), b3 + hstep, voffB); PG8_STAGE(PG8_SA(1, 0), a3, voffA);
;             PG8_WAIT_V(8); PG8_WAIT_L(0); PG8_BAR; PG8_MMA(1, 0, At, B0); PG8_MMA(1, 1, At, B1); PG8_BAR; PG8_SCHED;
	s_mov_b32 m0, s48
	v_lshl_add_u64 v[214:215], v[214:215], 0, s[16:17]
	s_add_u32 s60, s60, 0x40080
	ds_read_b128 v[182:185], v145 offset:49152
	ds_read_b128 v[186:189], v145 offset:50176
	ds_read_b128 v[190:193], v145 offset:51200
	ds_read_b128 v[194:197], v145 offset:52224
	ds_read_b128 v[198:201], v145 offset:53248
	ds_read_b128 v[202:205], v145 offset:54272
	ds_read_b128 v[206:209], v145 offset:55296
	ds_read_b128 v[210:213], v145 offset:56320
	global_load_lds_dwordx4 v[214:215], off
	v_lshl_add_u64 v[214:215], v[216:217], 0, s[16:17]
	s_mov_b32 m0, s49
	s_addc_u32 s61, s61, 0
	global_load_lds_dwordx4 v[214:215], off
	v_lshl_add_u64 v[214:215], s[60:61], 0, v[130:131]
	s_mov_b32 m0, s82
	s_nop 0
	global_load_lds_dwordx4 v[214:215], off
	v_lshl_add_u64 v[214:215], s[60:61], 0, v[136:137]
	s_mov_b32 m0, s83
	s_nop 0
	global_load_lds_dwordx4 v[214:215], off
	v_lshl_add_u64 v[214:215], v[218:219], 0, s[16:17]
	s_mov_b32 m0, s50
	s_nop 0
	global_load_lds_dwordx4 v[214:215], off
	v_lshl_add_u64 v[214:215], v[220:221], 0, s[16:17]
	s_mov_b32 m0, s51
	s_nop 0
	global_load_lds_dwordx4 v[214:215], off
	s_waitcnt vmcnt(8)
	s_waitcnt lgkmcnt(0)
	s_barrier
	s_setprio 1
	s_waitcnt lgkmcnt(0)
	v_mfma_f32_16x16x32_bf16 v[62:65], v[150:153], v[182:185], v[62:65]
	v_mfma_f32_16x16x32_bf16 v[58:61], v[158:161], v[182:185], v[58:61]
	v_mfma_f32_16x16x32_bf16 v[54:57], v[150:153], v[190:193], v[54:57]
	v_mfma_f32_16x16x32_bf16 v[50:53], v[158:161], v[190:193], v[50:53]
	v_mfma_f32_16x16x32_bf16 v[38:41], v[150:153], v[198:201], v[38:41]
	v_mfma_f32_16x16x32_bf16 v[34:37], v[158:161], v[198:201], v[34:37]
	v_mfma_f32_16x16x32_bf16 v[22:25], v[150:153], v[206:209], v[22:25]
	v_mfma_f32_16x16x32_bf16 v[18:21], v[158:161], v[206:209], v[18:21]
	v_mfma_f32_16x16x32_bf16 v[62:65], v[154:157], v[186:189], v[62:65]
	v_mfma_f32_16x16x32_bf16 v[58:61], v[162:165], v[186:189], v[58:61]
	v_mfma_f32_16x16x32_bf16 v[54:57], v[154:157], v[194:197], v[54:57]
	v_mfma_f32_16x16x32_bf16 v[50:53], v[162:165], v[194:197], v[50:53]
	v_mfma_f32_16x16x32_bf16 v[38:41], v[154:157], v[202:205], v[38:41]
	v_mfma_f32_16x16x32_bf16 v[34:37], v[162:165], v[202:205], v[34:37]
	v_mfma_f32_16x16x32_bf16 v[22:25], v[154:157], v[210:213], v[22:25]
	v_mfma_f32_16x16x32_bf16 v[18:21], v[162:165], v[210:213], v[18:21]
	s_setprio 0
	s_setprio 1
	v_mfma_f32_16x16x32_bf16 v[46:49], v[166:169], v[182:185], v[46:49]
	v_mfma_f32_16x16x32_bf16 v[42:45], v[174:177], v[182:185], v[42:45]
	v_mfma_f32_16x16x32_bf16 v[30:33], v[166:169], v[190:193], v[30:33]
	v_mfma_f32_16x16x32_bf16 v[26:29], v[174:177], v[190:193], v[26:29]
	v_mfma_f32_16x16x32_bf16 v[14:17], v[166:169], v[198:201], v[14:17]
	v_mfma_f32_16x16x32_bf16 v[10:13], v[174:177], v[198:201], v[10:13]
	v_mfma_f32_16x16x32_bf16 v[6:9], v[166:169], v[206:209], v[6:9]
	v_mfma_f32_16x16x32_bf16 v[2:5], v[174:177], v[206:209], v[2:5]
	v_mfma_f32_16x16x32_bf16 v[46:49], v[170:173], v[186:189], v[46:49]
	v_mfma_f32_16x16x32_bf16 v[42:45], v[178:181], v[186:189], v[42:45]
	v_mfma_f32_16x16x32_bf16 v[30:33], v[170:173], v[194:197], v[30:33]
	v_mfma_f32_16x16x32_bf16 v[26:29], v[178:181], v[194:197], v[26:29]
	v_mfma_f32_16x16x32_bf16 v[14:17], v[170:173], v[202:205], v[14:17]
	v_mfma_f32_16x16x32_bf16 v[10:13], v[178:181], v[202:205], v[10:13]
	v_mfma_f32_16x16x32_bf16 v[6:9], v[170:173], v[210:213], v[6:9]
	v_mfma_f32_16x16x32_bf16 v[2:5], v[178:181], v[210:213], v[2:5]
	s_setprio 0
	s_barrier
	s_add_u32 s43, s43, 0x100
	s_addc_u32 s45, s45, 0
	s_add_u32 s56, s56, 0x100
	s_addc_u32 s57, s57, 0
	s_cmp_ge_u32 s88, s81
	s_mov_b32 s59, s88

; #define PG8_STAGE(bufoff, gbase, voff) do { _Pragma("unroll") for (int _i = 0; _i < 2; ++_i) \
;         __builtin_amdgcn_global_load_lds((const unsigned*)((const char*)(gbase) + (voff)[_i]), (PG8_LAS unsigned*)(lds + (bufoff) + ldsw + _i * 8192), 16, 0, 0); } while (0)
; #define PG8_LDA(dst, b, h) do { _Pragma("unroll") for (int m = 0; m < 4; ++m) _Pragma("unroll") for (int k = 0; k < 2; ++k) dst[m][k] = *(const PG8_LAS bf16x8*)(lds + PG8_SA(b, h) + aoff + m * 2048 + k * 1024); } while (0)
; #define PG8_LDB(dst, b, h) do { _Pragma("unroll") for (int n = 0; n < 2; ++n) _Pragma("unroll") for (int k = 0; k < 2; ++k) dst[n][k] = *(const PG8_LAS bf16x8*)(lds + PG8_SB(b, h) + boff + n * 2048 + k * 1024); } while (0)
; #define PG8_MMA(ai, bj, At, Bt) do { __builtin_amdgcn_s_setprio(1); _Pragma("unroll") for (int m = 0; m < 4; ++m) _Pragma("unroll") for (int n = 0; n < 2; ++n) _Pragma("unroll") for (int k = 0; k < 2; ++k) \
;         acc[ai][bj][m][n] = __builtin_amdgcn_mfma_f32_16x16x32_bf16(Bt[n][k], At[m][k], acc[ai][bj][m][n], 0, 0, 0); __builtin_amdgcn_s_setprio(0); } while (0)
; template <class Epi, class Sched, bool ALIGN_EPI = false, bool SP2 = false>
; __device__ __forceinline__ void gemm_phase(PG8_LAS unsigned char* lds, const Gemm g, const Sched& S, const Epi& E) {
;     ...
;         const bool has_next = S.next(ui + 1, nxt);
;         const char* nA = has_next ? (const char*)g.A + (size_t)nxt.pm * tstep + (size_t)nxt.ks * K * 2 : cA; const char* nB = has_next ? (const char*)g.Bt + (size_t)nxt.pn * tstep + (size_t)nxt.ks * K * 2 : cB;
;         for (int t = 0; t < nt; t += 2) {
;             const bool last = (t == nt - 2);
;             const char* a1 = cA + (size_t)(t + 1) * kstep;
;             const char* a2 = last ? nA : cA + (size_t)(t + 2) * kstep; const char* b2 = last ? nB : cB + (size_t)(t + 2) * kstep;
;             const char* a3 = a2 + kstep; const char* b3 = b2 + kstep;
;             if (last && has_next) S.a_ready(nxt);
;             if constexpr (SP2) {
;             PG8_LDB(B0, 0, 0); PG8_LDB(B1, 0, 1); PG8_SCHED; PG8_LDA(At, 0, 0); PG8_STAGE(PG8_SA(1, 1), a1 + hstep, voffA);
;             PG8_WAIT_V(8); PG8_WAIT_L(0); PG8_BAR; PG8_MMA(0, 0, At, B0); PG8_MMA(0, 1, At, B1); PG8_BAR; PG8_SCHED;
;             PG8_LDA(At, 0, 1); PG8_STAGE(PG8_SB(0, 0), b2, voffB); PG8_STAGE(PG8_SB(0, 1), b2 + hstep, voffB); PG8_STAGE(PG8_SA(0, 0), a2, voffA);
.LBB0_1037:
	s_ashr_i32 s13, s12, 31
	s_lshl_b64 s[14:15], s[12:13], 19
	s_add_u32 s14, s28, s14
	s_addc_u32 s15, s29, s15
	s_and_b64 s[16:17], s[2:3], exec
	s_cselect_b32 s13, s15, s23
	s_cselect_b32 s48, s14, s22
	s_ashr_i32 s11, s10, 31
	s_lshl_b64 s[16:17], s[10:11], 19
	s_add_u32 s16, s30, s16
	s_addc_u32 s17, s31, s17
	s_and_b64 s[24:25], s[2:3], exec
	s_cselect_b32 s11, s17, s21
	s_cselect_b32 s49, s16, s20
	s_add_u32 s50, s20, 0x100
	s_addc_u32 s51, s21, 0
	s_add_u32 s20, s22, 0x40080
	s_addc_u32 s21, s23, 0
	s_mov_b32 s54, -2
	ds_read_b128 v[146:149], v152
	ds_read_b128 v[158:161], v152 offset:1024
	ds_read_b128 v[162:165], v152 offset:2048
	ds_read_b128 v[166:169], v152 offset:3072
	ds_read_b128 v[170:173], v153
	ds_read_b128 v[174:177], v153 offset:1024
	ds_read_b128 v[178:181], v153 offset:2048
	ds_read_b128 v[182:185], v153 offset:3072
	s_add_u32 s22, s20, 0xfffc0080
	s_addc_u32 s23, s21, -1
	s_cmp_eq_u32 s54, 12
	s_cselect_b32 s25, s13, s23
	s_cselect_b32 s24, s48, s22
	s_cselect_b32 s23, s11, s51
	s_cselect_b32 s22, s49, s50
	v_lshl_add_u64 v[218:219], s[20:21], 0, v[140:141]
	s_add_i32 m0, s41, 0xc000
	ds_read_b128 v[186:189], v154
	ds_read_b128 v[190:193], v154 offset:1024
	ds_read_b128 v[194:197], v154 offset:2048
	ds_read_b128 v[198:201], v154 offset:3072
	ds_read_b128 v[202:205], v154 offset:4096
	ds_read_b128 v[206:209], v154 offset:5120
	ds_read_b128 v[210:213], v154 offset:6144
	ds_read_b128 v[214:217], v154 offset:7168
	global_load_lds_dwordx4 v[218:219], off
	v_lshl_add_u64 v[218:219], s[20:21], 0, v[138:139]
	s_add_i32 m0, s41, 0xe000
	s_nop 0
	global_load_lds_dwordx4 v[218:219], off
	s_waitcnt vmcnt(8)
	s_waitcnt lgkmcnt(0)
	s_barrier
	s_setprio 1
	s_waitcnt lgkmcnt(0)
	v_mfma_f32_16x16x32_bf16 v[126:129], v[146:149], v[186:189], 0
	v_mfma_f32_16x16x32_bf16 v[118:121], v[162:165], v[186:189], 0
	v_mfma_f32_16x16x32_bf16 v[110:113], v[146:149], v[194:197], 0
	v_mfma_f32_16x16x32_bf16 v[102:105], v[162:165], v[194:197], 0
	v_mfma_f32_16x16x32_bf16 v[94:97], v[146:149], v[202:205], 0
	v_mfma_f32_16x16x32_bf16 v[86:89], v[162:165], v[202:205], 0
	v_mfma_f32_16x16x32_bf16 v[78:81], v[146:149], v[210:213], 0
	v_mfma_f32_16x16x32_bf16 v[70:73], v[162:165], v[210:213], 0
	v_mfma_f32_16x16x32_bf16 v[126:129], v[158:161], v[190:193], v[126:129]
	v_mfma_f32_16x16x32_bf16 v[118:121], v[166:169], v[190:193], v[118:121]
	v_mfma_f32_16x16x32_bf16 v[110:113], v[158:161], v[198:201], v[110:113]
	v_mfma_f32_16x16x32_bf16 v[102:105], v[166:169], v[198:201], v[102:105]
	v_mfma_f32_16x16x32_bf16 v[94:97], v[158:161], v[206:209], v[94:97]
	v_mfma_f32_16x16x32_bf16 v[86:89], v[166:169], v[206:209], v[86:89]
	v_mfma_f32_16x16x32_bf16 v[78:81], v[158:161], v[214:217], v[78:81]
	v_mfma_f32_16x16x32_bf16 v[70:73], v[166:169], v[214:217], v[70:73]
	s_setprio 0
	s_setprio 1
	v_mfma_f32_16x16x32_bf16 v[122:125], v[170:173], v[186:189], 0
	v_mfma_f32_16x16x32_bf16 v[114:117], v[178:181], v[186:189], 0
	v_mfma_f32_16x16x32_bf16 v[106:109], v[170:173], v[194:197], 0
	v_mfma_f32_16x16x32_bf16 v[98:101], v[178:181], v[194:197], 0
	v_mfma_f32_16x16x32_bf16 v[90:93], v[170:173], v[202:205], 0
	v_mfma_f32_16x16x32_bf16 v[82:85], v[178:181], v[202:205], 0
	v_mfma_f32_16x16x32_bf16 v[74:77], v[170:173], v[210:213], 0
	v_mfma_f32_16x16x32_bf16 v[66:69], v[178:181], v[210:213], 0
	v_mfma_f32_16x16x32_bf16 v[122:125], v[174:177], v[190:193], v[122:125]
	v_mfma_f32_16x16x32_bf16 v[114:117], v[182:185], v[190:193], v[114:117]
	v_mfma_f32_16x16x32_bf16 v[106:109], v[174:177], v[198:201], v[106:109]
	v_mfma_f32_16x16x32_bf16 v[98:101], v[182:185], v[198:201], v[98:101]
	v_mfma_f32_16x16x32_bf16 v[90:93], v[174:177], v[206:209], v[90:93]
	v_mfma_f32_16x16x32_bf16 v[82:85], v[182:185], v[206:209], v[82:85]
	v_mfma_f32_16x16x32_bf16 v[74:77], v[174:177], v[214:217], v[74:77]
	v_mfma_f32_16x16x32_bf16 v[66:69], v[182:185], v[214:217], v[66:69]
	s_setprio 0
	s_barrier
	s_mov_b32 m0, s19
	v_lshl_add_u64 v[218:219], s[22:23], 0, v[134:135]
	s_add_u32 s58, s22, 0x40000
	ds_read_b128 v[186:189], v154 offset:16384
	ds_read_b128 v[190:193], v154 offset:17408
	ds_read_b128 v[194:197], v154 offset:18432
	ds_read_b128 v[198:201], v154 offset:19456
	ds_read_b128 v[202:205], v154 offset:20480
	ds_read_b128 v[206:209], v154 offset:21504
	ds_read_b128 v[210:213], v154 offset:22528
	ds_read_b128 v[214:217], v154 offset:23552
	global_load_lds_dwordx4 v[218:219], off
	v_lshl_add_u64 v[220:221], s[22:23], 0, v[130:131]
	s_mov_b32 m0, s38
	s_addc_u32 s59, s23, 0
	global_load_lds_dwordx4 v[220:221], off
	v_lshl_add_u64 v[222:223], s[58:59], 0, v[134:135]
	s_mov_b32 m0, s39
	v_lshl_add_u64 v[224:225], s[24:25], 0, v[132:133]
	global_load_lds_dwordx4 v[222:223], off
	v_lshl_add_u64 v[222:223], s[58:59], 0, v[130:131]
	s_mov_b32 m0, s40
	s_nop 0
	global_load_lds_dwordx4 v[222:223], off
	v_lshl_add_u64 v[222:223], s[24:25], 0, v[136:137]
	s_mov_b32 m0, s41
	s_nop 0
	global_load_lds_dwordx4 v[222:223], off
	s_mov_b32 m0, s42
	s_nop 0
	global_load_lds_dwordx4 v[224:225], off
	s_waitcnt vmcnt(8)
	s_waitcnt lgkmcnt(0)
	s_barrier
; #define PG8_STAGE(bufoff, gbase, voff) do { _Pragma("unroll") for (int _i = 0; _i < 2; ++_i) \
;         __builtin_amdgcn_global_load_lds((const unsigned*)((const char*)(gbase) + (voff)[_i]), (PG8_LAS unsigned*)(lds + (bufoff) + ldsw + _i * 8192), 16, 0, 0); } while (0)
; #define PG8_LDA(dst, b, h) do { _Pragma("unroll") for (int m = 0; m < 4; ++m) _Pragma("unroll") for (int k = 0; k < 2; ++k) dst[m][k] = *(const PG8_LAS bf16x8*)(lds + PG8_SA(b, h) + aoff + m * 2048 + k * 1024); } while (0)
; #define PG8_LDB(dst, b, h) do { _Pragma("unroll") for (int n = 0; n < 2; ++n) _Pragma("unroll") for (int k = 0; k < 2; ++k) dst[n][k] = *(const PG8_LAS bf16x8*)(lds + PG8_SB(b, h) + boff + n * 2048 + k * 1024); } while (0)
; #define PG8_MMA(ai, bj, At, Bt) do { __builtin_amdgcn_s_setprio(1); _Pragma("unroll") for (int m = 0; m < 4; ++m) _Pragma("unroll") for (int n = 0; n < 2; ++n) _Pragma("unroll") for (int k = 0; k < 2; ++k) \
;         acc[ai][bj][m][n] = __builtin_amdgcn_mfma_f32_16x16x32_bf16(Bt[n][k], At[m][k], acc[ai][bj][m][n], 0, 0, 0); __builtin_amdgcn_s_setprio(0); } while (0)
; #define PG8_WAIT_V(n) asm volatile("s_waitcnt vmcnt(" #n ")" ::: "memory")
; #define PG8_WAIT_L(n) asm volatile("s_waitcnt lgkmcnt(" #n ")" ::: "memory")
; #define PG8_BAR __builtin_amdgcn_s_barrier()
; #define PG8_SCHED __builtin_amdgcn_sched_barrier(0)
; template <class Epi, class Sched, bool ALIGN_EPI = false, bool SP2 = false>
; __device__ __forceinline__ void gemm_phase(PG8_LAS unsigned char* lds, const Gemm g, const Sched& S, const Epi& E) {
;     ...
;             PG8_WAIT_V(8); PG8_WAIT_L(0); PG8_BAR; PG8_MMA(1, 0, At, B0); PG8_MMA(1, 1, At, B1); PG8_BAR; PG8_SCHED;
;             PG8_LDB(B0, 1, 0); PG8_LDB(B1, 1, 1); PG8_SCHED; PG8_LDA(At, 1, 0); PG8_STAGE(PG8_SA(0, 1), a2 + hstep, voffA);
;             PG8_WAIT_V(8); PG8_WAIT_L(0); PG8_BAR; PG8_MMA(0, 0, At, B0); PG8_MMA(0, 1, At, B1); PG8_BAR; PG8_SCHED;
	s_setprio 1
	s_waitcnt lgkmcnt(0)
	v_mfma_f32_16x16x32_bf16 v[62:65], v[146:149], v[186:189], 0
	v_mfma_f32_16x16x32_bf16 v[54:57], v[162:165], v[186:189], 0
	v_mfma_f32_16x16x32_bf16 v[46:49], v[146:149], v[194:197], 0
	v_mfma_f32_16x16x32_bf16 v[38:41], v[162:165], v[194:197], 0
	v_mfma_f32_16x16x32_bf16 v[30:33], v[146:149], v[202:205], 0
	v_mfma_f32_16x16x32_bf16 v[22:25], v[162:165], v[202:205], 0
	v_mfma_f32_16x16x32_bf16 v[14:17], v[146:149], v[210:213], 0
	v_mfma_f32_16x16x32_bf16 v[6:9], v[162:165], v[210:213], 0
	v_mfma_f32_16x16x32_bf16 v[62:65], v[158:161], v[190:193], v[62:65]
	v_mfma_f32_16x16x32_bf16 v[54:57], v[166:169], v[190:193], v[54:57]
	v_mfma_f32_16x16x32_bf16 v[46:49], v[158:161], v[198:201], v[46:49]
	v_mfma_f32_16x16x32_bf16 v[38:41], v[166:169], v[198:201], v[38:41]
	v_mfma_f32_16x16x32_bf16 v[30:33], v[158:161], v[206:209], v[30:33]
	v_mfma_f32_16x16x32_bf16 v[22:25], v[166:169], v[206:209], v[22:25]
	v_mfma_f32_16x16x32_bf16 v[14:17], v[158:161], v[214:217], v[14:17]
	v_mfma_f32_16x16x32_bf16 v[6:9], v[166:169], v[214:217], v[6:9]
	s_setprio 0
	s_setprio 1
	v_mfma_f32_16x16x32_bf16 v[58:61], v[170:173], v[186:189], 0
	v_mfma_f32_16x16x32_bf16 v[50:53], v[178:181], v[186:189], 0
	v_mfma_f32_16x16x32_bf16 v[42:45], v[170:173], v[194:197], 0
	v_mfma_f32_16x16x32_bf16 v[34:37], v[178:181], v[194:197], 0
	v_mfma_f32_16x16x32_bf16 v[26:29], v[170:173], v[202:205], 0
	v_mfma_f32_16x16x32_bf16 v[18:21], v[178:181], v[202:205], 0
	v_mfma_f32_16x16x32_bf16 v[10:13], v[170:173], v[210:213], 0
	v_mfma_f32_16x16x32_bf16 v[2:5], v[178:181], v[210:213], 0
	v_mfma_f32_16x16x32_bf16 v[58:61], v[174:177], v[190:193], v[58:61]
	v_mfma_f32_16x16x32_bf16 v[50:53], v[182:185], v[190:193], v[50:53]
	v_mfma_f32_16x16x32_bf16 v[42:45], v[174:177], v[198:201], v[42:45]
	v_mfma_f32_16x16x32_bf16 v[34:37], v[182:185], v[198:201], v[34:37]
	v_mfma_f32_16x16x32_bf16 v[26:29], v[174:177], v[206:209], v[26:29]
	v_mfma_f32_16x16x32_bf16 v[18:21], v[182:185], v[206:209], v[18:21]
	v_mfma_f32_16x16x32_bf16 v[10:13], v[174:177], v[214:217], v[10:13]
	v_mfma_f32_16x16x32_bf16 v[2:5], v[182:185], v[214:217], v[2:5]
	s_setprio 0
	s_barrier
	ds_read_b128 v[146:149], v155
	ds_read_b128 v[158:161], v155 offset:1024
	ds_read_b128 v[162:165], v155 offset:2048
	ds_read_b128 v[166:169], v155 offset:3072
	ds_read_b128 v[170:173], v156
	ds_read_b128 v[174:177], v156 offset:1024
	ds_read_b128 v[178:181], v156 offset:2048
	ds_read_b128 v[182:185], v156 offset:3072
	s_add_u32 s24, s24, 0x40000
	s_addc_u32 s25, s25, 0
	s_mov_b32 m0, s43
	v_lshl_add_u64 v[226:227], s[24:25], 0, v[136:137]
	ds_read_b128 v[186:189], v154 offset:32768
	ds_read_b128 v[190:193], v154 offset:33792
	ds_read_b128 v[194:197], v154 offset:34816
	ds_read_b128 v[198:201], v154 offset:35840
	ds_read_b128 v[202:205], v154 offset:36864
	ds_read_b128 v[206:209], v154 offset:37888
	ds_read_b128 v[210:213], v154 offset:38912
	ds_read_b128 v[214:217], v154 offset:39936
	global_load_lds_dwordx4 v[226:227], off
	v_lshl_add_u64 v[226:227], s[24:25], 0, v[132:133]
	s_mov_b32 m0, s44
	s_nop 0
	global_load_lds_dwordx4 v[226:227], off
	s_waitcnt vmcnt(8)
	s_waitcnt lgkmcnt(0)
	s_barrier
	s_setprio 1
	s_waitcnt lgkmcnt(0)
	v_mfma_f32_16x16x32_bf16 v[126:129], v[146:149], v[186:189], v[126:129]
	v_mfma_f32_16x16x32_bf16 v[118:121], v[162:165], v[186:189], v[118:121]
	v_mfma_f32_16x16x32_bf16 v[110:113], v[146:149], v[194:197], v[110:113]
	v_mfma_f32_16x16x32_bf16 v[102:105], v[162:165], v[194:197], v[102:105]
	v_mfma_f32_16x16x32_bf16 v[94:97], v[146:149], v[202:205], v[94:97]
	v_mfma_f32_16x16x32_bf16 v[86:89], v[162:165], v[202:205], v[86:89]
	v_mfma_f32_16x16x32_bf16 v[78:81], v[146:149], v[210:213], v[78:81]
	v_mfma_f32_16x16x32_bf16 v[70:73], v[162:165], v[210:213], v[70:73]
	v_mfma_f32_16x16x32_bf16 v[126:129], v[158:161], v[190:193], v[126:129]
	v_mfma_f32_16x16x32_bf16 v[118:121], v[166:169], v[190:193], v[118:121]
	v_mfma_f32_16x16x32_bf16 v[110:113], v[158:161], v[198:201], v[110:113]
	v_mfma_f32_16x16x32_bf16 v[102:105], v[166:169], v[198:201], v[102:105]
	v_mfma_f32_16x16x32_bf16 v[94:97], v[158:161], v[206:209], v[94:97]
	v_mfma_f32_16x16x32_bf16 v[86:89], v[166:169], v[206:209], v[86:89]
	v_mfma_f32_16x16x32_bf16 v[78:81], v[158:161], v[214:217], v[78:81]
	v_mfma_f32_16x16x32_bf16 v[70:73], v[166:169], v[214:217], v[70:73]
	s_setprio 0
	s_setprio 1
	v_mfma_f32_16x16x32_bf16 v[122:125], v[170:173], v[186:189], v[122:125]
	v_mfma_f32_16x16x32_bf16 v[114:117], v[178:181], v[186:189], v[114:117]
	v_mfma_f32_16x16x32_bf16 v[106:109], v[170:173], v[194:197], v[106:109]
	v_mfma_f32_16x16x32_bf16 v[98:101], v[178:181], v[194:197], v[98:101]
	v_mfma_f32_16x16x32_bf16 v[90:93], v[170:173], v[202:205], v[90:93]
	v_mfma_f32_16x16x32_bf16 v[82:85], v[178:181], v[202:205], v[82:85]
	v_mfma_f32_16x16x32_bf16 v[74:77], v[170:173], v[210:213], v[74:77]
	v_mfma_f32_16x16x32_bf16 v[66:69], v[178:181], v[210:213], v[66:69]
	v_mfma_f32_16x16x32_bf16 v[122:125], v[174:177], v[190:193], v[122:125]
	v_mfma_f32_16x16x32_bf16 v[114:117], v[182:185], v[190:193], v[114:117]
	v_mfma_f32_16x16x32_bf16 v[106:109], v[174:177], v[198:201], v[106:109]
	v_mfma_f32_16x16x32_bf16 v[98:101], v[182:185], v[198:201], v[98:101]
	v_mfma_f32_16x16x32_bf16 v[90:93], v[174:177], v[206:209], v[90:93]
	v_mfma_f32_16x16x32_bf16 v[82:85], v[182:185], v[206:209], v[82:85]
	v_mfma_f32_16x16x32_bf16 v[74:77], v[174:177], v[214:217], v[74:77]
	v_mfma_f32_16x16x32_bf16 v[66:69], v[182:185], v[214:217], v[66:69]
	s_setprio 0
	s_barrier
; #define PG8_STAGE(bufoff, gbase, voff) do { _Pragma("unroll") for (int _i = 0; _i < 2; ++_i) \
;         __builtin_amdgcn_global_load_lds((const unsigned*)((const char*)(gbase) + (voff)[_i]), (PG8_LAS unsigned*)(lds + (bufoff) + ldsw + _i * 8192), 16, 0, 0); } while (0)
; #define PG8_LDA(dst, b, h) do { _Pragma("unroll") for (int m = 0; m < 4; ++m) _Pragma("unroll") for (int k = 0; k < 2; ++k) dst[m][k] = *(const PG8_LAS bf16x8*)(lds + PG8_SA(b, h) + aoff + m * 2048 + k * 1024); } while (0)
; #define PG8_MMA(ai, bj, At, Bt) do { __builtin_amdgcn_s_setprio(1); _Pragma("unroll") for (int m = 0; m < 4; ++m) _Pragma("unroll") for (int n = 0; n < 2; ++n) _Pragma("unroll") for (int k = 0; k < 2; ++k) \
;         acc[ai][bj][m][n] = __builtin_amdgcn_mfma_f32_16x16x32_bf16(Bt[n][k], At[m][k], acc[ai][bj][m][n], 0, 0, 0); __builtin_amdgcn_s_setprio(0); } while (0)
; #define PG8_WAIT_V(n) asm volatile("s_waitcnt vmcnt(" #n ")" ::: "memory")
; #define PG8_WAIT_L(n) asm volatile("s_waitcnt lgkmcnt(" #n ")" ::: "memory")
; #define PG8_BAR __builtin_amdgcn_s_barrier()
; #define PG8_SCHED __builtin_amdgcn_sched_barrier(0)
; template <class Epi, class Sched, bool ALIGN_EPI = false, bool SP2 = false>
; __device__ __forceinline__ void gemm_phase(PG8_LAS unsigned char* lds, const Gemm g, const Sched& S, const Epi& E) {
;     ...
;         for (int t = 0; t < nt; t += 2) {
;     ...
;             PG8_LDA(At, 1, 1); PG8_STAGE(PG8_SB(1, 0), b3, voffB); PG8_STAGE(PG8_SB(1, 1), b3 + hstep, voffB); PG8_STAGE(PG8_SA(1, 0), a3, voffA);
;             PG8_WAIT_V(8); PG8_WAIT_L(0); PG8_BAR; PG8_MMA(1, 0, At, B0); PG8_MMA(1, 1, At, B1); PG8_BAR; PG8_SCHED;
	s_mov_b32 m0, s45
	v_lshl_add_u64 v[218:219], v[218:219], 0, s[6:7]
	s_add_u32 s22, s22, 0x40080
	ds_read_b128 v[186:189], v154 offset:49152
	ds_read_b128 v[190:193], v154 offset:50176
	ds_read_b128 v[194:197], v154 offset:51200
	ds_read_b128 v[198:201], v154 offset:52224
	ds_read_b128 v[202:205], v154 offset:53248
	ds_read_b128 v[206:209], v154 offset:54272
	ds_read_b128 v[210:213], v154 offset:55296
	ds_read_b128 v[214:217], v154 offset:56320
	global_load_lds_dwordx4 v[218:219], off
	v_lshl_add_u64 v[218:219], v[220:221], 0, s[6:7]
	s_mov_b32 m0, s46
	s_addc_u32 s23, s23, 0
	global_load_lds_dwordx4 v[218:219], off
	v_lshl_add_u64 v[218:219], s[22:23], 0, v[134:135]
	s_mov_b32 m0, s53
	s_nop 0
	global_load_lds_dwordx4 v[218:219], off
	v_lshl_add_u64 v[218:219], s[22:23], 0, v[130:131]
	s_mov_b32 m0, s56
	s_nop 0
	global_load_lds_dwordx4 v[218:219], off
	v_lshl_add_u64 v[218:219], v[222:223], 0, s[6:7]
	s_mov_b32 m0, s47
	s_nop 0
	global_load_lds_dwordx4 v[218:219], off
	v_lshl_add_u64 v[218:219], v[224:225], 0, s[6:7]
	s_mov_b32 m0, s52
	s_nop 0
	global_load_lds_dwordx4 v[218:219], off
	s_waitcnt vmcnt(8)
	s_waitcnt lgkmcnt(0)
	s_barrier
	s_setprio 1
	s_waitcnt lgkmcnt(0)
	v_mfma_f32_16x16x32_bf16 v[62:65], v[146:149], v[186:189], v[62:65]
	v_mfma_f32_16x16x32_bf16 v[54:57], v[162:165], v[186:189], v[54:57]
	v_mfma_f32_16x16x32_bf16 v[46:49], v[146:149], v[194:197], v[46:49]
	v_mfma_f32_16x16x32_bf16 v[38:41], v[162:165], v[194:197], v[38:41]
	v_mfma_f32_16x16x32_bf16 v[30:33], v[146:149], v[202:205], v[30:33]
	v_mfma_f32_16x16x32_bf16 v[22:25], v[162:165], v[202:205], v[22:25]
	v_mfma_f32_16x16x32_bf16 v[14:17], v[146:149], v[210:213], v[14:17]
	v_mfma_f32_16x16x32_bf16 v[6:9], v[162:165], v[210:213], v[6:9]
	v_mfma_f32_16x16x32_bf16 v[62:65], v[158:161], v[190:193], v[62:65]
	v_mfma_f32_16x16x32_bf16 v[54:57], v[166:169], v[190:193], v[54:57]
	v_mfma_f32_16x16x32_bf16 v[46:49], v[158:161], v[198:201], v[46:49]
	v_mfma_f32_16x16x32_bf16 v[38:41], v[166:169], v[198:201], v[38:41]
	v_mfma_f32_16x16x32_bf16 v[30:33], v[158:161], v[206:209], v[30:33]
	v_mfma_f32_16x16x32_bf16 v[22:25], v[166:169], v[206:209], v[22:25]
	v_mfma_f32_16x16x32_bf16 v[14:17], v[158:161], v[214:217], v[14:17]
	v_mfma_f32_16x16x32_bf16 v[6:9], v[166:169], v[214:217], v[6:9]
	s_setprio 0
	s_setprio 1
	v_mfma_f32_16x16x32_bf16 v[58:61], v[170:173], v[186:189], v[58:61]
	v_mfma_f32_16x16x32_bf16 v[50:53], v[178:181], v[186:189], v[50:53]
	v_mfma_f32_16x16x32_bf16 v[42:45], v[170:173], v[194:197], v[42:45]
	v_mfma_f32_16x16x32_bf16 v[34:37], v[178:181], v[194:197], v[34:37]
	v_mfma_f32_16x16x32_bf16 v[26:29], v[170:173], v[202:205], v[26:29]
	v_mfma_f32_16x16x32_bf16 v[18:21], v[178:181], v[202:205], v[18:21]
	v_mfma_f32_16x16x32_bf16 v[10:13], v[170:173], v[210:213], v[10:13]
	v_mfma_f32_16x16x32_bf16 v[2:5], v[178:181], v[210:213], v[2:5]
	v_mfma_f32_16x16x32_bf16 v[58:61], v[174:177], v[190:193], v[58:61]
	v_mfma_f32_16x16x32_bf16 v[50:53], v[182:185], v[190:193], v[50:53]
	v_mfma_f32_16x16x32_bf16 v[42:45], v[174:177], v[198:201], v[42:45]
	v_mfma_f32_16x16x32_bf16 v[34:37], v[182:185], v[198:201], v[34:37]
	v_mfma_f32_16x16x32_bf16 v[26:29], v[174:177], v[206:209], v[26:29]
	v_mfma_f32_16x16x32_bf16 v[18:21], v[182:185], v[206:209], v[18:21]
	v_mfma_f32_16x16x32_bf16 v[10:13], v[174:177], v[214:217], v[10:13]
	v_mfma_f32_16x16x32_bf16 v[2:5], v[182:185], v[214:217], v[2:5]
	s_setprio 0
	s_barrier
	s_add_i32 s54, s54, 2
	s_add_u32 s50, s50, 0x100
	s_addc_u32 s51, s51, 0
	s_add_u32 s20, s20, 0x100
	s_addc_u32 s21, s21, 0
	s_cmp_gt_u32 s54, 13

; #define PG8_STAGE(bufoff, gbase, voff) do { _Pragma("unroll") for (int _i = 0; _i < 2; ++_i) \
;         __builtin_amdgcn_global_load_lds((const unsigned*)((const char*)(gbase) + (voff)[_i]), (PG8_LAS unsigned*)(lds + (bufoff) + ldsw + _i * 8192), 16, 0, 0); } while (0)
; #define PG8_LDA(dst, b, h) do { _Pragma("unroll") for (int m = 0; m < 4; ++m) _Pragma("unroll") for (int k = 0; k < 2; ++k) dst[m][k] = *(const PG8_LAS bf16x8*)(lds + PG8_SA(b, h) + aoff + m * 2048 + k * 1024); } while (0)
; #define PG8_LDB(dst, b, h) do { _Pragma("unroll") for (int n = 0; n < 2; ++n) _Pragma("unroll") for (int k = 0; k < 2; ++k) dst[n][k] = *(const PG8_LAS bf16x8*)(lds + PG8_SB(b, h) + boff + n * 2048 + k * 1024); } while (0)
; #define PG8_MMA(ai, bj, At, Bt) do { __builtin_amdgcn_s_setprio(1); _Pragma("unroll") for (int m = 0; m < 4; ++m) _Pragma("unroll") for (int n = 0; n < 2; ++n) _Pragma("unroll") for (int k = 0; k < 2; ++k) \
;         acc[ai][bj][m][n] = __builtin_amdgcn_mfma_f32_16x16x32_bf16(Bt[n][k], At[m][k], acc[ai][bj][m][n], 0, 0, 0); __builtin_amdgcn_s_setprio(0); } while (0)
; #define PG8_WAIT_V(n) asm volatile("s_waitcnt vmcnt(" #n ")" ::: "memory")
; #define PG8_WAIT_L(n) asm volatile("s_waitcnt lgkmcnt(" #n ")" ::: "memory")
; #define PG8_BAR __builtin_amdgcn_s_barrier()
; #define PG8_SCHED __builtin_amdgcn_sched_barrier(0)
; template <class Epi, class Sched, bool ALIGN_EPI = false, bool SP2 = false>
; __device__ __forceinline__ void gemm_phase(PG8_LAS unsigned char* lds, const Gemm g, const Sched& S, const Epi& E) {
;     ...
;         for (int t = 0; t < nt; t += 2) {
;             const bool last = (t == nt - 2);
;             const char* a1 = cA + (size_t)(t + 1) * kstep;
;             const char* a2 = last ? nA : cA + (size_t)(t + 2) * kstep; const char* b2 = last ? nB : cB + (size_t)(t + 2) * kstep;
;             const char* a3 = a2 + kstep; const char* b3 = b2 + kstep;
;             if (last && has_next) S.a_ready(nxt);
;             if constexpr (SP2) {
;             PG8_LDB(B0, 0, 0); PG8_LDB(B1, 0, 1); PG8_SCHED; PG8_LDA(At, 0, 0); PG8_STAGE(PG8_SA(1, 1), a1 + hstep, voffA);
;             PG8_WAIT_V(8); PG8_WAIT_L(0); PG8_BAR; PG8_MMA(0, 0, At, B0); PG8_MMA(0, 1, At, B1); PG8_BAR; PG8_SCHED;
;             PG8_LDA(At, 0, 1); PG8_STAGE(PG8_SB(0, 0), b2, voffB); PG8_STAGE(PG8_SB(0, 1), b2 + hstep, voffB); PG8_STAGE(PG8_SA(0, 0), a2, voffA);
.LBB0_1125:
	s_add_u32 s91, s46, 0x100
	s_addc_u32 s92, s47, 0
	s_mov_b32 s52, 0
	ds_read_b128 v[150:153], v147
	ds_read_b128 v[154:157], v147 offset:1024
	ds_read_b128 v[158:161], v147 offset:2048
	ds_read_b128 v[162:165], v147 offset:3072
	ds_read_b128 v[166:169], v148
	ds_read_b128 v[170:173], v148 offset:1024
	ds_read_b128 v[174:177], v148 offset:2048
	ds_read_b128 v[178:181], v148 offset:3072
	s_add_i32 s93, s52, 2
	s_add_u32 s46, s44, 0x100
	s_addc_u32 s47, s45, 0
	s_cmp_eq_u32 s86, s52
	s_cselect_b32 s52, s42, s91
	s_cselect_b32 s57, s41, s47
	s_cselect_b32 s56, s40, s46
	s_cselect_b32 s53, s43, s92
	v_lshl_add_u64 v[214:215], s[44:45], 0, v[140:141]
	s_add_i32 m0, s77, 0xc000
	ds_read_b128 v[182:185], v146
	ds_read_b128 v[186:189], v146 offset:1024
	ds_read_b128 v[190:193], v146 offset:2048
	ds_read_b128 v[194:197], v146 offset:3072
	ds_read_b128 v[198:201], v146 offset:4096
	ds_read_b128 v[202:205], v146 offset:5120
	ds_read_b128 v[206:209], v146 offset:6144
	ds_read_b128 v[210:213], v146 offset:7168
	global_load_lds_dwordx4 v[214:215], off
	v_lshl_add_u64 v[214:215], s[44:45], 0, v[138:139]
	s_add_i32 m0, s77, 0xe000
	s_nop 0
	global_load_lds_dwordx4 v[214:215], off
	s_waitcnt vmcnt(8)
	s_waitcnt lgkmcnt(0)
	s_barrier
	s_setprio 1
	s_waitcnt lgkmcnt(0)
	v_mfma_f32_16x16x32_bf16 v[126:129], v[150:153], v[182:185], 0
	v_mfma_f32_16x16x32_bf16 v[122:125], v[158:161], v[182:185], 0
	v_mfma_f32_16x16x32_bf16 v[118:121], v[150:153], v[190:193], 0
	v_mfma_f32_16x16x32_bf16 v[114:117], v[158:161], v[190:193], 0
	v_mfma_f32_16x16x32_bf16 v[102:105], v[150:153], v[198:201], 0
	v_mfma_f32_16x16x32_bf16 v[98:101], v[158:161], v[198:201], 0
	v_mfma_f32_16x16x32_bf16 v[86:89], v[150:153], v[206:209], 0
	v_mfma_f32_16x16x32_bf16 v[82:85], v[158:161], v[206:209], 0
	v_mfma_f32_16x16x32_bf16 v[126:129], v[154:157], v[186:189], v[126:129]
	v_mfma_f32_16x16x32_bf16 v[122:125], v[162:165], v[186:189], v[122:125]
	v_mfma_f32_16x16x32_bf16 v[118:121], v[154:157], v[194:197], v[118:121]
	v_mfma_f32_16x16x32_bf16 v[114:117], v[162:165], v[194:197], v[114:117]
	v_mfma_f32_16x16x32_bf16 v[102:105], v[154:157], v[202:205], v[102:105]
	v_mfma_f32_16x16x32_bf16 v[98:101], v[162:165], v[202:205], v[98:101]
	v_mfma_f32_16x16x32_bf16 v[86:89], v[154:157], v[210:213], v[86:89]
	v_mfma_f32_16x16x32_bf16 v[82:85], v[162:165], v[210:213], v[82:85]
	s_setprio 0
	s_setprio 1
	v_mfma_f32_16x16x32_bf16 v[110:113], v[166:169], v[182:185], 0
	v_mfma_f32_16x16x32_bf16 v[106:109], v[174:177], v[182:185], 0
	v_mfma_f32_16x16x32_bf16 v[94:97], v[166:169], v[190:193], 0
	v_mfma_f32_16x16x32_bf16 v[90:93], v[174:177], v[190:193], 0
	v_mfma_f32_16x16x32_bf16 v[78:81], v[166:169], v[198:201], 0
	v_mfma_f32_16x16x32_bf16 v[74:77], v[174:177], v[198:201], 0
	v_mfma_f32_16x16x32_bf16 v[70:73], v[166:169], v[206:209], 0
	v_mfma_f32_16x16x32_bf16 v[66:69], v[174:177], v[206:209], 0
	v_mfma_f32_16x16x32_bf16 v[110:113], v[170:173], v[186:189], v[110:113]
	v_mfma_f32_16x16x32_bf16 v[106:109], v[178:181], v[186:189], v[106:109]
	v_mfma_f32_16x16x32_bf16 v[94:97], v[170:173], v[194:197], v[94:97]
	v_mfma_f32_16x16x32_bf16 v[90:93], v[178:181], v[194:197], v[90:93]
	v_mfma_f32_16x16x32_bf16 v[78:81], v[170:173], v[202:205], v[78:81]
	v_mfma_f32_16x16x32_bf16 v[74:77], v[178:181], v[202:205], v[74:77]
	v_mfma_f32_16x16x32_bf16 v[70:73], v[170:173], v[210:213], v[70:73]
	v_mfma_f32_16x16x32_bf16 v[66:69], v[178:181], v[210:213], v[66:69]
	s_setprio 0
	s_barrier
	s_mov_b32 m0, s73
	v_lshl_add_u64 v[214:215], s[52:53], 0, v[130:131]
	s_add_u32 s44, s52, 0xb0000
	ds_read_b128 v[182:185], v146 offset:16384
	ds_read_b128 v[186:189], v146 offset:17408
	ds_read_b128 v[190:193], v146 offset:18432
	ds_read_b128 v[194:197], v146 offset:19456
	ds_read_b128 v[198:201], v146 offset:20480
	ds_read_b128 v[202:205], v146 offset:21504
	ds_read_b128 v[206:209], v146 offset:22528
	ds_read_b128 v[210:213], v146 offset:23552
	global_load_lds_dwordx4 v[214:215], off
	v_lshl_add_u64 v[216:217], s[52:53], 0, v[136:137]
	s_mov_b32 m0, s74
	s_addc_u32 s45, s53, 0
	global_load_lds_dwordx4 v[216:217], off
	v_lshl_add_u64 v[218:219], s[44:45], 0, v[130:131]
	s_mov_b32 m0, s75
	v_lshl_add_u64 v[220:221], s[56:57], 0, v[134:135]
	global_load_lds_dwordx4 v[218:219], off
	v_lshl_add_u64 v[218:219], s[44:45], 0, v[136:137]
	s_mov_b32 m0, s76
	s_nop 0
	global_load_lds_dwordx4 v[218:219], off
	v_lshl_add_u64 v[218:219], s[56:57], 0, v[132:133]
	s_mov_b32 m0, s77
	s_nop 0
	global_load_lds_dwordx4 v[218:219], off
	s_mov_b32 m0, s78
	s_nop 0
	global_load_lds_dwordx4 v[220:221], off
	s_waitcnt vmcnt(8)
	s_waitcnt lgkmcnt(0)
	s_barrier
; #define PG8_STAGE(bufoff, gbase, voff) do { _Pragma("unroll") for (int _i = 0; _i < 2; ++_i) \
;         __builtin_amdgcn_global_load_lds((const unsigned*)((const char*)(gbase) + (voff)[_i]), (PG8_LAS unsigned*)(lds + (bufoff) + ldsw + _i * 8192), 16, 0, 0); } while (0)
; #define PG8_LDA(dst, b, h) do { _Pragma("unroll") for (int m = 0; m < 4; ++m) _Pragma("unroll") for (int k = 0; k < 2; ++k) dst[m][k] = *(const PG8_LAS bf16x8*)(lds + PG8_SA(b, h) + aoff + m * 2048 + k * 1024); } while (0)
; #define PG8_LDB(dst, b, h) do { _Pragma("unroll") for (int n = 0; n < 2; ++n) _Pragma("unroll") for (int k = 0; k < 2; ++k) dst[n][k] = *(const PG8_LAS bf16x8*)(lds + PG8_SB(b, h) + boff + n * 2048 + k * 1024); } while (0)
; #define PG8_MMA(ai, bj, At, Bt) do { __builtin_amdgcn_s_setprio(1); _Pragma("unroll") for (int m = 0; m < 4; ++m) _Pragma("unroll") for (int n = 0; n < 2; ++n) _Pragma("unroll") for (int k = 0; k < 2; ++k) \
;         acc[ai][bj][m][n] = __builtin_amdgcn_mfma_f32_16x16x32_bf16(Bt[n][k], At[m][k], acc[ai][bj][m][n], 0, 0, 0); __builtin_amdgcn_s_setprio(0); } while (0)
; #define PG8_WAIT_V(n) asm volatile("s_waitcnt vmcnt(" #n ")" ::: "memory")
; #define PG8_WAIT_L(n) asm volatile("s_waitcnt lgkmcnt(" #n ")" ::: "memory")
; #define PG8_BAR __builtin_amdgcn_s_barrier()
; #define PG8_SCHED __builtin_amdgcn_sched_barrier(0)
; template <class Epi, class Sched, bool ALIGN_EPI = false, bool SP2 = false>
; __device__ __forceinline__ void gemm_phase(PG8_LAS unsigned char* lds, const Gemm g, const Sched& S, const Epi& E) {
;     ...
;             PG8_WAIT_V(8); PG8_WAIT_L(0); PG8_BAR; PG8_MMA(1, 0, At, B0); PG8_MMA(1, 1, At, B1); PG8_BAR; PG8_SCHED;
;             PG8_LDB(B0, 1, 0); PG8_LDB(B1, 1, 1); PG8_SCHED; PG8_LDA(At, 1, 0); PG8_STAGE(PG8_SA(0, 1), a2 + hstep, voffA);
;             PG8_WAIT_V(8); PG8_WAIT_L(0); PG8_BAR; PG8_MMA(0, 0, At, B0); PG8_MMA(0, 1, At, B1); PG8_BAR; PG8_SCHED;
	s_setprio 1
	s_waitcnt lgkmcnt(0)
	v_mfma_f32_16x16x32_bf16 v[62:65], v[150:153], v[182:185], 0
	v_mfma_f32_16x16x32_bf16 v[58:61], v[158:161], v[182:185], 0
	v_mfma_f32_16x16x32_bf16 v[54:57], v[150:153], v[190:193], 0
	v_mfma_f32_16x16x32_bf16 v[50:53], v[158:161], v[190:193], 0
	v_mfma_f32_16x16x32_bf16 v[38:41], v[150:153], v[198:201], 0
	v_mfma_f32_16x16x32_bf16 v[34:37], v[158:161], v[198:201], 0
	v_mfma_f32_16x16x32_bf16 v[22:25], v[150:153], v[206:209], 0
	v_mfma_f32_16x16x32_bf16 v[18:21], v[158:161], v[206:209], 0
	v_mfma_f32_16x16x32_bf16 v[62:65], v[154:157], v[186:189], v[62:65]
	v_mfma_f32_16x16x32_bf16 v[58:61], v[162:165], v[186:189], v[58:61]
	v_mfma_f32_16x16x32_bf16 v[54:57], v[154:157], v[194:197], v[54:57]
	v_mfma_f32_16x16x32_bf16 v[50:53], v[162:165], v[194:197], v[50:53]
	v_mfma_f32_16x16x32_bf16 v[38:41], v[154:157], v[202:205], v[38:41]
	v_mfma_f32_16x16x32_bf16 v[34:37], v[162:165], v[202:205], v[34:37]
	v_mfma_f32_16x16x32_bf16 v[22:25], v[154:157], v[210:213], v[22:25]
	v_mfma_f32_16x16x32_bf16 v[18:21], v[162:165], v[210:213], v[18:21]
	s_setprio 0
	s_setprio 1
	v_mfma_f32_16x16x32_bf16 v[46:49], v[166:169], v[182:185], 0
	v_mfma_f32_16x16x32_bf16 v[42:45], v[174:177], v[182:185], 0
	v_mfma_f32_16x16x32_bf16 v[30:33], v[166:169], v[190:193], 0
	v_mfma_f32_16x16x32_bf16 v[26:29], v[174:177], v[190:193], 0
	v_mfma_f32_16x16x32_bf16 v[14:17], v[166:169], v[198:201], 0
	v_mfma_f32_16x16x32_bf16 v[10:13], v[174:177], v[198:201], 0
	v_mfma_f32_16x16x32_bf16 v[6:9], v[166:169], v[206:209], 0
	v_mfma_f32_16x16x32_bf16 v[2:5], v[174:177], v[206:209], 0
	v_mfma_f32_16x16x32_bf16 v[46:49], v[170:173], v[186:189], v[46:49]
	v_mfma_f32_16x16x32_bf16 v[42:45], v[178:181], v[186:189], v[42:45]
	v_mfma_f32_16x16x32_bf16 v[30:33], v[170:173], v[194:197], v[30:33]
	v_mfma_f32_16x16x32_bf16 v[26:29], v[178:181], v[194:197], v[26:29]
	v_mfma_f32_16x16x32_bf16 v[14:17], v[170:173], v[202:205], v[14:17]
	v_mfma_f32_16x16x32_bf16 v[10:13], v[178:181], v[202:205], v[10:13]
	v_mfma_f32_16x16x32_bf16 v[6:9], v[170:173], v[210:213], v[6:9]
	v_mfma_f32_16x16x32_bf16 v[2:5], v[178:181], v[210:213], v[2:5]
	s_setprio 0
	s_barrier
	v_add_u32_e32 v178, s66, v144
	ds_read_b128 v[150:153], v149
	ds_read_b128 v[154:157], v149 offset:1024
	ds_read_b128 v[158:161], v149 offset:2048
	ds_read_b128 v[162:165], v149 offset:3072
	ds_read_b128 v[166:169], v178
	ds_read_b128 v[170:173], v178 offset:1024
	ds_read_b128 v[174:177], v178 offset:2048
	ds_read_b128 v[178:181], v178 offset:3072
	s_add_u32 s44, s56, 0xb0000
	s_addc_u32 s45, s57, 0
	s_mov_b32 m0, s79
	v_lshl_add_u64 v[222:223], s[44:45], 0, v[132:133]
	ds_read_b128 v[182:185], v146 offset:32768
	ds_read_b128 v[186:189], v146 offset:33792
	ds_read_b128 v[190:193], v146 offset:34816
	ds_read_b128 v[194:197], v146 offset:35840
	ds_read_b128 v[198:201], v146 offset:36864
	ds_read_b128 v[202:205], v146 offset:37888
	ds_read_b128 v[206:209], v146 offset:38912
	ds_read_b128 v[210:213], v146 offset:39936
	global_load_lds_dwordx4 v[222:223], off
	v_lshl_add_u64 v[222:223], s[44:45], 0, v[134:135]
	s_mov_b32 m0, s80
	s_nop 0
	global_load_lds_dwordx4 v[222:223], off
	s_waitcnt vmcnt(8)
	s_waitcnt lgkmcnt(0)
	s_barrier
	s_setprio 1
	s_waitcnt lgkmcnt(0)
	v_mfma_f32_16x16x32_bf16 v[126:129], v[150:153], v[182:185], v[126:129]
	v_mfma_f32_16x16x32_bf16 v[122:125], v[158:161], v[182:185], v[122:125]
	v_mfma_f32_16x16x32_bf16 v[118:121], v[150:153], v[190:193], v[118:121]
	v_mfma_f32_16x16x32_bf16 v[114:117], v[158:161], v[190:193], v[114:117]
	v_mfma_f32_16x16x32_bf16 v[102:105], v[150:153], v[198:201], v[102:105]
	v_mfma_f32_16x16x32_bf16 v[98:101], v[158:161], v[198:201], v[98:101]
	v_mfma_f32_16x16x32_bf16 v[86:89], v[150:153], v[206:209], v[86:89]
	v_mfma_f32_16x16x32_bf16 v[82:85], v[158:161], v[206:209], v[82:85]
	v_mfma_f32_16x16x32_bf16 v[126:129], v[154:157], v[186:189], v[126:129]
	v_mfma_f32_16x16x32_bf16 v[122:125], v[162:165], v[186:189], v[122:125]
	v_mfma_f32_16x16x32_bf16 v[118:121], v[154:157], v[194:197], v[118:121]
	v_mfma_f32_16x16x32_bf16 v[114:117], v[162:165], v[194:197], v[114:117]
	v_mfma_f32_16x16x32_bf16 v[102:105], v[154:157], v[202:205], v[102:105]
	v_mfma_f32_16x16x32_bf16 v[98:101], v[162:165], v[202:205], v[98:101]
	v_mfma_f32_16x16x32_bf16 v[86:89], v[154:157], v[210:213], v[86:89]
	v_mfma_f32_16x16x32_bf16 v[82:85], v[162:165], v[210:213], v[82:85]
	s_setprio 0
	s_setprio 1
	v_mfma_f32_16x16x32_bf16 v[110:113], v[166:169], v[182:185], v[110:113]
	v_mfma_f32_16x16x32_bf16 v[106:109], v[174:177], v[182:185], v[106:109]
	v_mfma_f32_16x16x32_bf16 v[94:97], v[166:169], v[190:193], v[94:97]
	v_mfma_f32_16x16x32_bf16 v[90:93], v[174:177], v[190:193], v[90:93]
	v_mfma_f32_16x16x32_bf16 v[78:81], v[166:169], v[198:201], v[78:81]
	v_mfma_f32_16x16x32_bf16 v[74:77], v[174:177], v[198:201], v[74:77]
	v_mfma_f32_16x16x32_bf16 v[70:73], v[166:169], v[206:209], v[70:73]
	v_mfma_f32_16x16x32_bf16 v[66:69], v[174:177], v[206:209], v[66:69]
	v_mfma_f32_16x16x32_bf16 v[110:113], v[170:173], v[186:189], v[110:113]
	v_mfma_f32_16x16x32_bf16 v[106:109], v[178:181], v[186:189], v[106:109]
	v_mfma_f32_16x16x32_bf16 v[94:97], v[170:173], v[194:197], v[94:97]
	v_mfma_f32_16x16x32_bf16 v[90:93], v[178:181], v[194:197], v[90:93]
	v_mfma_f32_16x16x32_bf16 v[78:81], v[170:173], v[202:205], v[78:81]
	v_mfma_f32_16x16x32_bf16 v[74:77], v[178:181], v[202:205], v[74:77]
	v_mfma_f32_16x16x32_bf16 v[70:73], v[170:173], v[210:213], v[70:73]
	v_mfma_f32_16x16x32_bf16 v[66:69], v[178:181], v[210:213], v[66:69]
	s_setprio 0
	s_barrier
; #define PG8_STAGE(bufoff, gbase, voff) do { _Pragma("unroll") for (int _i = 0; _i < 2; ++_i) \
;         __builtin_amdgcn_global_load_lds((const unsigned*)((const char*)(gbase) + (voff)[_i]), (PG8_LAS unsigned*)(lds + (bufoff) + ldsw + _i * 8192), 16, 0, 0); } while (0)
; #define PG8_LDA(dst, b, h) do { _Pragma("unroll") for (int m = 0; m < 4; ++m) _Pragma("unroll") for (int k = 0; k < 2; ++k) dst[m][k] = *(const PG8_LAS bf16x8*)(lds + PG8_SA(b, h) + aoff + m * 2048 + k * 1024); } while (0)
; #define PG8_MMA(ai, bj, At, Bt) do { __builtin_amdgcn_s_setprio(1); _Pragma("unroll") for (int m = 0; m < 4; ++m) _Pragma("unroll") for (int n = 0; n < 2; ++n) _Pragma("unroll") for (int k = 0; k < 2; ++k) \
;         acc[ai][bj][m][n] = __builtin_amdgcn_mfma_f32_16x16x32_bf16(Bt[n][k], At[m][k], acc[ai][bj][m][n], 0, 0, 0); __builtin_amdgcn_s_setprio(0); } while (0)
; #define PG8_WAIT_V(n) asm volatile("s_waitcnt vmcnt(" #n ")" ::: "memory")
; #define PG8_WAIT_L(n) asm volatile("s_waitcnt lgkmcnt(" #n ")" ::: "memory")
; #define PG8_BAR __builtin_amdgcn_s_barrier()
; #define PG8_SCHED __builtin_amdgcn_sched_barrier(0)
; template <class Epi, class Sched, bool ALIGN_EPI = false, bool SP2 = false>
; __device__ __forceinline__ void gemm_phase(PG8_LAS unsigned char* lds, const Gemm g, const Sched& S, const Epi& E) {
;     ...
;         for (int t = 0; t < nt; t += 2) {
;     ...
;             PG8_LDA(At, 1, 1); PG8_STAGE(PG8_SB(1, 0), b3, voffB); PG8_STAGE(PG8_SB(1, 1), b3 + hstep, voffB); PG8_STAGE(PG8_SA(1, 0), a3, voffA);
;             PG8_WAIT_V(8); PG8_WAIT_L(0); PG8_BAR; PG8_MMA(1, 0, At, B0); PG8_MMA(1, 1, At, B1); PG8_BAR; PG8_SCHED;
	s_mov_b32 m0, s48
	v_lshl_add_u64 v[214:215], v[214:215], 0, s[16:17]
	s_add_u32 s44, s52, 0xb0080
	ds_read_b128 v[182:185], v146 offset:49152
	ds_read_b128 v[186:189], v146 offset:50176
	ds_read_b128 v[190:193], v146 offset:51200
	ds_read_b128 v[194:197], v146 offset:52224
	ds_read_b128 v[198:201], v146 offset:53248
	ds_read_b128 v[202:205], v146 offset:54272
	ds_read_b128 v[206:209], v146 offset:55296
	ds_read_b128 v[210:213], v146 offset:56320
	global_load_lds_dwordx4 v[214:215], off
	v_lshl_add_u64 v[214:215], v[216:217], 0, s[16:17]
	s_mov_b32 m0, s49
	s_addc_u32 s45, s53, 0
	global_load_lds_dwordx4 v[214:215], off
	v_lshl_add_u64 v[214:215], s[44:45], 0, v[130:131]
	s_mov_b32 m0, s83
	s_nop 0
	global_load_lds_dwordx4 v[214:215], off
	v_lshl_add_u64 v[214:215], s[44:45], 0, v[136:137]
	s_mov_b32 m0, s84
	s_nop 0
	global_load_lds_dwordx4 v[214:215], off
	v_lshl_add_u64 v[214:215], v[218:219], 0, s[16:17]
	s_mov_b32 m0, s50
	s_nop 0
	global_load_lds_dwordx4 v[214:215], off
	v_lshl_add_u64 v[214:215], v[220:221], 0, s[16:17]
	s_mov_b32 m0, s51
	s_nop 0
	global_load_lds_dwordx4 v[214:215], off
	s_waitcnt vmcnt(8)
	s_waitcnt lgkmcnt(0)
	s_barrier
	s_setprio 1
	s_waitcnt lgkmcnt(0)
	v_mfma_f32_16x16x32_bf16 v[62:65], v[150:153], v[182:185], v[62:65]
	v_mfma_f32_16x16x32_bf16 v[58:61], v[158:161], v[182:185], v[58:61]
	v_mfma_f32_16x16x32_bf16 v[54:57], v[150:153], v[190:193], v[54:57]
	v_mfma_f32_16x16x32_bf16 v[50:53], v[158:161], v[190:193], v[50:53]
	v_mfma_f32_16x16x32_bf16 v[38:41], v[150:153], v[198:201], v[38:41]
	v_mfma_f32_16x16x32_bf16 v[34:37], v[158:161], v[198:201], v[34:37]
	v_mfma_f32_16x16x32_bf16 v[22:25], v[150:153], v[206:209], v[22:25]
	v_mfma_f32_16x16x32_bf16 v[18:21], v[158:161], v[206:209], v[18:21]
	v_mfma_f32_16x16x32_bf16 v[62:65], v[154:157], v[186:189], v[62:65]
	v_mfma_f32_16x16x32_bf16 v[58:61], v[162:165], v[186:189], v[58:61]
	v_mfma_f32_16x16x32_bf16 v[54:57], v[154:157], v[194:197], v[54:57]
	v_mfma_f32_16x16x32_bf16 v[50:53], v[162:165], v[194:197], v[50:53]
	v_mfma_f32_16x16x32_bf16 v[38:41], v[154:157], v[202:205], v[38:41]
	v_mfma_f32_16x16x32_bf16 v[34:37], v[162:165], v[202:205], v[34:37]
	v_mfma_f32_16x16x32_bf16 v[22:25], v[154:157], v[210:213], v[22:25]
	v_mfma_f32_16x16x32_bf16 v[18:21], v[162:165], v[210:213], v[18:21]
	s_setprio 0
	s_setprio 1
	v_mfma_f32_16x16x32_bf16 v[46:49], v[166:169], v[182:185], v[46:49]
	v_mfma_f32_16x16x32_bf16 v[42:45], v[174:177], v[182:185], v[42:45]
	v_mfma_f32_16x16x32_bf16 v[30:33], v[166:169], v[190:193], v[30:33]
	v_mfma_f32_16x16x32_bf16 v[26:29], v[174:177], v[190:193], v[26:29]
	v_mfma_f32_16x16x32_bf16 v[14:17], v[166:169], v[198:201], v[14:17]
	v_mfma_f32_16x16x32_bf16 v[10:13], v[174:177], v[198:201], v[10:13]
	v_mfma_f32_16x16x32_bf16 v[6:9], v[166:169], v[206:209], v[6:9]
	v_mfma_f32_16x16x32_bf16 v[2:5], v[174:177], v[206:209], v[2:5]
	v_mfma_f32_16x16x32_bf16 v[46:49], v[170:173], v[186:189], v[46:49]
	v_mfma_f32_16x16x32_bf16 v[42:45], v[178:181], v[186:189], v[42:45]
	v_mfma_f32_16x16x32_bf16 v[30:33], v[170:173], v[194:197], v[30:33]
	v_mfma_f32_16x16x32_bf16 v[26:29], v[178:181], v[194:197], v[26:29]
	v_mfma_f32_16x16x32_bf16 v[14:17], v[170:173], v[202:205], v[14:17]
	v_mfma_f32_16x16x32_bf16 v[10:13], v[178:181], v[202:205], v[10:13]
	v_mfma_f32_16x16x32_bf16 v[6:9], v[170:173], v[210:213], v[6:9]
	v_mfma_f32_16x16x32_bf16 v[2:5], v[178:181], v[210:213], v[2:5]
	s_setprio 0
	s_barrier
	s_add_u32 s91, s91, 0x100
	s_addc_u32 s92, s92, 0
	s_cmp_ge_u32 s93, s81
	s_mov_b64 s[44:45], s[46:47]
	s_mov_b32 s52, s93

; #define PG8_STAGE(bufoff, gbase, voff) do { _Pragma("unroll") for (int _i = 0; _i < 2; ++_i) \
;         __builtin_amdgcn_global_load_lds((const unsigned*)((const char*)(gbase) + (voff)[_i]), (PG8_LAS unsigned*)(lds + (bufoff) + ldsw + _i * 8192), 16, 0, 0); } while (0)
; #define PG8_LDA(dst, b, h) do { _Pragma("unroll") for (int m = 0; m < 4; ++m) _Pragma("unroll") for (int k = 0; k < 2; ++k) dst[m][k] = *(const PG8_LAS bf16x8*)(lds + PG8_SA(b, h) + aoff + m * 2048 + k * 1024); } while (0)
; #define PG8_LDB(dst, b, h) do { _Pragma("unroll") for (int n = 0; n < 2; ++n) _Pragma("unroll") for (int k = 0; k < 2; ++k) dst[n][k] = *(const PG8_LAS bf16x8*)(lds + PG8_SB(b, h) + boff + n * 2048 + k * 1024); } while (0)
; #define PG8_MMA(ai, bj, At, Bt) do { __builtin_amdgcn_s_setprio(1); _Pragma("unroll") for (int m = 0; m < 4; ++m) _Pragma("unroll") for (int n = 0; n < 2; ++n) _Pragma("unroll") for (int k = 0; k < 2; ++k) \
;         acc[ai][bj][m][n] = __builtin_amdgcn_mfma_f32_16x16x32_bf16(Bt[n][k], At[m][k], acc[ai][bj][m][n], 0, 0, 0); __builtin_amdgcn_s_setprio(0); } while (0)
; template <class Epi, class Sched, bool ALIGN_EPI = false, bool SP2 = false>
; __device__ __forceinline__ void gemm_phase(PG8_LAS unsigned char* lds, const Gemm g, const Sched& S, const Epi& E) {
;     ...
;         const bool has_next = S.next(ui + 1, nxt);
;         const char* nA = has_next ? (const char*)g.A + (size_t)nxt.pm * tstep + (size_t)nxt.ks * K * 2 : cA; const char* nB = has_next ? (const char*)g.Bt + (size_t)nxt.pn * tstep + (size_t)nxt.ks * K * 2 : cB;
;         for (int t = 0; t < nt; t += 2) {
;             const bool last = (t == nt - 2);
;             const char* a1 = cA + (size_t)(t + 1) * kstep;
;             const char* a2 = last ? nA : cA + (size_t)(t + 2) * kstep; const char* b2 = last ? nB : cB + (size_t)(t + 2) * kstep;
;             const char* a3 = a2 + kstep; const char* b3 = b2 + kstep;
;             if (last && has_next) S.a_ready(nxt);
;             if constexpr (SP2) {
;             PG8_LDB(B0, 0, 0); PG8_LDB(B1, 0, 1); PG8_SCHED; PG8_LDA(At, 0, 0); PG8_STAGE(PG8_SA(1, 1), a1 + hstep, voffA);
;             PG8_WAIT_V(8); PG8_WAIT_L(0); PG8_BAR; PG8_MMA(0, 0, At, B0); PG8_MMA(0, 1, At, B1); PG8_BAR; PG8_SCHED;
;             PG8_LDA(At, 0, 1); PG8_STAGE(PG8_SB(0, 0), b2, voffB); PG8_STAGE(PG8_SB(0, 1), b2 + hstep, voffB); PG8_STAGE(PG8_SA(0, 0), a2, voffA);
.LBB0_1582:
	s_ashr_i32 s73, s72, 31
	s_lshl_b64 s[12:13], s[72:73], 19
	s_add_u32 s74, s87, s12
	s_addc_u32 s75, s88, s13
	s_and_b64 s[12:13], s[4:5], exec
	s_cselect_b32 s7, s75, s11
	s_cselect_b32 s14, s74, s10
	s_ashr_i32 s71, s70, 31
	s_lshl_b64 s[12:13], s[70:71], 19
	s_add_u32 s76, s89, s12
	s_addc_u32 s77, s90, s13
	s_and_b64 s[12:13], s[4:5], exec
	s_cselect_b32 s15, s77, s9
	s_cselect_b32 s16, s76, s8
	s_add_u32 s17, s8, 0x100
	s_addc_u32 s18, s9, 0
	s_add_u32 s8, s10, 0x40080
	s_addc_u32 s9, s11, 0
	s_mov_b32 s19, -2
	ds_read_b128 v[130:133], v171
	ds_read_b128 v[134:137], v171 offset:1024
	ds_read_b128 v[156:159], v171 offset:2048
	ds_read_b128 v[160:163], v171 offset:3072
	ds_read_b128 v[164:167], v172
	ds_read_b128 v[178:181], v172 offset:1024
	ds_read_b128 v[182:185], v172 offset:2048
	ds_read_b128 v[186:189], v172 offset:3072
	s_add_u32 s10, s8, 0xfffc0080
	s_addc_u32 s11, s9, -1
	s_cmp_eq_u32 s19, 12
	s_cselect_b32 s13, s7, s11
	s_cselect_b32 s12, s14, s10
	s_cselect_b32 s11, s15, s18
	s_cselect_b32 s10, s16, s17
	v_lshl_add_u64 v[222:223], s[8:9], 0, v[150:151]
	s_add_i32 m0, s95, 0xc000
	ds_read_b128 v[190:193], v173
	ds_read_b128 v[194:197], v173 offset:1024
	ds_read_b128 v[198:201], v173 offset:2048
	ds_read_b128 v[202:205], v173 offset:3072
	ds_read_b128 v[206:209], v173 offset:4096
	ds_read_b128 v[210:213], v173 offset:5120
	ds_read_b128 v[214:217], v173 offset:6144
	ds_read_b128 v[218:221], v173 offset:7168
	global_load_lds_dwordx4 v[222:223], off
	v_lshl_add_u64 v[222:223], s[8:9], 0, v[148:149]
	s_add_i32 m0, s95, 0xe000
	s_nop 0
	global_load_lds_dwordx4 v[222:223], off
	s_waitcnt vmcnt(8)
	s_waitcnt lgkmcnt(0)
	s_barrier
	s_setprio 1
	s_waitcnt lgkmcnt(0)
	v_mfma_f32_16x16x32_bf16 v[126:129], v[130:133], v[190:193], 0
	v_mfma_f32_16x16x32_bf16 v[122:125], v[156:159], v[190:193], 0
	v_mfma_f32_16x16x32_bf16 v[110:113], v[130:133], v[198:201], 0
	v_mfma_f32_16x16x32_bf16 v[106:109], v[156:159], v[198:201], 0
	v_mfma_f32_16x16x32_bf16 v[94:97], v[130:133], v[206:209], 0
	v_mfma_f32_16x16x32_bf16 v[90:93], v[156:159], v[206:209], 0
	v_mfma_f32_16x16x32_bf16 v[78:81], v[130:133], v[214:217], 0
	v_mfma_f32_16x16x32_bf16 v[74:77], v[156:159], v[214:217], 0
	v_mfma_f32_16x16x32_bf16 v[126:129], v[134:137], v[194:197], v[126:129]
	v_mfma_f32_16x16x32_bf16 v[122:125], v[160:163], v[194:197], v[122:125]
	v_mfma_f32_16x16x32_bf16 v[110:113], v[134:137], v[202:205], v[110:113]
	v_mfma_f32_16x16x32_bf16 v[106:109], v[160:163], v[202:205], v[106:109]
	v_mfma_f32_16x16x32_bf16 v[94:97], v[134:137], v[210:213], v[94:97]
	v_mfma_f32_16x16x32_bf16 v[90:93], v[160:163], v[210:213], v[90:93]
	v_mfma_f32_16x16x32_bf16 v[78:81], v[134:137], v[218:221], v[78:81]
	v_mfma_f32_16x16x32_bf16 v[74:77], v[160:163], v[218:221], v[74:77]
	s_setprio 0
	s_setprio 1
	v_mfma_f32_16x16x32_bf16 v[118:121], v[164:167], v[190:193], 0
	v_mfma_f32_16x16x32_bf16 v[114:117], v[182:185], v[190:193], 0
	v_mfma_f32_16x16x32_bf16 v[102:105], v[164:167], v[198:201], 0
	v_mfma_f32_16x16x32_bf16 v[98:101], v[182:185], v[198:201], 0
	v_mfma_f32_16x16x32_bf16 v[86:89], v[164:167], v[206:209], 0
	v_mfma_f32_16x16x32_bf16 v[82:85], v[182:185], v[206:209], 0
	v_mfma_f32_16x16x32_bf16 v[70:73], v[164:167], v[214:217], 0
	v_mfma_f32_16x16x32_bf16 v[66:69], v[182:185], v[214:217], 0
	v_mfma_f32_16x16x32_bf16 v[118:121], v[178:181], v[194:197], v[118:121]
	v_mfma_f32_16x16x32_bf16 v[114:117], v[186:189], v[194:197], v[114:117]
	v_mfma_f32_16x16x32_bf16 v[102:105], v[178:181], v[202:205], v[102:105]
	v_mfma_f32_16x16x32_bf16 v[98:101], v[186:189], v[202:205], v[98:101]
	v_mfma_f32_16x16x32_bf16 v[86:89], v[178:181], v[210:213], v[86:89]
	v_mfma_f32_16x16x32_bf16 v[82:85], v[186:189], v[210:213], v[82:85]
	v_mfma_f32_16x16x32_bf16 v[70:73], v[178:181], v[218:221], v[70:73]
	v_mfma_f32_16x16x32_bf16 v[66:69], v[186:189], v[218:221], v[66:69]
	s_setprio 0
	s_barrier
	s_mov_b32 m0, s91
	v_lshl_add_u64 v[222:223], s[10:11], 0, v[138:139]
	s_add_u32 s20, s10, 0x40000
	ds_read_b128 v[190:193], v173 offset:16384
	ds_read_b128 v[194:197], v173 offset:17408
	ds_read_b128 v[198:201], v173 offset:18432
	ds_read_b128 v[202:205], v173 offset:19456
	ds_read_b128 v[206:209], v173 offset:20480
	ds_read_b128 v[210:213], v173 offset:21504
	ds_read_b128 v[214:217], v173 offset:22528
	ds_read_b128 v[218:221], v173 offset:23552
	global_load_lds_dwordx4 v[222:223], off
	v_lshl_add_u64 v[224:225], s[10:11], 0, v[140:141]
	s_mov_b32 m0, s92
	s_addc_u32 s21, s11, 0
	global_load_lds_dwordx4 v[224:225], off
	v_lshl_add_u64 v[226:227], s[20:21], 0, v[138:139]
	s_mov_b32 m0, s93
	v_lshl_add_u64 v[228:229], s[12:13], 0, v[140:141]
	global_load_lds_dwordx4 v[226:227], off
	v_lshl_add_u64 v[226:227], s[20:21], 0, v[140:141]
	s_mov_b32 m0, s94
	s_nop 0
	global_load_lds_dwordx4 v[226:227], off
	v_lshl_add_u64 v[226:227], s[12:13], 0, v[138:139]
	s_mov_b32 m0, s95
	s_nop 0
	global_load_lds_dwordx4 v[226:227], off
	s_mov_b32 m0, s96
	s_nop 0
	global_load_lds_dwordx4 v[228:229], off
	s_waitcnt vmcnt(8)
	s_waitcnt lgkmcnt(0)
	s_barrier
; #define PG8_STAGE(bufoff, gbase, voff) do { _Pragma("unroll") for (int _i = 0; _i < 2; ++_i) \
;         __builtin_amdgcn_global_load_lds((const unsigned*)((const char*)(gbase) + (voff)[_i]), (PG8_LAS unsigned*)(lds + (bufoff) + ldsw + _i * 8192), 16, 0, 0); } while (0)
; #define PG8_LDA(dst, b, h) do { _Pragma("unroll") for (int m = 0; m < 4; ++m) _Pragma("unroll") for (int k = 0; k < 2; ++k) dst[m][k] = *(const PG8_LAS bf16x8*)(lds + PG8_SA(b, h) + aoff + m * 2048 + k * 1024); } while (0)
; #define PG8_LDB(dst, b, h) do { _Pragma("unroll") for (int n = 0; n < 2; ++n) _Pragma("unroll") for (int k = 0; k < 2; ++k) dst[n][k] = *(const PG8_LAS bf16x8*)(lds + PG8_SB(b, h) + boff + n * 2048 + k * 1024); } while (0)
; #define PG8_MMA(ai, bj, At, Bt) do { __builtin_amdgcn_s_setprio(1); _Pragma("unroll") for (int m = 0; m < 4; ++m) _Pragma("unroll") for (int n = 0; n < 2; ++n) _Pragma("unroll") for (int k = 0; k < 2; ++k) \
;         acc[ai][bj][m][n] = __builtin_amdgcn_mfma_f32_16x16x32_bf16(Bt[n][k], At[m][k], acc[ai][bj][m][n], 0, 0, 0); __builtin_amdgcn_s_setprio(0); } while (0)
; #define PG8_WAIT_V(n) asm volatile("s_waitcnt vmcnt(" #n ")" ::: "memory")
; #define PG8_WAIT_L(n) asm volatile("s_waitcnt lgkmcnt(" #n ")" ::: "memory")
; #define PG8_BAR __builtin_amdgcn_s_barrier()
; #define PG8_SCHED __builtin_amdgcn_sched_barrier(0)
; template <class Epi, class Sched, bool ALIGN_EPI = false, bool SP2 = false>
; __device__ __forceinline__ void gemm_phase(PG8_LAS unsigned char* lds, const Gemm g, const Sched& S, const Epi& E) {
;     ...
;             PG8_WAIT_V(8); PG8_WAIT_L(0); PG8_BAR; PG8_MMA(1, 0, At, B0); PG8_MMA(1, 1, At, B1); PG8_BAR; PG8_SCHED;
;             PG8_LDB(B0, 1, 0); PG8_LDB(B1, 1, 1); PG8_SCHED; PG8_LDA(At, 1, 0); PG8_STAGE(PG8_SA(0, 1), a2 + hstep, voffA);
;             PG8_WAIT_V(8); PG8_WAIT_L(0); PG8_BAR; PG8_MMA(0, 0, At, B0); PG8_MMA(0, 1, At, B1); PG8_BAR; PG8_SCHED;
	s_setprio 1
	s_waitcnt lgkmcnt(0)
	v_mfma_f32_16x16x32_bf16 v[62:65], v[130:133], v[190:193], 0
	v_mfma_f32_16x16x32_bf16 v[58:61], v[156:159], v[190:193], 0
	v_mfma_f32_16x16x32_bf16 v[46:49], v[130:133], v[198:201], 0
	v_mfma_f32_16x16x32_bf16 v[42:45], v[156:159], v[198:201], 0
	v_mfma_f32_16x16x32_bf16 v[30:33], v[130:133], v[206:209], 0
	v_mfma_f32_16x16x32_bf16 v[26:29], v[156:159], v[206:209], 0
	v_mfma_f32_16x16x32_bf16 v[14:17], v[130:133], v[214:217], 0
	v_mfma_f32_16x16x32_bf16 v[10:13], v[156:159], v[214:217], 0
	v_mfma_f32_16x16x32_bf16 v[62:65], v[134:137], v[194:197], v[62:65]
	v_mfma_f32_16x16x32_bf16 v[58:61], v[160:163], v[194:197], v[58:61]
	v_mfma_f32_16x16x32_bf16 v[46:49], v[134:137], v[202:205], v[46:49]
	v_mfma_f32_16x16x32_bf16 v[42:45], v[160:163], v[202:205], v[42:45]
	v_mfma_f32_16x16x32_bf16 v[30:33], v[134:137], v[210:213], v[30:33]
	v_mfma_f32_16x16x32_bf16 v[26:29], v[160:163], v[210:213], v[26:29]
	v_mfma_f32_16x16x32_bf16 v[14:17], v[134:137], v[218:221], v[14:17]
	v_mfma_f32_16x16x32_bf16 v[10:13], v[160:163], v[218:221], v[10:13]
	s_setprio 0
	s_setprio 1
	v_mfma_f32_16x16x32_bf16 v[54:57], v[164:167], v[190:193], 0
	v_mfma_f32_16x16x32_bf16 v[50:53], v[182:185], v[190:193], 0
	v_mfma_f32_16x16x32_bf16 v[38:41], v[164:167], v[198:201], 0
	v_mfma_f32_16x16x32_bf16 v[34:37], v[182:185], v[198:201], 0
	v_mfma_f32_16x16x32_bf16 v[22:25], v[164:167], v[206:209], 0
	v_mfma_f32_16x16x32_bf16 v[18:21], v[182:185], v[206:209], 0
	v_mfma_f32_16x16x32_bf16 v[6:9], v[164:167], v[214:217], 0
	v_mfma_f32_16x16x32_bf16 v[2:5], v[182:185], v[214:217], 0
	v_mfma_f32_16x16x32_bf16 v[54:57], v[178:181], v[194:197], v[54:57]
	v_mfma_f32_16x16x32_bf16 v[50:53], v[186:189], v[194:197], v[50:53]
	v_mfma_f32_16x16x32_bf16 v[38:41], v[178:181], v[202:205], v[38:41]
	v_mfma_f32_16x16x32_bf16 v[34:37], v[186:189], v[202:205], v[34:37]
	v_mfma_f32_16x16x32_bf16 v[22:25], v[178:181], v[210:213], v[22:25]
	v_mfma_f32_16x16x32_bf16 v[18:21], v[186:189], v[210:213], v[18:21]
	v_mfma_f32_16x16x32_bf16 v[6:9], v[178:181], v[218:221], v[6:9]
	v_mfma_f32_16x16x32_bf16 v[2:5], v[186:189], v[218:221], v[2:5]
	s_setprio 0
	s_barrier
	ds_read_b128 v[130:133], v174
	ds_read_b128 v[134:137], v174 offset:1024
	ds_read_b128 v[156:159], v174 offset:2048
	ds_read_b128 v[160:163], v174 offset:3072
	ds_read_b128 v[164:167], v175
	ds_read_b128 v[178:181], v175 offset:1024
	ds_read_b128 v[182:185], v175 offset:2048
	ds_read_b128 v[186:189], v175 offset:3072
	s_add_u32 s12, s12, 0x40000
	s_addc_u32 s13, s13, 0
	s_mov_b32 m0, s97
	v_lshl_add_u64 v[230:231], s[12:13], 0, v[138:139]
	ds_read_b128 v[190:193], v173 offset:32768
	ds_read_b128 v[194:197], v173 offset:33792
	ds_read_b128 v[198:201], v173 offset:34816
	ds_read_b128 v[202:205], v173 offset:35840
	ds_read_b128 v[206:209], v173 offset:36864
	ds_read_b128 v[210:213], v173 offset:37888
	ds_read_b128 v[214:217], v173 offset:38912
	ds_read_b128 v[218:221], v173 offset:39936
	global_load_lds_dwordx4 v[230:231], off
	v_lshl_add_u64 v[230:231], s[12:13], 0, v[140:141]
	s_mov_b32 m0, s30
	s_nop 0
	global_load_lds_dwordx4 v[230:231], off
	s_waitcnt vmcnt(8)
	s_waitcnt lgkmcnt(0)
	s_barrier
	s_setprio 1
	s_waitcnt lgkmcnt(0)
	v_mfma_f32_16x16x32_bf16 v[126:129], v[130:133], v[190:193], v[126:129]
	v_mfma_f32_16x16x32_bf16 v[122:125], v[156:159], v[190:193], v[122:125]
	v_mfma_f32_16x16x32_bf16 v[110:113], v[130:133], v[198:201], v[110:113]
	v_mfma_f32_16x16x32_bf16 v[106:109], v[156:159], v[198:201], v[106:109]
	v_mfma_f32_16x16x32_bf16 v[94:97], v[130:133], v[206:209], v[94:97]
	v_mfma_f32_16x16x32_bf16 v[90:93], v[156:159], v[206:209], v[90:93]
	v_mfma_f32_16x16x32_bf16 v[78:81], v[130:133], v[214:217], v[78:81]
	v_mfma_f32_16x16x32_bf16 v[74:77], v[156:159], v[214:217], v[74:77]
	v_mfma_f32_16x16x32_bf16 v[126:129], v[134:137], v[194:197], v[126:129]
	v_mfma_f32_16x16x32_bf16 v[122:125], v[160:163], v[194:197], v[122:125]
	v_mfma_f32_16x16x32_bf16 v[110:113], v[134:137], v[202:205], v[110:113]
	v_mfma_f32_16x16x32_bf16 v[106:109], v[160:163], v[202:205], v[106:109]
	v_mfma_f32_16x16x32_bf16 v[94:97], v[134:137], v[210:213], v[94:97]
	v_mfma_f32_16x16x32_bf16 v[90:93], v[160:163], v[210:213], v[90:93]
	v_mfma_f32_16x16x32_bf16 v[78:81], v[134:137], v[218:221], v[78:81]
	v_mfma_f32_16x16x32_bf16 v[74:77], v[160:163], v[218:221], v[74:77]
	s_setprio 0
	s_setprio 1
	v_mfma_f32_16x16x32_bf16 v[118:121], v[164:167], v[190:193], v[118:121]
	v_mfma_f32_16x16x32_bf16 v[114:117], v[182:185], v[190:193], v[114:117]
	v_mfma_f32_16x16x32_bf16 v[102:105], v[164:167], v[198:201], v[102:105]
	v_mfma_f32_16x16x32_bf16 v[98:101], v[182:185], v[198:201], v[98:101]
	v_mfma_f32_16x16x32_bf16 v[86:89], v[164:167], v[206:209], v[86:89]
	v_mfma_f32_16x16x32_bf16 v[82:85], v[182:185], v[206:209], v[82:85]
	v_mfma_f32_16x16x32_bf16 v[70:73], v[164:167], v[214:217], v[70:73]
	v_mfma_f32_16x16x32_bf16 v[66:69], v[182:185], v[214:217], v[66:69]
	v_mfma_f32_16x16x32_bf16 v[118:121], v[178:181], v[194:197], v[118:121]
	v_mfma_f32_16x16x32_bf16 v[114:117], v[186:189], v[194:197], v[114:117]
	v_mfma_f32_16x16x32_bf16 v[102:105], v[178:181], v[202:205], v[102:105]
	v_mfma_f32_16x16x32_bf16 v[98:101], v[186:189], v[202:205], v[98:101]
	v_mfma_f32_16x16x32_bf16 v[86:89], v[178:181], v[210:213], v[86:89]
	v_mfma_f32_16x16x32_bf16 v[82:85], v[186:189], v[210:213], v[82:85]
	v_mfma_f32_16x16x32_bf16 v[70:73], v[178:181], v[218:221], v[70:73]
	v_mfma_f32_16x16x32_bf16 v[66:69], v[186:189], v[218:221], v[66:69]
	s_setprio 0
	s_barrier
; #define PG8_STAGE(bufoff, gbase, voff) do { _Pragma("unroll") for (int _i = 0; _i < 2; ++_i) \
;         __builtin_amdgcn_global_load_lds((const unsigned*)((const char*)(gbase) + (voff)[_i]), (PG8_LAS unsigned*)(lds + (bufoff) + ldsw + _i * 8192), 16, 0, 0); } while (0)
; #define PG8_LDA(dst, b, h) do { _Pragma("unroll") for (int m = 0; m < 4; ++m) _Pragma("unroll") for (int k = 0; k < 2; ++k) dst[m][k] = *(const PG8_LAS bf16x8*)(lds + PG8_SA(b, h) + aoff + m * 2048 + k * 1024); } while (0)
; #define PG8_MMA(ai, bj, At, Bt) do { __builtin_amdgcn_s_setprio(1); _Pragma("unroll") for (int m = 0; m < 4; ++m) _Pragma("unroll") for (int n = 0; n < 2; ++n) _Pragma("unroll") for (int k = 0; k < 2; ++k) \
;         acc[ai][bj][m][n] = __builtin_amdgcn_mfma_f32_16x16x32_bf16(Bt[n][k], At[m][k], acc[ai][bj][m][n], 0, 0, 0); __builtin_amdgcn_s_setprio(0); } while (0)
; #define PG8_WAIT_V(n) asm volatile("s_waitcnt vmcnt(" #n ")" ::: "memory")
; #define PG8_WAIT_L(n) asm volatile("s_waitcnt lgkmcnt(" #n ")" ::: "memory")
; #define PG8_BAR __builtin_amdgcn_s_barrier()
; #define PG8_SCHED __builtin_amdgcn_sched_barrier(0)
; template <class Epi, class Sched, bool ALIGN_EPI = false, bool SP2 = false>
; __device__ __forceinline__ void gemm_phase(PG8_LAS unsigned char* lds, const Gemm g, const Sched& S, const Epi& E) {
;     ...
;             PG8_LDA(At, 1, 1); PG8_STAGE(PG8_SB(1, 0), b3, voffB); PG8_STAGE(PG8_SB(1, 1), b3 + hstep, voffB); PG8_STAGE(PG8_SA(1, 0), a3, voffA);
;             PG8_WAIT_V(8); PG8_WAIT_L(0); PG8_BAR; PG8_MMA(1, 0, At, B0); PG8_MMA(1, 1, At, B1); PG8_BAR; PG8_SCHED;
	s_mov_b32 m0, s63
	v_lshl_add_u64 v[222:223], v[222:223], 0, s[56:57]
	s_add_u32 s10, s10, 0x40080
	ds_read_b128 v[190:193], v173 offset:49152
	ds_read_b128 v[194:197], v173 offset:50176
	ds_read_b128 v[198:201], v173 offset:51200
	ds_read_b128 v[202:205], v173 offset:52224
	ds_read_b128 v[206:209], v173 offset:53248
	ds_read_b128 v[210:213], v173 offset:54272
	ds_read_b128 v[214:217], v173 offset:55296
	ds_read_b128 v[218:221], v173 offset:56320
	global_load_lds_dwordx4 v[222:223], off
	v_lshl_add_u64 v[222:223], v[224:225], 0, s[56:57]
	s_mov_b32 m0, s64
	s_addc_u32 s11, s11, 0
	global_load_lds_dwordx4 v[222:223], off
	v_lshl_add_u64 v[222:223], s[10:11], 0, v[138:139]
	s_mov_b32 m0, s67
	s_nop 0
	global_load_lds_dwordx4 v[222:223], off
	v_lshl_add_u64 v[222:223], s[10:11], 0, v[140:141]
	s_mov_b32 m0, s26
	s_nop 0
	global_load_lds_dwordx4 v[222:223], off
	v_lshl_add_u64 v[222:223], v[226:227], 0, s[56:57]
	s_mov_b32 m0, s65
	s_nop 0
	global_load_lds_dwordx4 v[222:223], off
	v_lshl_add_u64 v[222:223], v[228:229], 0, s[56:57]
	s_mov_b32 m0, s66
	s_nop 0
	global_load_lds_dwordx4 v[222:223], off
	s_waitcnt vmcnt(8)
	s_waitcnt lgkmcnt(0)
	s_barrier
	s_setprio 1
	s_waitcnt lgkmcnt(0)
	v_mfma_f32_16x16x32_bf16 v[62:65], v[130:133], v[190:193], v[62:65]
	v_mfma_f32_16x16x32_bf16 v[58:61], v[156:159], v[190:193], v[58:61]
	v_mfma_f32_16x16x32_bf16 v[46:49], v[130:133], v[198:201], v[46:49]
	v_mfma_f32_16x16x32_bf16 v[42:45], v[156:159], v[198:201], v[42:45]
	v_mfma_f32_16x16x32_bf16 v[30:33], v[130:133], v[206:209], v[30:33]
	v_mfma_f32_16x16x32_bf16 v[26:29], v[156:159], v[206:209], v[26:29]
	v_mfma_f32_16x16x32_bf16 v[14:17], v[130:133], v[214:217], v[14:17]
	v_mfma_f32_16x16x32_bf16 v[10:13], v[156:159], v[214:217], v[10:13]
	v_mfma_f32_16x16x32_bf16 v[62:65], v[134:137], v[194:197], v[62:65]
	v_mfma_f32_16x16x32_bf16 v[58:61], v[160:163], v[194:197], v[58:61]
	v_mfma_f32_16x16x32_bf16 v[46:49], v[134:137], v[202:205], v[46:49]
	v_mfma_f32_16x16x32_bf16 v[42:45], v[160:163], v[202:205], v[42:45]
	v_mfma_f32_16x16x32_bf16 v[30:33], v[134:137], v[210:213], v[30:33]
	v_mfma_f32_16x16x32_bf16 v[26:29], v[160:163], v[210:213], v[26:29]
	v_mfma_f32_16x16x32_bf16 v[14:17], v[134:137], v[218:221], v[14:17]
	v_mfma_f32_16x16x32_bf16 v[10:13], v[160:163], v[218:221], v[10:13]
	s_setprio 0
	s_setprio 1
	v_mfma_f32_16x16x32_bf16 v[54:57], v[164:167], v[190:193], v[54:57]
	v_mfma_f32_16x16x32_bf16 v[50:53], v[182:185], v[190:193], v[50:53]
	v_mfma_f32_16x16x32_bf16 v[38:41], v[164:167], v[198:201], v[38:41]
	v_mfma_f32_16x16x32_bf16 v[34:37], v[182:185], v[198:201], v[34:37]
	v_mfma_f32_16x16x32_bf16 v[22:25], v[164:167], v[206:209], v[22:25]
	v_mfma_f32_16x16x32_bf16 v[18:21], v[182:185], v[206:209], v[18:21]
	v_mfma_f32_16x16x32_bf16 v[6:9], v[164:167], v[214:217], v[6:9]
	v_mfma_f32_16x16x32_bf16 v[2:5], v[182:185], v[214:217], v[2:5]
	v_mfma_f32_16x16x32_bf16 v[54:57], v[178:181], v[194:197], v[54:57]
	v_mfma_f32_16x16x32_bf16 v[50:53], v[186:189], v[194:197], v[50:53]
	v_mfma_f32_16x16x32_bf16 v[38:41], v[178:181], v[202:205], v[38:41]
	v_mfma_f32_16x16x32_bf16 v[34:37], v[186:189], v[202:205], v[34:37]
	v_mfma_f32_16x16x32_bf16 v[22:25], v[178:181], v[210:213], v[22:25]
	v_mfma_f32_16x16x32_bf16 v[18:21], v[186:189], v[210:213], v[18:21]
	v_mfma_f32_16x16x32_bf16 v[6:9], v[178:181], v[218:221], v[6:9]
	v_mfma_f32_16x16x32_bf16 v[2:5], v[186:189], v[218:221], v[2:5]
	s_setprio 0
	s_barrier
	s_add_i32 s19, s19, 2
	s_add_u32 s17, s17, 0x100
	s_addc_u32 s18, s18, 0
	s_add_u32 s8, s8, 0x100
	s_addc_u32 s9, s9, 0
	s_cmp_gt_u32 s19, 13

; #define PG8_STAGE(bufoff, gbase, voff) do { _Pragma("unroll") for (int _i = 0; _i < 2; ++_i) \
;         __builtin_amdgcn_global_load_lds((const unsigned*)((const char*)(gbase) + (voff)[_i]), (PG8_LAS unsigned*)(lds + (bufoff) + ldsw + _i * 8192), 16, 0, 0); } while (0)
; #define PG8_LDA(dst, b, h) do { _Pragma("unroll") for (int m = 0; m < 4; ++m) _Pragma("unroll") for (int k = 0; k < 2; ++k) dst[m][k] = *(const PG8_LAS bf16x8*)(lds + PG8_SA(b, h) + aoff + m * 2048 + k * 1024); } while (0)
; #define PG8_LDB(dst, b, h) do { _Pragma("unroll") for (int n = 0; n < 2; ++n) _Pragma("unroll") for (int k = 0; k < 2; ++k) dst[n][k] = *(const PG8_LAS bf16x8*)(lds + PG8_SB(b, h) + boff + n * 2048 + k * 1024); } while (0)
; #define PG8_MMA(ai, bj, At, Bt) do { __builtin_amdgcn_s_setprio(1); _Pragma("unroll") for (int m = 0; m < 4; ++m) _Pragma("unroll") for (int n = 0; n < 2; ++n) _Pragma("unroll") for (int k = 0; k < 2; ++k) \
;         acc[ai][bj][m][n] = __builtin_amdgcn_mfma_f32_16x16x32_bf16(Bt[n][k], At[m][k], acc[ai][bj][m][n], 0, 0, 0); __builtin_amdgcn_s_setprio(0); } while (0)
; template <class Epi, class Sched, bool ALIGN_EPI = false, bool SP2 = false>
; __device__ __forceinline__ void gemm_phase(PG8_LAS unsigned char* lds, const Gemm g, const Sched& S, const Epi& E) {
;     ...
;         const bool has_next = S.next(ui + 1, nxt);
;         const char* nA = has_next ? (const char*)g.A + (size_t)nxt.pm * tstep + (size_t)nxt.ks * K * 2 : cA; const char* nB = has_next ? (const char*)g.Bt + (size_t)nxt.pn * tstep + (size_t)nxt.ks * K * 2 : cB;
;         for (int t = 0; t < nt; t += 2) {
;             const bool last = (t == nt - 2);
;             const char* a1 = cA + (size_t)(t + 1) * kstep;
;             const char* a2 = last ? nA : cA + (size_t)(t + 2) * kstep; const char* b2 = last ? nB : cB + (size_t)(t + 2) * kstep;
;             const char* a3 = a2 + kstep; const char* b3 = b2 + kstep;
;             if (last && has_next) S.a_ready(nxt);
;             if constexpr (SP2) {
;             PG8_LDB(B0, 0, 0); PG8_LDB(B1, 0, 1); PG8_SCHED; PG8_LDA(At, 0, 0); PG8_STAGE(PG8_SA(1, 1), a1 + hstep, voffA);
;             PG8_WAIT_V(8); PG8_WAIT_L(0); PG8_BAR; PG8_MMA(0, 0, At, B0); PG8_MMA(0, 1, At, B1); PG8_BAR; PG8_SCHED;
;             PG8_LDA(At, 0, 1); PG8_STAGE(PG8_SB(0, 0), b2, voffB); PG8_STAGE(PG8_SB(0, 1), b2 + hstep, voffB); PG8_STAGE(PG8_SA(0, 0), a2, voffA);
.LBB0_2133:
	s_ashr_i32 s21, s20, 31
	s_lshl_b64 s[24:25], s[20:21], 19
	s_add_u32 s24, s31, s24
	s_addc_u32 s25, s33, s25
	s_and_b64 s[36:37], s[2:3], exec
	s_cselect_b32 s21, s25, s41
	s_cselect_b32 s64, s24, s40
	s_ashr_i32 s23, s22, 31
	s_lshl_b64 s[36:37], s[22:23], 19
	s_add_u32 s36, s29, s36
	s_addc_u32 s37, s30, s37
	s_and_b64 s[42:43], s[2:3], exec
	s_cselect_b32 s23, s37, s39
	s_cselect_b32 s65, s36, s38
	s_add_u32 s66, s38, 0x100
	s_addc_u32 s67, s39, 0
	s_add_u32 s38, s40, 0x40080
	s_addc_u32 s39, s41, 0
	s_mov_b32 s68, -2
	ds_read_b128 v[154:157], v148
	ds_read_b128 v[158:161], v148 offset:1024
	ds_read_b128 v[162:165], v148 offset:2048
	ds_read_b128 v[166:169], v148 offset:3072
	ds_read_b128 v[170:173], v149
	ds_read_b128 v[174:177], v149 offset:1024
	ds_read_b128 v[178:181], v149 offset:2048
	ds_read_b128 v[182:185], v149 offset:3072
	s_add_u32 s40, s38, 0xfffc0080
	s_addc_u32 s41, s39, -1
	s_cmp_eq_u32 s68, 12
	s_cselect_b32 s43, s21, s41
	s_cselect_b32 s42, s64, s40
	s_cselect_b32 s41, s23, s67
	s_cselect_b32 s40, s65, s66
	v_lshl_add_u64 v[218:219], s[38:39], 0, v[140:141]
	s_add_i32 m0, s47, 0xc000
	ds_read_b128 v[186:189], v150
	ds_read_b128 v[190:193], v150 offset:1024
	ds_read_b128 v[194:197], v150 offset:2048
	ds_read_b128 v[198:201], v150 offset:3072
	ds_read_b128 v[202:205], v150 offset:4096
	ds_read_b128 v[206:209], v150 offset:5120
	ds_read_b128 v[210:213], v150 offset:6144
	ds_read_b128 v[214:217], v150 offset:7168
	global_load_lds_dwordx4 v[218:219], off
	v_lshl_add_u64 v[218:219], s[38:39], 0, v[138:139]
	s_add_i32 m0, s47, 0xe000
	s_nop 0
	global_load_lds_dwordx4 v[218:219], off
	s_waitcnt vmcnt(8)
	s_waitcnt lgkmcnt(0)
	s_barrier
	s_setprio 1
	s_waitcnt lgkmcnt(0)
	v_mfma_f32_16x16x32_bf16 v[126:129], v[154:157], v[186:189], 0
	v_mfma_f32_16x16x32_bf16 v[122:125], v[162:165], v[186:189], 0
	v_mfma_f32_16x16x32_bf16 v[118:121], v[154:157], v[194:197], 0
	v_mfma_f32_16x16x32_bf16 v[114:117], v[162:165], v[194:197], 0
	v_mfma_f32_16x16x32_bf16 v[102:105], v[154:157], v[202:205], 0
	v_mfma_f32_16x16x32_bf16 v[98:101], v[162:165], v[202:205], 0
	v_mfma_f32_16x16x32_bf16 v[86:89], v[154:157], v[210:213], 0
	v_mfma_f32_16x16x32_bf16 v[82:85], v[162:165], v[210:213], 0
	v_mfma_f32_16x16x32_bf16 v[126:129], v[158:161], v[190:193], v[126:129]
	v_mfma_f32_16x16x32_bf16 v[122:125], v[166:169], v[190:193], v[122:125]
	v_mfma_f32_16x16x32_bf16 v[118:121], v[158:161], v[198:201], v[118:121]
	v_mfma_f32_16x16x32_bf16 v[114:117], v[166:169], v[198:201], v[114:117]
	v_mfma_f32_16x16x32_bf16 v[102:105], v[158:161], v[206:209], v[102:105]
	v_mfma_f32_16x16x32_bf16 v[98:101], v[166:169], v[206:209], v[98:101]
	v_mfma_f32_16x16x32_bf16 v[86:89], v[158:161], v[214:217], v[86:89]
	v_mfma_f32_16x16x32_bf16 v[82:85], v[166:169], v[214:217], v[82:85]
	s_setprio 0
	s_setprio 1
	v_mfma_f32_16x16x32_bf16 v[110:113], v[170:173], v[186:189], 0
	v_mfma_f32_16x16x32_bf16 v[106:109], v[178:181], v[186:189], 0
	v_mfma_f32_16x16x32_bf16 v[94:97], v[170:173], v[194:197], 0
	v_mfma_f32_16x16x32_bf16 v[90:93], v[178:181], v[194:197], 0
	v_mfma_f32_16x16x32_bf16 v[78:81], v[170:173], v[202:205], 0
	v_mfma_f32_16x16x32_bf16 v[74:77], v[178:181], v[202:205], 0
	v_mfma_f32_16x16x32_bf16 v[70:73], v[170:173], v[210:213], 0
	v_mfma_f32_16x16x32_bf16 v[66:69], v[178:181], v[210:213], 0
	v_mfma_f32_16x16x32_bf16 v[110:113], v[174:177], v[190:193], v[110:113]
	v_mfma_f32_16x16x32_bf16 v[106:109], v[182:185], v[190:193], v[106:109]
	v_mfma_f32_16x16x32_bf16 v[94:97], v[174:177], v[198:201], v[94:97]
	v_mfma_f32_16x16x32_bf16 v[90:93], v[182:185], v[198:201], v[90:93]
	v_mfma_f32_16x16x32_bf16 v[78:81], v[174:177], v[206:209], v[78:81]
	v_mfma_f32_16x16x32_bf16 v[74:77], v[182:185], v[206:209], v[74:77]
	v_mfma_f32_16x16x32_bf16 v[70:73], v[174:177], v[214:217], v[70:73]
	v_mfma_f32_16x16x32_bf16 v[66:69], v[182:185], v[214:217], v[66:69]
	s_setprio 0
	s_barrier
	s_mov_b32 m0, s19
	v_lshl_add_u64 v[218:219], s[40:41], 0, v[132:133]
	s_add_u32 s70, s40, 0x40000
	ds_read_b128 v[186:189], v150 offset:16384
	ds_read_b128 v[190:193], v150 offset:17408
	ds_read_b128 v[194:197], v150 offset:18432
	ds_read_b128 v[198:201], v150 offset:19456
	ds_read_b128 v[202:205], v150 offset:20480
	ds_read_b128 v[206:209], v150 offset:21504
	ds_read_b128 v[210:213], v150 offset:22528
	ds_read_b128 v[214:217], v150 offset:23552
	global_load_lds_dwordx4 v[218:219], off
	v_lshl_add_u64 v[220:221], s[40:41], 0, v[136:137]
	s_mov_b32 m0, s44
	s_addc_u32 s71, s41, 0
	global_load_lds_dwordx4 v[220:221], off
	v_lshl_add_u64 v[222:223], s[70:71], 0, v[132:133]
	s_mov_b32 m0, s45
	v_lshl_add_u64 v[224:225], s[42:43], 0, v[134:135]
	global_load_lds_dwordx4 v[222:223], off
	v_lshl_add_u64 v[222:223], s[70:71], 0, v[136:137]
	s_mov_b32 m0, s46
	s_nop 0
	global_load_lds_dwordx4 v[222:223], off
	v_lshl_add_u64 v[222:223], s[42:43], 0, v[130:131]
	s_mov_b32 m0, s47
	s_nop 0
	global_load_lds_dwordx4 v[222:223], off
	s_mov_b32 m0, s48
	s_nop 0
	global_load_lds_dwordx4 v[224:225], off
	s_waitcnt vmcnt(8)
	s_waitcnt lgkmcnt(0)
	s_barrier
; #define PG8_STAGE(bufoff, gbase, voff) do { _Pragma("unroll") for (int _i = 0; _i < 2; ++_i) \
;         __builtin_amdgcn_global_load_lds((const unsigned*)((const char*)(gbase) + (voff)[_i]), (PG8_LAS unsigned*)(lds + (bufoff) + ldsw + _i * 8192), 16, 0, 0); } while (0)
; #define PG8_LDA(dst, b, h) do { _Pragma("unroll") for (int m = 0; m < 4; ++m) _Pragma("unroll") for (int k = 0; k < 2; ++k) dst[m][k] = *(const PG8_LAS bf16x8*)(lds + PG8_SA(b, h) + aoff + m * 2048 + k * 1024); } while (0)
; #define PG8_LDB(dst, b, h) do { _Pragma("unroll") for (int n = 0; n < 2; ++n) _Pragma("unroll") for (int k = 0; k < 2; ++k) dst[n][k] = *(const PG8_LAS bf16x8*)(lds + PG8_SB(b, h) + boff + n * 2048 + k * 1024); } while (0)
; #define PG8_MMA(ai, bj, At, Bt) do { __builtin_amdgcn_s_setprio(1); _Pragma("unroll") for (int m = 0; m < 4; ++m) _Pragma("unroll") for (int n = 0; n < 2; ++n) _Pragma("unroll") for (int k = 0; k < 2; ++k) \
;         acc[ai][bj][m][n] = __builtin_amdgcn_mfma_f32_16x16x32_bf16(Bt[n][k], At[m][k], acc[ai][bj][m][n], 0, 0, 0); __builtin_amdgcn_s_setprio(0); } while (0)
; #define PG8_WAIT_V(n) asm volatile("s_waitcnt vmcnt(" #n ")" ::: "memory")
; #define PG8_WAIT_L(n) asm volatile("s_waitcnt lgkmcnt(" #n ")" ::: "memory")
; #define PG8_BAR __builtin_amdgcn_s_barrier()
; #define PG8_SCHED __builtin_amdgcn_sched_barrier(0)
; template <class Epi, class Sched, bool ALIGN_EPI = false, bool SP2 = false>
; __device__ __forceinline__ void gemm_phase(PG8_LAS unsigned char* lds, const Gemm g, const Sched& S, const Epi& E) {
;     ...
;             PG8_WAIT_V(8); PG8_WAIT_L(0); PG8_BAR; PG8_MMA(1, 0, At, B0); PG8_MMA(1, 1, At, B1); PG8_BAR; PG8_SCHED;
;             PG8_LDB(B0, 1, 0); PG8_LDB(B1, 1, 1); PG8_SCHED; PG8_LDA(At, 1, 0); PG8_STAGE(PG8_SA(0, 1), a2 + hstep, voffA);
;             PG8_WAIT_V(8); PG8_WAIT_L(0); PG8_BAR; PG8_MMA(0, 0, At, B0); PG8_MMA(0, 1, At, B1); PG8_BAR; PG8_SCHED;
	s_setprio 1
	s_waitcnt lgkmcnt(0)
	v_mfma_f32_16x16x32_bf16 v[62:65], v[154:157], v[186:189], 0
	v_mfma_f32_16x16x32_bf16 v[58:61], v[162:165], v[186:189], 0
	v_mfma_f32_16x16x32_bf16 v[54:57], v[154:157], v[194:197], 0
	v_mfma_f32_16x16x32_bf16 v[50:53], v[162:165], v[194:197], 0
	v_mfma_f32_16x16x32_bf16 v[38:41], v[154:157], v[202:205], 0
	v_mfma_f32_16x16x32_bf16 v[34:37], v[162:165], v[202:205], 0
	v_mfma_f32_16x16x32_bf16 v[22:25], v[154:157], v[210:213], 0
	v_mfma_f32_16x16x32_bf16 v[18:21], v[162:165], v[210:213], 0
	v_mfma_f32_16x16x32_bf16 v[62:65], v[158:161], v[190:193], v[62:65]
	v_mfma_f32_16x16x32_bf16 v[58:61], v[166:169], v[190:193], v[58:61]
	v_mfma_f32_16x16x32_bf16 v[54:57], v[158:161], v[198:201], v[54:57]
	v_mfma_f32_16x16x32_bf16 v[50:53], v[166:169], v[198:201], v[50:53]
	v_mfma_f32_16x16x32_bf16 v[38:41], v[158:161], v[206:209], v[38:41]
	v_mfma_f32_16x16x32_bf16 v[34:37], v[166:169], v[206:209], v[34:37]
	v_mfma_f32_16x16x32_bf16 v[22:25], v[158:161], v[214:217], v[22:25]
	v_mfma_f32_16x16x32_bf16 v[18:21], v[166:169], v[214:217], v[18:21]
	s_setprio 0
	s_setprio 1
	v_mfma_f32_16x16x32_bf16 v[46:49], v[170:173], v[186:189], 0
	v_mfma_f32_16x16x32_bf16 v[42:45], v[178:181], v[186:189], 0
	v_mfma_f32_16x16x32_bf16 v[30:33], v[170:173], v[194:197], 0
	v_mfma_f32_16x16x32_bf16 v[26:29], v[178:181], v[194:197], 0
	v_mfma_f32_16x16x32_bf16 v[14:17], v[170:173], v[202:205], 0
	v_mfma_f32_16x16x32_bf16 v[10:13], v[178:181], v[202:205], 0
	v_mfma_f32_16x16x32_bf16 v[6:9], v[170:173], v[210:213], 0
	v_mfma_f32_16x16x32_bf16 v[2:5], v[178:181], v[210:213], 0
	v_mfma_f32_16x16x32_bf16 v[46:49], v[174:177], v[190:193], v[46:49]
	v_mfma_f32_16x16x32_bf16 v[42:45], v[182:185], v[190:193], v[42:45]
	v_mfma_f32_16x16x32_bf16 v[30:33], v[174:177], v[198:201], v[30:33]
	v_mfma_f32_16x16x32_bf16 v[26:29], v[182:185], v[198:201], v[26:29]
	v_mfma_f32_16x16x32_bf16 v[14:17], v[174:177], v[206:209], v[14:17]
	v_mfma_f32_16x16x32_bf16 v[10:13], v[182:185], v[206:209], v[10:13]
	v_mfma_f32_16x16x32_bf16 v[6:9], v[174:177], v[214:217], v[6:9]
	v_mfma_f32_16x16x32_bf16 v[2:5], v[182:185], v[214:217], v[2:5]
	s_setprio 0
	s_barrier
	ds_read_b128 v[154:157], v151
	ds_read_b128 v[158:161], v151 offset:1024
	ds_read_b128 v[162:165], v151 offset:2048
	ds_read_b128 v[166:169], v151 offset:3072
	ds_read_b128 v[170:173], v152
	ds_read_b128 v[174:177], v152 offset:1024
	ds_read_b128 v[178:181], v152 offset:2048
	ds_read_b128 v[182:185], v152 offset:3072
	s_add_u32 s42, s42, 0x40000
	s_addc_u32 s43, s43, 0
	s_mov_b32 m0, s49
	v_lshl_add_u64 v[226:227], s[42:43], 0, v[130:131]
	ds_read_b128 v[186:189], v150 offset:32768
	ds_read_b128 v[190:193], v150 offset:33792
	ds_read_b128 v[194:197], v150 offset:34816
	ds_read_b128 v[198:201], v150 offset:35840
	ds_read_b128 v[202:205], v150 offset:36864
	ds_read_b128 v[206:209], v150 offset:37888
	ds_read_b128 v[210:213], v150 offset:38912
	ds_read_b128 v[214:217], v150 offset:39936
	global_load_lds_dwordx4 v[226:227], off
	v_lshl_add_u64 v[226:227], s[42:43], 0, v[134:135]
	s_mov_b32 m0, s50
	s_nop 0
	global_load_lds_dwordx4 v[226:227], off
	s_waitcnt vmcnt(8)
	s_waitcnt lgkmcnt(0)
	s_barrier
	s_setprio 1
	s_waitcnt lgkmcnt(0)
	v_mfma_f32_16x16x32_bf16 v[126:129], v[154:157], v[186:189], v[126:129]
	v_mfma_f32_16x16x32_bf16 v[122:125], v[162:165], v[186:189], v[122:125]
	v_mfma_f32_16x16x32_bf16 v[118:121], v[154:157], v[194:197], v[118:121]
	v_mfma_f32_16x16x32_bf16 v[114:117], v[162:165], v[194:197], v[114:117]
	v_mfma_f32_16x16x32_bf16 v[102:105], v[154:157], v[202:205], v[102:105]
	v_mfma_f32_16x16x32_bf16 v[98:101], v[162:165], v[202:205], v[98:101]
	v_mfma_f32_16x16x32_bf16 v[86:89], v[154:157], v[210:213], v[86:89]
	v_mfma_f32_16x16x32_bf16 v[82:85], v[162:165], v[210:213], v[82:85]
	v_mfma_f32_16x16x32_bf16 v[126:129], v[158:161], v[190:193], v[126:129]
	v_mfma_f32_16x16x32_bf16 v[122:125], v[166:169], v[190:193], v[122:125]
	v_mfma_f32_16x16x32_bf16 v[118:121], v[158:161], v[198:201], v[118:121]
	v_mfma_f32_16x16x32_bf16 v[114:117], v[166:169], v[198:201], v[114:117]
	v_mfma_f32_16x16x32_bf16 v[102:105], v[158:161], v[206:209], v[102:105]
	v_mfma_f32_16x16x32_bf16 v[98:101], v[166:169], v[206:209], v[98:101]
	v_mfma_f32_16x16x32_bf16 v[86:89], v[158:161], v[214:217], v[86:89]
	v_mfma_f32_16x16x32_bf16 v[82:85], v[166:169], v[214:217], v[82:85]
	s_setprio 0
	s_setprio 1
	v_mfma_f32_16x16x32_bf16 v[110:113], v[170:173], v[186:189], v[110:113]
	v_mfma_f32_16x16x32_bf16 v[106:109], v[178:181], v[186:189], v[106:109]
	v_mfma_f32_16x16x32_bf16 v[94:97], v[170:173], v[194:197], v[94:97]
	v_mfma_f32_16x16x32_bf16 v[90:93], v[178:181], v[194:197], v[90:93]
	v_mfma_f32_16x16x32_bf16 v[78:81], v[170:173], v[202:205], v[78:81]
	v_mfma_f32_16x16x32_bf16 v[74:77], v[178:181], v[202:205], v[74:77]
	v_mfma_f32_16x16x32_bf16 v[70:73], v[170:173], v[210:213], v[70:73]
	v_mfma_f32_16x16x32_bf16 v[66:69], v[178:181], v[210:213], v[66:69]
	v_mfma_f32_16x16x32_bf16 v[110:113], v[174:177], v[190:193], v[110:113]
	v_mfma_f32_16x16x32_bf16 v[106:109], v[182:185], v[190:193], v[106:109]
	v_mfma_f32_16x16x32_bf16 v[94:97], v[174:177], v[198:201], v[94:97]
	v_mfma_f32_16x16x32_bf16 v[90:93], v[182:185], v[198:201], v[90:93]
	v_mfma_f32_16x16x32_bf16 v[78:81], v[174:177], v[206:209], v[78:81]
	v_mfma_f32_16x16x32_bf16 v[74:77], v[182:185], v[206:209], v[74:77]
	v_mfma_f32_16x16x32_bf16 v[70:73], v[174:177], v[214:217], v[70:73]
	v_mfma_f32_16x16x32_bf16 v[66:69], v[182:185], v[214:217], v[66:69]
	s_setprio 0
	s_barrier
; #define PG8_STAGE(bufoff, gbase, voff) do { _Pragma("unroll") for (int _i = 0; _i < 2; ++_i) \
;         __builtin_amdgcn_global_load_lds((const unsigned*)((const char*)(gbase) + (voff)[_i]), (PG8_LAS unsigned*)(lds + (bufoff) + ldsw + _i * 8192), 16, 0, 0); } while (0)
; #define PG8_LDA(dst, b, h) do { _Pragma("unroll") for (int m = 0; m < 4; ++m) _Pragma("unroll") for (int k = 0; k < 2; ++k) dst[m][k] = *(const PG8_LAS bf16x8*)(lds + PG8_SA(b, h) + aoff + m * 2048 + k * 1024); } while (0)
; #define PG8_MMA(ai, bj, At, Bt) do { __builtin_amdgcn_s_setprio(1); _Pragma("unroll") for (int m = 0; m < 4; ++m) _Pragma("unroll") for (int n = 0; n < 2; ++n) _Pragma("unroll") for (int k = 0; k < 2; ++k) \
;         acc[ai][bj][m][n] = __builtin_amdgcn_mfma_f32_16x16x32_bf16(Bt[n][k], At[m][k], acc[ai][bj][m][n], 0, 0, 0); __builtin_amdgcn_s_setprio(0); } while (0)
; #define PG8_WAIT_V(n) asm volatile("s_waitcnt vmcnt(" #n ")" ::: "memory")
; #define PG8_WAIT_L(n) asm volatile("s_waitcnt lgkmcnt(" #n ")" ::: "memory")
; #define PG8_BAR __builtin_amdgcn_s_barrier()
; #define PG8_SCHED __builtin_amdgcn_sched_barrier(0)
; template <class Epi, class Sched, bool ALIGN_EPI = false, bool SP2 = false>
; __device__ __forceinline__ void gemm_phase(PG8_LAS unsigned char* lds, const Gemm g, const Sched& S, const Epi& E) {
;     ...
;             PG8_LDA(At, 1, 1); PG8_STAGE(PG8_SB(1, 0), b3, voffB); PG8_STAGE(PG8_SB(1, 1), b3 + hstep, voffB); PG8_STAGE(PG8_SA(1, 0), a3, voffA);
;             PG8_WAIT_V(8); PG8_WAIT_L(0); PG8_BAR; PG8_MMA(1, 0, At, B0); PG8_MMA(1, 1, At, B1); PG8_BAR; PG8_SCHED;
	s_mov_b32 m0, s52
	v_lshl_add_u64 v[218:219], v[218:219], 0, s[8:9]
	s_add_u32 s40, s40, 0x40080
	ds_read_b128 v[186:189], v150 offset:49152
	ds_read_b128 v[190:193], v150 offset:50176
	ds_read_b128 v[194:197], v150 offset:51200
	ds_read_b128 v[198:201], v150 offset:52224
	ds_read_b128 v[202:205], v150 offset:53248
	ds_read_b128 v[206:209], v150 offset:54272
	ds_read_b128 v[210:213], v150 offset:55296
	ds_read_b128 v[214:217], v150 offset:56320
	global_load_lds_dwordx4 v[218:219], off
	v_lshl_add_u64 v[218:219], v[220:221], 0, s[8:9]
	s_mov_b32 m0, s53
	s_addc_u32 s41, s41, 0
	global_load_lds_dwordx4 v[218:219], off
	v_lshl_add_u64 v[218:219], s[40:41], 0, v[132:133]
	s_mov_b32 m0, s56
	s_nop 0
	global_load_lds_dwordx4 v[218:219], off
	v_lshl_add_u64 v[218:219], s[40:41], 0, v[136:137]
	s_mov_b32 m0, s57
	s_nop 0
	global_load_lds_dwordx4 v[218:219], off
	v_lshl_add_u64 v[218:219], v[222:223], 0, s[8:9]
	s_mov_b32 m0, s54
	s_nop 0
	global_load_lds_dwordx4 v[218:219], off
	v_lshl_add_u64 v[218:219], v[224:225], 0, s[8:9]
	s_mov_b32 m0, s55
	s_nop 0
	global_load_lds_dwordx4 v[218:219], off
	s_waitcnt vmcnt(8)
	s_waitcnt lgkmcnt(0)
	s_barrier
	s_setprio 1
	s_waitcnt lgkmcnt(0)
	v_mfma_f32_16x16x32_bf16 v[62:65], v[154:157], v[186:189], v[62:65]
	v_mfma_f32_16x16x32_bf16 v[58:61], v[162:165], v[186:189], v[58:61]
	v_mfma_f32_16x16x32_bf16 v[54:57], v[154:157], v[194:197], v[54:57]
	v_mfma_f32_16x16x32_bf16 v[50:53], v[162:165], v[194:197], v[50:53]
	v_mfma_f32_16x16x32_bf16 v[38:41], v[154:157], v[202:205], v[38:41]
	v_mfma_f32_16x16x32_bf16 v[34:37], v[162:165], v[202:205], v[34:37]
	v_mfma_f32_16x16x32_bf16 v[22:25], v[154:157], v[210:213], v[22:25]
	v_mfma_f32_16x16x32_bf16 v[18:21], v[162:165], v[210:213], v[18:21]
	v_mfma_f32_16x16x32_bf16 v[62:65], v[158:161], v[190:193], v[62:65]
	v_mfma_f32_16x16x32_bf16 v[58:61], v[166:169], v[190:193], v[58:61]
	v_mfma_f32_16x16x32_bf16 v[54:57], v[158:161], v[198:201], v[54:57]
	v_mfma_f32_16x16x32_bf16 v[50:53], v[166:169], v[198:201], v[50:53]
	v_mfma_f32_16x16x32_bf16 v[38:41], v[158:161], v[206:209], v[38:41]
	v_mfma_f32_16x16x32_bf16 v[34:37], v[166:169], v[206:209], v[34:37]
	v_mfma_f32_16x16x32_bf16 v[22:25], v[158:161], v[214:217], v[22:25]
	v_mfma_f32_16x16x32_bf16 v[18:21], v[166:169], v[214:217], v[18:21]
	s_setprio 0
	s_setprio 1
	v_mfma_f32_16x16x32_bf16 v[46:49], v[170:173], v[186:189], v[46:49]
	v_mfma_f32_16x16x32_bf16 v[42:45], v[178:181], v[186:189], v[42:45]
	v_mfma_f32_16x16x32_bf16 v[30:33], v[170:173], v[194:197], v[30:33]
	v_mfma_f32_16x16x32_bf16 v[26:29], v[178:181], v[194:197], v[26:29]
	v_mfma_f32_16x16x32_bf16 v[14:17], v[170:173], v[202:205], v[14:17]
	v_mfma_f32_16x16x32_bf16 v[10:13], v[178:181], v[202:205], v[10:13]
	v_mfma_f32_16x16x32_bf16 v[6:9], v[170:173], v[210:213], v[6:9]
	v_mfma_f32_16x16x32_bf16 v[2:5], v[178:181], v[210:213], v[2:5]
	v_mfma_f32_16x16x32_bf16 v[46:49], v[174:177], v[190:193], v[46:49]
	v_mfma_f32_16x16x32_bf16 v[42:45], v[182:185], v[190:193], v[42:45]
	v_mfma_f32_16x16x32_bf16 v[30:33], v[174:177], v[198:201], v[30:33]
	v_mfma_f32_16x16x32_bf16 v[26:29], v[182:185], v[198:201], v[26:29]
	v_mfma_f32_16x16x32_bf16 v[14:17], v[174:177], v[206:209], v[14:17]
	v_mfma_f32_16x16x32_bf16 v[10:13], v[182:185], v[206:209], v[10:13]
	v_mfma_f32_16x16x32_bf16 v[6:9], v[174:177], v[214:217], v[6:9]
	v_mfma_f32_16x16x32_bf16 v[2:5], v[182:185], v[214:217], v[2:5]
	s_setprio 0
	s_barrier
	s_add_i32 s68, s68, 2
	s_add_u32 s66, s66, 0x100
	s_addc_u32 s67, s67, 0
	s_add_u32 s38, s38, 0x100
	s_addc_u32 s39, s39, 0
	s_cmp_gt_u32 s68, 13

; #define PG8_STAGE(bufoff, gbase, voff) do { _Pragma("unroll") for (int _i = 0; _i < 2; ++_i) \
;         __builtin_amdgcn_global_load_lds((const unsigned*)((const char*)(gbase) + (voff)[_i]), (PG8_LAS unsigned*)(lds + (bufoff) + ldsw + _i * 8192), 16, 0, 0); } while (0)
; #define PG8_LDA(dst, b, h) do { _Pragma("unroll") for (int m = 0; m < 4; ++m) _Pragma("unroll") for (int k = 0; k < 2; ++k) dst[m][k] = *(const PG8_LAS bf16x8*)(lds + PG8_SA(b, h) + aoff + m * 2048 + k * 1024); } while (0)
; #define PG8_LDB(dst, b, h) do { _Pragma("unroll") for (int n = 0; n < 2; ++n) _Pragma("unroll") for (int k = 0; k < 2; ++k) dst[n][k] = *(const PG8_LAS bf16x8*)(lds + PG8_SB(b, h) + boff + n * 2048 + k * 1024); } while (0)
; #define PG8_MMA(ai, bj, At, Bt) do { __builtin_amdgcn_s_setprio(1); _Pragma("unroll") for (int m = 0; m < 4; ++m) _Pragma("unroll") for (int n = 0; n < 2; ++n) _Pragma("unroll") for (int k = 0; k < 2; ++k) \
;         acc[ai][bj][m][n] = __builtin_amdgcn_mfma_f32_16x16x32_bf16(Bt[n][k], At[m][k], acc[ai][bj][m][n], 0, 0, 0); __builtin_amdgcn_s_setprio(0); } while (0)
; template <class Epi, class Sched, bool ALIGN_EPI = false, bool SP2 = false>
; __device__ __forceinline__ void gemm_phase(PG8_LAS unsigned char* lds, const Gemm g, const Sched& S, const Epi& E) {
;     ...
;         const bool has_next = S.next(ui + 1, nxt);
;         const char* nA = has_next ? (const char*)g.A + (size_t)nxt.pm * tstep + (size_t)nxt.ks * K * 2 : cA; const char* nB = has_next ? (const char*)g.Bt + (size_t)nxt.pn * tstep + (size_t)nxt.ks * K * 2 : cB;
;         for (int t = 0; t < nt; t += 2) {
;             const bool last = (t == nt - 2);
;             const char* a1 = cA + (size_t)(t + 1) * kstep;
;             const char* a2 = last ? nA : cA + (size_t)(t + 2) * kstep; const char* b2 = last ? nB : cB + (size_t)(t + 2) * kstep;
;             const char* a3 = a2 + kstep; const char* b3 = b2 + kstep;
;             if (last && has_next) S.a_ready(nxt);
;             if constexpr (SP2) {
;             PG8_LDB(B0, 0, 0); PG8_LDB(B1, 0, 1); PG8_SCHED; PG8_LDA(At, 0, 0); PG8_STAGE(PG8_SA(1, 1), a1 + hstep, voffA);
;             PG8_WAIT_V(8); PG8_WAIT_L(0); PG8_BAR; PG8_MMA(0, 0, At, B0); PG8_MMA(0, 1, At, B1); PG8_BAR; PG8_SCHED;
;             PG8_LDA(At, 0, 1); PG8_STAGE(PG8_SB(0, 0), b2, voffB); PG8_STAGE(PG8_SB(0, 1), b2 + hstep, voffB); PG8_STAGE(PG8_SA(0, 0), a2, voffA);
.LBB0_2284:
	s_ashr_i32 s13, s12, 31
	s_lshl_b64 s[14:15], s[12:13], 19
	s_add_u32 s14, s28, s14
	s_addc_u32 s15, s29, s15
	s_and_b64 s[16:17], s[2:3], exec
	s_cselect_b32 s13, s15, s23
	s_cselect_b32 s50, s14, s22
	s_ashr_i32 s11, s10, 31
	s_lshl_b64 s[16:17], s[10:11], 19
	s_add_u32 s16, s30, s16
	s_addc_u32 s17, s31, s17
	s_and_b64 s[24:25], s[2:3], exec
	s_cselect_b32 s11, s17, s21
	s_cselect_b32 s51, s16, s20
	s_add_u32 s54, s20, 0x100
	s_addc_u32 s55, s21, 0
	s_add_u32 s20, s22, 0x40080
	s_addc_u32 s21, s23, 0
	s_mov_b32 s58, -2
	ds_read_b128 v[146:149], v152
	ds_read_b128 v[158:161], v152 offset:1024
	ds_read_b128 v[162:165], v152 offset:2048
	ds_read_b128 v[166:169], v152 offset:3072
	ds_read_b128 v[170:173], v153
	ds_read_b128 v[174:177], v153 offset:1024
	ds_read_b128 v[178:181], v153 offset:2048
	ds_read_b128 v[182:185], v153 offset:3072
	s_add_u32 s22, s20, 0xfffc0080
	s_addc_u32 s23, s21, -1
	s_cmp_eq_u32 s58, 12
	s_cselect_b32 s25, s13, s23
	s_cselect_b32 s24, s50, s22
	s_cselect_b32 s23, s11, s55
	s_cselect_b32 s22, s51, s54
	v_lshl_add_u64 v[218:219], s[20:21], 0, v[140:141]
	s_add_i32 m0, s41, 0xc000
	ds_read_b128 v[186:189], v154
	ds_read_b128 v[190:193], v154 offset:1024
	ds_read_b128 v[194:197], v154 offset:2048
	ds_read_b128 v[198:201], v154 offset:3072
	ds_read_b128 v[202:205], v154 offset:4096
	ds_read_b128 v[206:209], v154 offset:5120
	ds_read_b128 v[210:213], v154 offset:6144
	ds_read_b128 v[214:217], v154 offset:7168
	global_load_lds_dwordx4 v[218:219], off
	v_lshl_add_u64 v[218:219], s[20:21], 0, v[138:139]
	s_add_i32 m0, s41, 0xe000
	s_nop 0
	global_load_lds_dwordx4 v[218:219], off
	s_waitcnt vmcnt(8)
	s_waitcnt lgkmcnt(0)
	s_barrier
	s_setprio 1
	s_waitcnt lgkmcnt(0)
	v_mfma_f32_16x16x32_bf16 v[126:129], v[146:149], v[186:189], 0
	v_mfma_f32_16x16x32_bf16 v[118:121], v[162:165], v[186:189], 0
	v_mfma_f32_16x16x32_bf16 v[110:113], v[146:149], v[194:197], 0
	v_mfma_f32_16x16x32_bf16 v[102:105], v[162:165], v[194:197], 0
	v_mfma_f32_16x16x32_bf16 v[94:97], v[146:149], v[202:205], 0
	v_mfma_f32_16x16x32_bf16 v[86:89], v[162:165], v[202:205], 0
	v_mfma_f32_16x16x32_bf16 v[78:81], v[146:149], v[210:213], 0
	v_mfma_f32_16x16x32_bf16 v[70:73], v[162:165], v[210:213], 0
	v_mfma_f32_16x16x32_bf16 v[126:129], v[158:161], v[190:193], v[126:129]
	v_mfma_f32_16x16x32_bf16 v[118:121], v[166:169], v[190:193], v[118:121]
	v_mfma_f32_16x16x32_bf16 v[110:113], v[158:161], v[198:201], v[110:113]
	v_mfma_f32_16x16x32_bf16 v[102:105], v[166:169], v[198:201], v[102:105]
	v_mfma_f32_16x16x32_bf16 v[94:97], v[158:161], v[206:209], v[94:97]
	v_mfma_f32_16x16x32_bf16 v[86:89], v[166:169], v[206:209], v[86:89]
	v_mfma_f32_16x16x32_bf16 v[78:81], v[158:161], v[214:217], v[78:81]
	v_mfma_f32_16x16x32_bf16 v[70:73], v[166:169], v[214:217], v[70:73]
	s_setprio 0
	s_setprio 1
	v_mfma_f32_16x16x32_bf16 v[122:125], v[170:173], v[186:189], 0
	v_mfma_f32_16x16x32_bf16 v[114:117], v[178:181], v[186:189], 0
	v_mfma_f32_16x16x32_bf16 v[106:109], v[170:173], v[194:197], 0
	v_mfma_f32_16x16x32_bf16 v[98:101], v[178:181], v[194:197], 0
	v_mfma_f32_16x16x32_bf16 v[90:93], v[170:173], v[202:205], 0
	v_mfma_f32_16x16x32_bf16 v[82:85], v[178:181], v[202:205], 0
	v_mfma_f32_16x16x32_bf16 v[74:77], v[170:173], v[210:213], 0
	v_mfma_f32_16x16x32_bf16 v[66:69], v[178:181], v[210:213], 0
	v_mfma_f32_16x16x32_bf16 v[122:125], v[174:177], v[190:193], v[122:125]
	v_mfma_f32_16x16x32_bf16 v[114:117], v[182:185], v[190:193], v[114:117]
	v_mfma_f32_16x16x32_bf16 v[106:109], v[174:177], v[198:201], v[106:109]
	v_mfma_f32_16x16x32_bf16 v[98:101], v[182:185], v[198:201], v[98:101]
	v_mfma_f32_16x16x32_bf16 v[90:93], v[174:177], v[206:209], v[90:93]
	v_mfma_f32_16x16x32_bf16 v[82:85], v[182:185], v[206:209], v[82:85]
	v_mfma_f32_16x16x32_bf16 v[74:77], v[174:177], v[214:217], v[74:77]
	v_mfma_f32_16x16x32_bf16 v[66:69], v[182:185], v[214:217], v[66:69]
	s_setprio 0
	s_barrier
	s_mov_b32 m0, s19
	v_lshl_add_u64 v[218:219], s[22:23], 0, v[134:135]
	s_add_u32 s60, s22, 0x40000
	ds_read_b128 v[186:189], v154 offset:16384
	ds_read_b128 v[190:193], v154 offset:17408
	ds_read_b128 v[194:197], v154 offset:18432
	ds_read_b128 v[198:201], v154 offset:19456
	ds_read_b128 v[202:205], v154 offset:20480
	ds_read_b128 v[206:209], v154 offset:21504
	ds_read_b128 v[210:213], v154 offset:22528
	ds_read_b128 v[214:217], v154 offset:23552
	global_load_lds_dwordx4 v[218:219], off
	v_lshl_add_u64 v[220:221], s[22:23], 0, v[130:131]
	s_mov_b32 m0, s38
	s_addc_u32 s61, s23, 0
	global_load_lds_dwordx4 v[220:221], off
	v_lshl_add_u64 v[222:223], s[60:61], 0, v[134:135]
	s_mov_b32 m0, s39
	v_lshl_add_u64 v[224:225], s[24:25], 0, v[132:133]
	global_load_lds_dwordx4 v[222:223], off
	v_lshl_add_u64 v[222:223], s[60:61], 0, v[130:131]
	s_mov_b32 m0, s40
	s_nop 0
	global_load_lds_dwordx4 v[222:223], off
	v_lshl_add_u64 v[222:223], s[24:25], 0, v[136:137]
	s_mov_b32 m0, s41
	s_nop 0
	global_load_lds_dwordx4 v[222:223], off
	s_mov_b32 m0, s42
	s_nop 0
	global_load_lds_dwordx4 v[224:225], off
	s_waitcnt vmcnt(8)
	s_waitcnt lgkmcnt(0)
	s_barrier
; #define PG8_STAGE(bufoff, gbase, voff) do { _Pragma("unroll") for (int _i = 0; _i < 2; ++_i) \
;         __builtin_amdgcn_global_load_lds((const unsigned*)((const char*)(gbase) + (voff)[_i]), (PG8_LAS unsigned*)(lds + (bufoff) + ldsw + _i * 8192), 16, 0, 0); } while (0)
; #define PG8_LDA(dst, b, h) do { _Pragma("unroll") for (int m = 0; m < 4; ++m) _Pragma("unroll") for (int k = 0; k < 2; ++k) dst[m][k] = *(const PG8_LAS bf16x8*)(lds + PG8_SA(b, h) + aoff + m * 2048 + k * 1024); } while (0)
; #define PG8_LDB(dst, b, h) do { _Pragma("unroll") for (int n = 0; n < 2; ++n) _Pragma("unroll") for (int k = 0; k < 2; ++k) dst[n][k] = *(const PG8_LAS bf16x8*)(lds + PG8_SB(b, h) + boff + n * 2048 + k * 1024); } while (0)
; #define PG8_MMA(ai, bj, At, Bt) do { __builtin_amdgcn_s_setprio(1); _Pragma("unroll") for (int m = 0; m < 4; ++m) _Pragma("unroll") for (int n = 0; n < 2; ++n) _Pragma("unroll") for (int k = 0; k < 2; ++k) \
;         acc[ai][bj][m][n] = __builtin_amdgcn_mfma_f32_16x16x32_bf16(Bt[n][k], At[m][k], acc[ai][bj][m][n], 0, 0, 0); __builtin_amdgcn_s_setprio(0); } while (0)
; #define PG8_WAIT_V(n) asm volatile("s_waitcnt vmcnt(" #n ")" ::: "memory")
; #define PG8_WAIT_L(n) asm volatile("s_waitcnt lgkmcnt(" #n ")" ::: "memory")
; #define PG8_BAR __builtin_amdgcn_s_barrier()
; #define PG8_SCHED __builtin_amdgcn_sched_barrier(0)
; template <class Epi, class Sched, bool ALIGN_EPI = false, bool SP2 = false>
; __device__ __forceinline__ void gemm_phase(PG8_LAS unsigned char* lds, const Gemm g, const Sched& S, const Epi& E) {
;     ...
;             PG8_WAIT_V(8); PG8_WAIT_L(0); PG8_BAR; PG8_MMA(1, 0, At, B0); PG8_MMA(1, 1, At, B1); PG8_BAR; PG8_SCHED;
;             PG8_LDB(B0, 1, 0); PG8_LDB(B1, 1, 1); PG8_SCHED; PG8_LDA(At, 1, 0); PG8_STAGE(PG8_SA(0, 1), a2 + hstep, voffA);
;             PG8_WAIT_V(8); PG8_WAIT_L(0); PG8_BAR; PG8_MMA(0, 0, At, B0); PG8_MMA(0, 1, At, B1); PG8_BAR; PG8_SCHED;
	s_setprio 1
	s_waitcnt lgkmcnt(0)
	v_mfma_f32_16x16x32_bf16 v[62:65], v[146:149], v[186:189], 0
	v_mfma_f32_16x16x32_bf16 v[54:57], v[162:165], v[186:189], 0
	v_mfma_f32_16x16x32_bf16 v[46:49], v[146:149], v[194:197], 0
	v_mfma_f32_16x16x32_bf16 v[38:41], v[162:165], v[194:197], 0
	v_mfma_f32_16x16x32_bf16 v[30:33], v[146:149], v[202:205], 0
	v_mfma_f32_16x16x32_bf16 v[22:25], v[162:165], v[202:205], 0
	v_mfma_f32_16x16x32_bf16 v[14:17], v[146:149], v[210:213], 0
	v_mfma_f32_16x16x32_bf16 v[6:9], v[162:165], v[210:213], 0
	v_mfma_f32_16x16x32_bf16 v[62:65], v[158:161], v[190:193], v[62:65]
	v_mfma_f32_16x16x32_bf16 v[54:57], v[166:169], v[190:193], v[54:57]
	v_mfma_f32_16x16x32_bf16 v[46:49], v[158:161], v[198:201], v[46:49]
	v_mfma_f32_16x16x32_bf16 v[38:41], v[166:169], v[198:201], v[38:41]
	v_mfma_f32_16x16x32_bf16 v[30:33], v[158:161], v[206:209], v[30:33]
	v_mfma_f32_16x16x32_bf16 v[22:25], v[166:169], v[206:209], v[22:25]
	v_mfma_f32_16x16x32_bf16 v[14:17], v[158:161], v[214:217], v[14:17]
	v_mfma_f32_16x16x32_bf16 v[6:9], v[166:169], v[214:217], v[6:9]
	s_setprio 0
	s_setprio 1
	v_mfma_f32_16x16x32_bf16 v[58:61], v[170:173], v[186:189], 0
	v_mfma_f32_16x16x32_bf16 v[50:53], v[178:181], v[186:189], 0
	v_mfma_f32_16x16x32_bf16 v[42:45], v[170:173], v[194:197], 0
	v_mfma_f32_16x16x32_bf16 v[34:37], v[178:181], v[194:197], 0
	v_mfma_f32_16x16x32_bf16 v[26:29], v[170:173], v[202:205], 0
	v_mfma_f32_16x16x32_bf16 v[18:21], v[178:181], v[202:205], 0
	v_mfma_f32_16x16x32_bf16 v[10:13], v[170:173], v[210:213], 0
	v_mfma_f32_16x16x32_bf16 v[2:5], v[178:181], v[210:213], 0
	v_mfma_f32_16x16x32_bf16 v[58:61], v[174:177], v[190:193], v[58:61]
	v_mfma_f32_16x16x32_bf16 v[50:53], v[182:185], v[190:193], v[50:53]
	v_mfma_f32_16x16x32_bf16 v[42:45], v[174:177], v[198:201], v[42:45]
	v_mfma_f32_16x16x32_bf16 v[34:37], v[182:185], v[198:201], v[34:37]
	v_mfma_f32_16x16x32_bf16 v[26:29], v[174:177], v[206:209], v[26:29]
	v_mfma_f32_16x16x32_bf16 v[18:21], v[182:185], v[206:209], v[18:21]
	v_mfma_f32_16x16x32_bf16 v[10:13], v[174:177], v[214:217], v[10:13]
	v_mfma_f32_16x16x32_bf16 v[2:5], v[182:185], v[214:217], v[2:5]
	s_setprio 0
	s_barrier
	ds_read_b128 v[146:149], v155
	ds_read_b128 v[158:161], v155 offset:1024
	ds_read_b128 v[162:165], v155 offset:2048
	ds_read_b128 v[166:169], v155 offset:3072
	ds_read_b128 v[170:173], v156
	ds_read_b128 v[174:177], v156 offset:1024
	ds_read_b128 v[178:181], v156 offset:2048
	ds_read_b128 v[182:185], v156 offset:3072
	s_add_u32 s24, s24, 0x40000
	s_addc_u32 s25, s25, 0
	s_mov_b32 m0, s43
	v_lshl_add_u64 v[226:227], s[24:25], 0, v[136:137]
	ds_read_b128 v[186:189], v154 offset:32768
	ds_read_b128 v[190:193], v154 offset:33792
	ds_read_b128 v[194:197], v154 offset:34816
	ds_read_b128 v[198:201], v154 offset:35840
	ds_read_b128 v[202:205], v154 offset:36864
	ds_read_b128 v[206:209], v154 offset:37888
	ds_read_b128 v[210:213], v154 offset:38912
	ds_read_b128 v[214:217], v154 offset:39936
	global_load_lds_dwordx4 v[226:227], off
	v_lshl_add_u64 v[226:227], s[24:25], 0, v[132:133]
	s_mov_b32 m0, s44
	s_nop 0
	global_load_lds_dwordx4 v[226:227], off
	s_waitcnt vmcnt(8)
	s_waitcnt lgkmcnt(0)
	s_barrier
	s_setprio 1
	s_waitcnt lgkmcnt(0)
	v_mfma_f32_16x16x32_bf16 v[126:129], v[146:149], v[186:189], v[126:129]
	v_mfma_f32_16x16x32_bf16 v[118:121], v[162:165], v[186:189], v[118:121]
	v_mfma_f32_16x16x32_bf16 v[110:113], v[146:149], v[194:197], v[110:113]
	v_mfma_f32_16x16x32_bf16 v[102:105], v[162:165], v[194:197], v[102:105]
	v_mfma_f32_16x16x32_bf16 v[94:97], v[146:149], v[202:205], v[94:97]
	v_mfma_f32_16x16x32_bf16 v[86:89], v[162:165], v[202:205], v[86:89]
	v_mfma_f32_16x16x32_bf16 v[78:81], v[146:149], v[210:213], v[78:81]
	v_mfma_f32_16x16x32_bf16 v[70:73], v[162:165], v[210:213], v[70:73]
	v_mfma_f32_16x16x32_bf16 v[126:129], v[158:161], v[190:193], v[126:129]
	v_mfma_f32_16x16x32_bf16 v[118:121], v[166:169], v[190:193], v[118:121]
	v_mfma_f32_16x16x32_bf16 v[110:113], v[158:161], v[198:201], v[110:113]
	v_mfma_f32_16x16x32_bf16 v[102:105], v[166:169], v[198:201], v[102:105]
	v_mfma_f32_16x16x32_bf16 v[94:97], v[158:161], v[206:209], v[94:97]
	v_mfma_f32_16x16x32_bf16 v[86:89], v[166:169], v[206:209], v[86:89]
	v_mfma_f32_16x16x32_bf16 v[78:81], v[158:161], v[214:217], v[78:81]
	v_mfma_f32_16x16x32_bf16 v[70:73], v[166:169], v[214:217], v[70:73]
	s_setprio 0
	s_setprio 1
	v_mfma_f32_16x16x32_bf16 v[122:125], v[170:173], v[186:189], v[122:125]
	v_mfma_f32_16x16x32_bf16 v[114:117], v[178:181], v[186:189], v[114:117]
	v_mfma_f32_16x16x32_bf16 v[106:109], v[170:173], v[194:197], v[106:109]
	v_mfma_f32_16x16x32_bf16 v[98:101], v[178:181], v[194:197], v[98:101]
	v_mfma_f32_16x16x32_bf16 v[90:93], v[170:173], v[202:205], v[90:93]
	v_mfma_f32_16x16x32_bf16 v[82:85], v[178:181], v[202:205], v[82:85]
	v_mfma_f32_16x16x32_bf16 v[74:77], v[170:173], v[210:213], v[74:77]
	v_mfma_f32_16x16x32_bf16 v[66:69], v[178:181], v[210:213], v[66:69]
	v_mfma_f32_16x16x32_bf16 v[122:125], v[174:177], v[190:193], v[122:125]
	v_mfma_f32_16x16x32_bf16 v[114:117], v[182:185], v[190:193], v[114:117]
	v_mfma_f32_16x16x32_bf16 v[106:109], v[174:177], v[198:201], v[106:109]
	v_mfma_f32_16x16x32_bf16 v[98:101], v[182:185], v[198:201], v[98:101]
	v_mfma_f32_16x16x32_bf16 v[90:93], v[174:177], v[206:209], v[90:93]
	v_mfma_f32_16x16x32_bf16 v[82:85], v[182:185], v[206:209], v[82:85]
	v_mfma_f32_16x16x32_bf16 v[74:77], v[174:177], v[214:217], v[74:77]
	v_mfma_f32_16x16x32_bf16 v[66:69], v[182:185], v[214:217], v[66:69]
	s_setprio 0
	s_barrier
; #define PG8_STAGE(bufoff, gbase, voff) do { _Pragma("unroll") for (int _i = 0; _i < 2; ++_i) \
;         __builtin_amdgcn_global_load_lds((const unsigned*)((const char*)(gbase) + (voff)[_i]), (PG8_LAS unsigned*)(lds + (bufoff) + ldsw + _i * 8192), 16, 0, 0); } while (0)
; #define PG8_LDA(dst, b, h) do { _Pragma("unroll") for (int m = 0; m < 4; ++m) _Pragma("unroll") for (int k = 0; k < 2; ++k) dst[m][k] = *(const PG8_LAS bf16x8*)(lds + PG8_SA(b, h) + aoff + m * 2048 + k * 1024); } while (0)
; #define PG8_MMA(ai, bj, At, Bt) do { __builtin_amdgcn_s_setprio(1); _Pragma("unroll") for (int m = 0; m < 4; ++m) _Pragma("unroll") for (int n = 0; n < 2; ++n) _Pragma("unroll") for (int k = 0; k < 2; ++k) \
;         acc[ai][bj][m][n] = __builtin_amdgcn_mfma_f32_16x16x32_bf16(Bt[n][k], At[m][k], acc[ai][bj][m][n], 0, 0, 0); __builtin_amdgcn_s_setprio(0); } while (0)
; #define PG8_WAIT_V(n) asm volatile("s_waitcnt vmcnt(" #n ")" ::: "memory")
; #define PG8_WAIT_L(n) asm volatile("s_waitcnt lgkmcnt(" #n ")" ::: "memory")
; #define PG8_BAR __builtin_amdgcn_s_barrier()
; #define PG8_SCHED __builtin_amdgcn_sched_barrier(0)
; template <class Epi, class Sched, bool ALIGN_EPI = false, bool SP2 = false>
; __device__ __forceinline__ void gemm_phase(PG8_LAS unsigned char* lds, const Gemm g, const Sched& S, const Epi& E) {
;     ...
;             PG8_LDA(At, 1, 1); PG8_STAGE(PG8_SB(1, 0), b3, voffB); PG8_STAGE(PG8_SB(1, 1), b3 + hstep, voffB); PG8_STAGE(PG8_SA(1, 0), a3, voffA);
;             PG8_WAIT_V(8); PG8_WAIT_L(0); PG8_BAR; PG8_MMA(1, 0, At, B0); PG8_MMA(1, 1, At, B1); PG8_BAR; PG8_SCHED;
	s_mov_b32 m0, s45
	v_lshl_add_u64 v[218:219], v[218:219], 0, s[6:7]
	s_add_u32 s22, s22, 0x40080
	ds_read_b128 v[186:189], v154 offset:49152
	ds_read_b128 v[190:193], v154 offset:50176
	ds_read_b128 v[194:197], v154 offset:51200
	ds_read_b128 v[198:201], v154 offset:52224
	ds_read_b128 v[202:205], v154 offset:53248
	ds_read_b128 v[206:209], v154 offset:54272
	ds_read_b128 v[210:213], v154 offset:55296
	ds_read_b128 v[214:217], v154 offset:56320
	global_load_lds_dwordx4 v[218:219], off
	v_lshl_add_u64 v[218:219], v[220:221], 0, s[6:7]
	s_mov_b32 m0, s46
	s_addc_u32 s23, s23, 0
	global_load_lds_dwordx4 v[218:219], off
	v_lshl_add_u64 v[218:219], s[22:23], 0, v[134:135]
	s_mov_b32 m0, s49
	s_nop 0
	global_load_lds_dwordx4 v[218:219], off
	v_lshl_add_u64 v[218:219], s[22:23], 0, v[130:131]
	s_mov_b32 m0, s52
	s_nop 0
	global_load_lds_dwordx4 v[218:219], off
	v_lshl_add_u64 v[218:219], v[222:223], 0, s[6:7]
	s_mov_b32 m0, s47
	s_nop 0
	global_load_lds_dwordx4 v[218:219], off
	v_lshl_add_u64 v[218:219], v[224:225], 0, s[6:7]
	s_mov_b32 m0, s48
	s_nop 0
	global_load_lds_dwordx4 v[218:219], off
	s_waitcnt vmcnt(8)
	s_waitcnt lgkmcnt(0)
	s_barrier
	s_setprio 1
	s_waitcnt lgkmcnt(0)
	v_mfma_f32_16x16x32_bf16 v[62:65], v[146:149], v[186:189], v[62:65]
	v_mfma_f32_16x16x32_bf16 v[54:57], v[162:165], v[186:189], v[54:57]
	v_mfma_f32_16x16x32_bf16 v[46:49], v[146:149], v[194:197], v[46:49]
	v_mfma_f32_16x16x32_bf16 v[38:41], v[162:165], v[194:197], v[38:41]
	v_mfma_f32_16x16x32_bf16 v[30:33], v[146:149], v[202:205], v[30:33]
	v_mfma_f32_16x16x32_bf16 v[22:25], v[162:165], v[202:205], v[22:25]
	v_mfma_f32_16x16x32_bf16 v[14:17], v[146:149], v[210:213], v[14:17]
	v_mfma_f32_16x16x32_bf16 v[6:9], v[162:165], v[210:213], v[6:9]
	v_mfma_f32_16x16x32_bf16 v[62:65], v[158:161], v[190:193], v[62:65]
	v_mfma_f32_16x16x32_bf16 v[54:57], v[166:169], v[190:193], v[54:57]
	v_mfma_f32_16x16x32_bf16 v[46:49], v[158:161], v[198:201], v[46:49]
	v_mfma_f32_16x16x32_bf16 v[38:41], v[166:169], v[198:201], v[38:41]
	v_mfma_f32_16x16x32_bf16 v[30:33], v[158:161], v[206:209], v[30:33]
	v_mfma_f32_16x16x32_bf16 v[22:25], v[166:169], v[206:209], v[22:25]
	v_mfma_f32_16x16x32_bf16 v[14:17], v[158:161], v[214:217], v[14:17]
	v_mfma_f32_16x16x32_bf16 v[6:9], v[166:169], v[214:217], v[6:9]
	s_setprio 0
	s_setprio 1
	v_mfma_f32_16x16x32_bf16 v[58:61], v[170:173], v[186:189], v[58:61]
	v_mfma_f32_16x16x32_bf16 v[50:53], v[178:181], v[186:189], v[50:53]
	v_mfma_f32_16x16x32_bf16 v[42:45], v[170:173], v[194:197], v[42:45]
	v_mfma_f32_16x16x32_bf16 v[34:37], v[178:181], v[194:197], v[34:37]
	v_mfma_f32_16x16x32_bf16 v[26:29], v[170:173], v[202:205], v[26:29]
	v_mfma_f32_16x16x32_bf16 v[18:21], v[178:181], v[202:205], v[18:21]
	v_mfma_f32_16x16x32_bf16 v[10:13], v[170:173], v[210:213], v[10:13]
	v_mfma_f32_16x16x32_bf16 v[2:5], v[178:181], v[210:213], v[2:5]
	v_mfma_f32_16x16x32_bf16 v[58:61], v[174:177], v[190:193], v[58:61]
	v_mfma_f32_16x16x32_bf16 v[50:53], v[182:185], v[190:193], v[50:53]
	v_mfma_f32_16x16x32_bf16 v[42:45], v[174:177], v[198:201], v[42:45]
	v_mfma_f32_16x16x32_bf16 v[34:37], v[182:185], v[198:201], v[34:37]
	v_mfma_f32_16x16x32_bf16 v[26:29], v[174:177], v[206:209], v[26:29]
	v_mfma_f32_16x16x32_bf16 v[18:21], v[182:185], v[206:209], v[18:21]
	v_mfma_f32_16x16x32_bf16 v[10:13], v[174:177], v[214:217], v[10:13]
	v_mfma_f32_16x16x32_bf16 v[2:5], v[182:185], v[214:217], v[2:5]
	s_setprio 0
	s_barrier
	s_add_i32 s58, s58, 2
	s_add_u32 s54, s54, 0x100
	s_addc_u32 s55, s55, 0
	s_add_u32 s20, s20, 0x100
	s_addc_u32 s21, s21, 0
	s_cmp_gt_u32 s58, 13

; #define PG8_STAGE(bufoff, gbase, voff) do { _Pragma("unroll") for (int _i = 0; _i < 2; ++_i) \
;         __builtin_amdgcn_global_load_lds((const unsigned*)((const char*)(gbase) + (voff)[_i]), (PG8_LAS unsigned*)(lds + (bufoff) + ldsw + _i * 8192), 16, 0, 0); } while (0)
; #define PG8_LDA(dst, b, h) do { _Pragma("unroll") for (int m = 0; m < 4; ++m) _Pragma("unroll") for (int k = 0; k < 2; ++k) dst[m][k] = *(const PG8_LAS bf16x8*)(lds + PG8_SA(b, h) + aoff + m * 2048 + k * 1024); } while (0)
; #define PG8_LDB(dst, b, h) do { _Pragma("unroll") for (int n = 0; n < 2; ++n) _Pragma("unroll") for (int k = 0; k < 2; ++k) dst[n][k] = *(const PG8_LAS bf16x8*)(lds + PG8_SB(b, h) + boff + n * 2048 + k * 1024); } while (0)
; #define PG8_MMA(ai, bj, At, Bt) do { __builtin_amdgcn_s_setprio(1); _Pragma("unroll") for (int m = 0; m < 4; ++m) _Pragma("unroll") for (int n = 0; n < 2; ++n) _Pragma("unroll") for (int k = 0; k < 2; ++k) \
;         acc[ai][bj][m][n] = __builtin_amdgcn_mfma_f32_16x16x32_bf16(Bt[n][k], At[m][k], acc[ai][bj][m][n], 0, 0, 0); __builtin_amdgcn_s_setprio(0); } while (0)
; #define PG8_WAIT_V(n) asm volatile("s_waitcnt vmcnt(" #n ")" ::: "memory")
; #define PG8_WAIT_L(n) asm volatile("s_waitcnt lgkmcnt(" #n ")" ::: "memory")
; #define PG8_BAR __builtin_amdgcn_s_barrier()
; #define PG8_SCHED __builtin_amdgcn_sched_barrier(0)
; template <class Epi, class Sched, bool ALIGN_EPI = false, bool SP2 = false>
; __device__ __forceinline__ void gemm_phase(PG8_LAS unsigned char* lds, const Gemm g, const Sched& S, const Epi& E) {
;     ...
;         for (int t = 0; t < nt; t += 2) {
;             const bool last = (t == nt - 2);
;             const char* a1 = cA + (size_t)(t + 1) * kstep;
;             const char* a2 = last ? nA : cA + (size_t)(t + 2) * kstep; const char* b2 = last ? nB : cB + (size_t)(t + 2) * kstep;
;             const char* a3 = a2 + kstep; const char* b3 = b2 + kstep;
;             if (last && has_next) S.a_ready(nxt);
;             if constexpr (SP2) {
;             PG8_LDB(B0, 0, 0); PG8_LDB(B1, 0, 1); PG8_SCHED; PG8_LDA(At, 0, 0); PG8_STAGE(PG8_SA(1, 1), a1 + hstep, voffA);
;             PG8_WAIT_V(8); PG8_WAIT_L(0); PG8_BAR; PG8_MMA(0, 0, At, B0); PG8_MMA(0, 1, At, B1); PG8_BAR; PG8_SCHED;
;             PG8_LDA(At, 0, 1); PG8_STAGE(PG8_SB(0, 0), b2, voffB); PG8_STAGE(PG8_SB(0, 1), b2 + hstep, voffB); PG8_STAGE(PG8_SA(0, 0), a2, voffA);
.LBB0_2366:
	s_add_u32 s64, s24, 0x100
	s_addc_u32 s65, s25, 0
	s_mov_b32 s66, -2
	ds_read_b128 v[154:157], v148
	ds_read_b128 v[158:161], v148 offset:1024
	ds_read_b128 v[162:165], v148 offset:2048
	ds_read_b128 v[166:169], v148 offset:3072
	ds_read_b128 v[170:173], v149
	ds_read_b128 v[174:177], v149 offset:1024
	ds_read_b128 v[178:181], v149 offset:2048
	ds_read_b128 v[182:185], v149 offset:3072
	s_add_u32 s24, s22, 0x100
	s_addc_u32 s25, s23, 0
	s_cmp_eq_u32 s66, 40
	s_cselect_b32 s39, s5, s25
	s_cselect_b32 s38, s4, s24
	s_cselect_b32 s37, s21, s65
	s_cselect_b32 s36, s20, s64
	v_lshl_add_u64 v[218:219], s[22:23], 0, v[140:141]
	s_add_i32 m0, s44, 0xc000
	ds_read_b128 v[186:189], v150
	ds_read_b128 v[190:193], v150 offset:1024
	ds_read_b128 v[194:197], v150 offset:2048
	ds_read_b128 v[198:201], v150 offset:3072
	ds_read_b128 v[202:205], v150 offset:4096
	ds_read_b128 v[206:209], v150 offset:5120
	ds_read_b128 v[210:213], v150 offset:6144
	ds_read_b128 v[214:217], v150 offset:7168
	global_load_lds_dwordx4 v[218:219], off
	v_lshl_add_u64 v[218:219], s[22:23], 0, v[138:139]
	s_add_i32 m0, s44, 0xe000
	s_nop 0
	global_load_lds_dwordx4 v[218:219], off
	s_waitcnt vmcnt(8)
	s_waitcnt lgkmcnt(0)
	s_barrier
	s_setprio 1
	s_waitcnt lgkmcnt(0)
	v_mfma_f32_16x16x32_bf16 v[126:129], v[154:157], v[186:189], 0
	v_mfma_f32_16x16x32_bf16 v[122:125], v[162:165], v[186:189], 0
	v_mfma_f32_16x16x32_bf16 v[118:121], v[154:157], v[194:197], 0
	v_mfma_f32_16x16x32_bf16 v[114:117], v[162:165], v[194:197], 0
	v_mfma_f32_16x16x32_bf16 v[102:105], v[154:157], v[202:205], 0
	v_mfma_f32_16x16x32_bf16 v[98:101], v[162:165], v[202:205], 0
	v_mfma_f32_16x16x32_bf16 v[86:89], v[154:157], v[210:213], 0
	v_mfma_f32_16x16x32_bf16 v[82:85], v[162:165], v[210:213], 0
	v_mfma_f32_16x16x32_bf16 v[126:129], v[158:161], v[190:193], v[126:129]
	v_mfma_f32_16x16x32_bf16 v[122:125], v[166:169], v[190:193], v[122:125]
	v_mfma_f32_16x16x32_bf16 v[118:121], v[158:161], v[198:201], v[118:121]
	v_mfma_f32_16x16x32_bf16 v[114:117], v[166:169], v[198:201], v[114:117]
	v_mfma_f32_16x16x32_bf16 v[102:105], v[158:161], v[206:209], v[102:105]
	v_mfma_f32_16x16x32_bf16 v[98:101], v[166:169], v[206:209], v[98:101]
	v_mfma_f32_16x16x32_bf16 v[86:89], v[158:161], v[214:217], v[86:89]
	v_mfma_f32_16x16x32_bf16 v[82:85], v[166:169], v[214:217], v[82:85]
	s_setprio 0
	s_setprio 1
	v_mfma_f32_16x16x32_bf16 v[110:113], v[170:173], v[186:189], 0
	v_mfma_f32_16x16x32_bf16 v[106:109], v[178:181], v[186:189], 0
	v_mfma_f32_16x16x32_bf16 v[94:97], v[170:173], v[194:197], 0
	v_mfma_f32_16x16x32_bf16 v[90:93], v[178:181], v[194:197], 0
	v_mfma_f32_16x16x32_bf16 v[78:81], v[170:173], v[202:205], 0
	v_mfma_f32_16x16x32_bf16 v[74:77], v[178:181], v[202:205], 0
	v_mfma_f32_16x16x32_bf16 v[70:73], v[170:173], v[210:213], 0
	v_mfma_f32_16x16x32_bf16 v[66:69], v[178:181], v[210:213], 0
	v_mfma_f32_16x16x32_bf16 v[110:113], v[174:177], v[190:193], v[110:113]
	v_mfma_f32_16x16x32_bf16 v[106:109], v[182:185], v[190:193], v[106:109]
	v_mfma_f32_16x16x32_bf16 v[94:97], v[174:177], v[198:201], v[94:97]
	v_mfma_f32_16x16x32_bf16 v[90:93], v[182:185], v[198:201], v[90:93]
	v_mfma_f32_16x16x32_bf16 v[78:81], v[174:177], v[206:209], v[78:81]
	v_mfma_f32_16x16x32_bf16 v[74:77], v[182:185], v[206:209], v[74:77]
	v_mfma_f32_16x16x32_bf16 v[70:73], v[174:177], v[214:217], v[70:73]
	v_mfma_f32_16x16x32_bf16 v[66:69], v[182:185], v[214:217], v[66:69]
	s_setprio 0
	s_barrier
	s_mov_b32 m0, s40
	v_lshl_add_u64 v[218:219], s[36:37], 0, v[132:133]
	s_add_u32 s22, s36, 0xb0000
	ds_read_b128 v[186:189], v150 offset:16384
	ds_read_b128 v[190:193], v150 offset:17408
	ds_read_b128 v[194:197], v150 offset:18432
	ds_read_b128 v[198:201], v150 offset:19456
	ds_read_b128 v[202:205], v150 offset:20480
	ds_read_b128 v[206:209], v150 offset:21504
	ds_read_b128 v[210:213], v150 offset:22528
	ds_read_b128 v[214:217], v150 offset:23552
	global_load_lds_dwordx4 v[218:219], off
	v_lshl_add_u64 v[220:221], s[36:37], 0, v[136:137]
	s_mov_b32 m0, s41
	s_addc_u32 s23, s37, 0
	global_load_lds_dwordx4 v[220:221], off
	v_lshl_add_u64 v[222:223], s[22:23], 0, v[132:133]
	s_mov_b32 m0, s42
	v_lshl_add_u64 v[224:225], s[38:39], 0, v[134:135]
	global_load_lds_dwordx4 v[222:223], off
	v_lshl_add_u64 v[222:223], s[22:23], 0, v[136:137]
	s_mov_b32 m0, s43
	s_nop 0
	global_load_lds_dwordx4 v[222:223], off
	v_lshl_add_u64 v[222:223], s[38:39], 0, v[130:131]
	s_mov_b32 m0, s44
	s_nop 0
	global_load_lds_dwordx4 v[222:223], off
	s_mov_b32 m0, s45
	s_nop 0
	global_load_lds_dwordx4 v[224:225], off
	s_waitcnt vmcnt(8)
	s_waitcnt lgkmcnt(0)
	s_barrier
; #define PG8_STAGE(bufoff, gbase, voff) do { _Pragma("unroll") for (int _i = 0; _i < 2; ++_i) \
;         __builtin_amdgcn_global_load_lds((const unsigned*)((const char*)(gbase) + (voff)[_i]), (PG8_LAS unsigned*)(lds + (bufoff) + ldsw + _i * 8192), 16, 0, 0); } while (0)
; #define PG8_LDA(dst, b, h) do { _Pragma("unroll") for (int m = 0; m < 4; ++m) _Pragma("unroll") for (int k = 0; k < 2; ++k) dst[m][k] = *(const PG8_LAS bf16x8*)(lds + PG8_SA(b, h) + aoff + m * 2048 + k * 1024); } while (0)
; #define PG8_LDB(dst, b, h) do { _Pragma("unroll") for (int n = 0; n < 2; ++n) _Pragma("unroll") for (int k = 0; k < 2; ++k) dst[n][k] = *(const PG8_LAS bf16x8*)(lds + PG8_SB(b, h) + boff + n * 2048 + k * 1024); } while (0)
; #define PG8_MMA(ai, bj, At, Bt) do { __builtin_amdgcn_s_setprio(1); _Pragma("unroll") for (int m = 0; m < 4; ++m) _Pragma("unroll") for (int n = 0; n < 2; ++n) _Pragma("unroll") for (int k = 0; k < 2; ++k) \
;         acc[ai][bj][m][n] = __builtin_amdgcn_mfma_f32_16x16x32_bf16(Bt[n][k], At[m][k], acc[ai][bj][m][n], 0, 0, 0); __builtin_amdgcn_s_setprio(0); } while (0)
; #define PG8_WAIT_V(n) asm volatile("s_waitcnt vmcnt(" #n ")" ::: "memory")
; #define PG8_WAIT_L(n) asm volatile("s_waitcnt lgkmcnt(" #n ")" ::: "memory")
; #define PG8_BAR __builtin_amdgcn_s_barrier()
; #define PG8_SCHED __builtin_amdgcn_sched_barrier(0)
; template <class Epi, class Sched, bool ALIGN_EPI = false, bool SP2 = false>
; __device__ __forceinline__ void gemm_phase(PG8_LAS unsigned char* lds, const Gemm g, const Sched& S, const Epi& E) {
;     ...
;             PG8_WAIT_V(8); PG8_WAIT_L(0); PG8_BAR; PG8_MMA(1, 0, At, B0); PG8_MMA(1, 1, At, B1); PG8_BAR; PG8_SCHED;
;             PG8_LDB(B0, 1, 0); PG8_LDB(B1, 1, 1); PG8_SCHED; PG8_LDA(At, 1, 0); PG8_STAGE(PG8_SA(0, 1), a2 + hstep, voffA);
;             PG8_WAIT_V(8); PG8_WAIT_L(0); PG8_BAR; PG8_MMA(0, 0, At, B0); PG8_MMA(0, 1, At, B1); PG8_BAR; PG8_SCHED;
	s_setprio 1
	s_waitcnt lgkmcnt(0)
	v_mfma_f32_16x16x32_bf16 v[62:65], v[154:157], v[186:189], 0
	v_mfma_f32_16x16x32_bf16 v[58:61], v[162:165], v[186:189], 0
	v_mfma_f32_16x16x32_bf16 v[54:57], v[154:157], v[194:197], 0
	v_mfma_f32_16x16x32_bf16 v[50:53], v[162:165], v[194:197], 0
	v_mfma_f32_16x16x32_bf16 v[38:41], v[154:157], v[202:205], 0
	v_mfma_f32_16x16x32_bf16 v[34:37], v[162:165], v[202:205], 0
	v_mfma_f32_16x16x32_bf16 v[22:25], v[154:157], v[210:213], 0
	v_mfma_f32_16x16x32_bf16 v[18:21], v[162:165], v[210:213], 0
	v_mfma_f32_16x16x32_bf16 v[62:65], v[158:161], v[190:193], v[62:65]
	v_mfma_f32_16x16x32_bf16 v[58:61], v[166:169], v[190:193], v[58:61]
	v_mfma_f32_16x16x32_bf16 v[54:57], v[158:161], v[198:201], v[54:57]
	v_mfma_f32_16x16x32_bf16 v[50:53], v[166:169], v[198:201], v[50:53]
	v_mfma_f32_16x16x32_bf16 v[38:41], v[158:161], v[206:209], v[38:41]
	v_mfma_f32_16x16x32_bf16 v[34:37], v[166:169], v[206:209], v[34:37]
	v_mfma_f32_16x16x32_bf16 v[22:25], v[158:161], v[214:217], v[22:25]
	v_mfma_f32_16x16x32_bf16 v[18:21], v[166:169], v[214:217], v[18:21]
	s_setprio 0
	s_setprio 1
	v_mfma_f32_16x16x32_bf16 v[46:49], v[170:173], v[186:189], 0
	v_mfma_f32_16x16x32_bf16 v[42:45], v[178:181], v[186:189], 0
	v_mfma_f32_16x16x32_bf16 v[30:33], v[170:173], v[194:197], 0
	v_mfma_f32_16x16x32_bf16 v[26:29], v[178:181], v[194:197], 0
	v_mfma_f32_16x16x32_bf16 v[14:17], v[170:173], v[202:205], 0
	v_mfma_f32_16x16x32_bf16 v[10:13], v[178:181], v[202:205], 0
	v_mfma_f32_16x16x32_bf16 v[6:9], v[170:173], v[210:213], 0
	v_mfma_f32_16x16x32_bf16 v[2:5], v[178:181], v[210:213], 0
	v_mfma_f32_16x16x32_bf16 v[46:49], v[174:177], v[190:193], v[46:49]
	v_mfma_f32_16x16x32_bf16 v[42:45], v[182:185], v[190:193], v[42:45]
	v_mfma_f32_16x16x32_bf16 v[30:33], v[174:177], v[198:201], v[30:33]
	v_mfma_f32_16x16x32_bf16 v[26:29], v[182:185], v[198:201], v[26:29]
	v_mfma_f32_16x16x32_bf16 v[14:17], v[174:177], v[206:209], v[14:17]
	v_mfma_f32_16x16x32_bf16 v[10:13], v[182:185], v[206:209], v[10:13]
	v_mfma_f32_16x16x32_bf16 v[6:9], v[174:177], v[214:217], v[6:9]
	v_mfma_f32_16x16x32_bf16 v[2:5], v[182:185], v[214:217], v[2:5]
	s_setprio 0
	s_barrier
	ds_read_b128 v[154:157], v151
	ds_read_b128 v[158:161], v151 offset:1024
	ds_read_b128 v[162:165], v151 offset:2048
	ds_read_b128 v[166:169], v151 offset:3072
	ds_read_b128 v[170:173], v152
	ds_read_b128 v[174:177], v152 offset:1024
	ds_read_b128 v[178:181], v152 offset:2048
	ds_read_b128 v[182:185], v152 offset:3072
	s_add_u32 s22, s38, 0xb0000
	s_addc_u32 s23, s39, 0
	s_mov_b32 m0, s46
	v_lshl_add_u64 v[226:227], s[22:23], 0, v[130:131]
	ds_read_b128 v[186:189], v150 offset:32768
	ds_read_b128 v[190:193], v150 offset:33792
	ds_read_b128 v[194:197], v150 offset:34816
	ds_read_b128 v[198:201], v150 offset:35840
	ds_read_b128 v[202:205], v150 offset:36864
	ds_read_b128 v[206:209], v150 offset:37888
	ds_read_b128 v[210:213], v150 offset:38912
	ds_read_b128 v[214:217], v150 offset:39936
	global_load_lds_dwordx4 v[226:227], off
	v_lshl_add_u64 v[226:227], s[22:23], 0, v[134:135]
	s_mov_b32 m0, s47
	s_nop 0
	global_load_lds_dwordx4 v[226:227], off
	s_waitcnt vmcnt(8)
	s_waitcnt lgkmcnt(0)
	s_barrier
	s_setprio 1
	s_waitcnt lgkmcnt(0)
	v_mfma_f32_16x16x32_bf16 v[126:129], v[154:157], v[186:189], v[126:129]
	v_mfma_f32_16x16x32_bf16 v[122:125], v[162:165], v[186:189], v[122:125]
	v_mfma_f32_16x16x32_bf16 v[118:121], v[154:157], v[194:197], v[118:121]
	v_mfma_f32_16x16x32_bf16 v[114:117], v[162:165], v[194:197], v[114:117]
	v_mfma_f32_16x16x32_bf16 v[102:105], v[154:157], v[202:205], v[102:105]
	v_mfma_f32_16x16x32_bf16 v[98:101], v[162:165], v[202:205], v[98:101]
	v_mfma_f32_16x16x32_bf16 v[86:89], v[154:157], v[210:213], v[86:89]
	v_mfma_f32_16x16x32_bf16 v[82:85], v[162:165], v[210:213], v[82:85]
	v_mfma_f32_16x16x32_bf16 v[126:129], v[158:161], v[190:193], v[126:129]
	v_mfma_f32_16x16x32_bf16 v[122:125], v[166:169], v[190:193], v[122:125]
	v_mfma_f32_16x16x32_bf16 v[118:121], v[158:161], v[198:201], v[118:121]
	v_mfma_f32_16x16x32_bf16 v[114:117], v[166:169], v[198:201], v[114:117]
	v_mfma_f32_16x16x32_bf16 v[102:105], v[158:161], v[206:209], v[102:105]
	v_mfma_f32_16x16x32_bf16 v[98:101], v[166:169], v[206:209], v[98:101]
	v_mfma_f32_16x16x32_bf16 v[86:89], v[158:161], v[214:217], v[86:89]
	v_mfma_f32_16x16x32_bf16 v[82:85], v[166:169], v[214:217], v[82:85]
	s_setprio 0
	s_setprio 1
	v_mfma_f32_16x16x32_bf16 v[110:113], v[170:173], v[186:189], v[110:113]
	v_mfma_f32_16x16x32_bf16 v[106:109], v[178:181], v[186:189], v[106:109]
	v_mfma_f32_16x16x32_bf16 v[94:97], v[170:173], v[194:197], v[94:97]
	v_mfma_f32_16x16x32_bf16 v[90:93], v[178:181], v[194:197], v[90:93]
	v_mfma_f32_16x16x32_bf16 v[78:81], v[170:173], v[202:205], v[78:81]
	v_mfma_f32_16x16x32_bf16 v[74:77], v[178:181], v[202:205], v[74:77]
	v_mfma_f32_16x16x32_bf16 v[70:73], v[170:173], v[210:213], v[70:73]
	v_mfma_f32_16x16x32_bf16 v[66:69], v[178:181], v[210:213], v[66:69]
	v_mfma_f32_16x16x32_bf16 v[110:113], v[174:177], v[190:193], v[110:113]
	v_mfma_f32_16x16x32_bf16 v[106:109], v[182:185], v[190:193], v[106:109]
	v_mfma_f32_16x16x32_bf16 v[94:97], v[174:177], v[198:201], v[94:97]
	v_mfma_f32_16x16x32_bf16 v[90:93], v[182:185], v[198:201], v[90:93]
	v_mfma_f32_16x16x32_bf16 v[78:81], v[174:177], v[206:209], v[78:81]
	v_mfma_f32_16x16x32_bf16 v[74:77], v[182:185], v[206:209], v[74:77]
	v_mfma_f32_16x16x32_bf16 v[70:73], v[174:177], v[214:217], v[70:73]
	v_mfma_f32_16x16x32_bf16 v[66:69], v[182:185], v[214:217], v[66:69]
	s_setprio 0
	s_barrier
; #define PG8_STAGE(bufoff, gbase, voff) do { _Pragma("unroll") for (int _i = 0; _i < 2; ++_i) \
;         __builtin_amdgcn_global_load_lds((const unsigned*)((const char*)(gbase) + (voff)[_i]), (PG8_LAS unsigned*)(lds + (bufoff) + ldsw + _i * 8192), 16, 0, 0); } while (0)
; #define PG8_LDA(dst, b, h) do { _Pragma("unroll") for (int m = 0; m < 4; ++m) _Pragma("unroll") for (int k = 0; k < 2; ++k) dst[m][k] = *(const PG8_LAS bf16x8*)(lds + PG8_SA(b, h) + aoff + m * 2048 + k * 1024); } while (0)
; #define PG8_MMA(ai, bj, At, Bt) do { __builtin_amdgcn_s_setprio(1); _Pragma("unroll") for (int m = 0; m < 4; ++m) _Pragma("unroll") for (int n = 0; n < 2; ++n) _Pragma("unroll") for (int k = 0; k < 2; ++k) \
;         acc[ai][bj][m][n] = __builtin_amdgcn_mfma_f32_16x16x32_bf16(Bt[n][k], At[m][k], acc[ai][bj][m][n], 0, 0, 0); __builtin_amdgcn_s_setprio(0); } while (0)
; #define PG8_WAIT_V(n) asm volatile("s_waitcnt vmcnt(" #n ")" ::: "memory")
; #define PG8_WAIT_L(n) asm volatile("s_waitcnt lgkmcnt(" #n ")" ::: "memory")
; #define PG8_BAR __builtin_amdgcn_s_barrier()
; #define PG8_SCHED __builtin_amdgcn_sched_barrier(0)
; template <class Epi, class Sched, bool ALIGN_EPI = false, bool SP2 = false>
; __device__ __forceinline__ void gemm_phase(PG8_LAS unsigned char* lds, const Gemm g, const Sched& S, const Epi& E) {
;     ...
;             PG8_LDA(At, 1, 1); PG8_STAGE(PG8_SB(1, 0), b3, voffB); PG8_STAGE(PG8_SB(1, 1), b3 + hstep, voffB); PG8_STAGE(PG8_SA(1, 0), a3, voffA);
;             PG8_WAIT_V(8); PG8_WAIT_L(0); PG8_BAR; PG8_MMA(1, 0, At, B0); PG8_MMA(1, 1, At, B1); PG8_BAR; PG8_SCHED;
	s_mov_b32 m0, s49
	v_lshl_add_u64 v[218:219], v[218:219], 0, s[8:9]
	s_add_u32 s22, s36, 0xb0080
	ds_read_b128 v[186:189], v150 offset:49152
	ds_read_b128 v[190:193], v150 offset:50176
	ds_read_b128 v[194:197], v150 offset:51200
	ds_read_b128 v[198:201], v150 offset:52224
	ds_read_b128 v[202:205], v150 offset:53248
	ds_read_b128 v[206:209], v150 offset:54272
	ds_read_b128 v[210:213], v150 offset:55296
	ds_read_b128 v[214:217], v150 offset:56320
	global_load_lds_dwordx4 v[218:219], off
	v_lshl_add_u64 v[218:219], v[220:221], 0, s[8:9]
	s_mov_b32 m0, s50
	s_addc_u32 s23, s37, 0
	global_load_lds_dwordx4 v[218:219], off
	v_lshl_add_u64 v[218:219], s[22:23], 0, v[132:133]
	s_mov_b32 m0, s53
	s_nop 0
	global_load_lds_dwordx4 v[218:219], off
	v_lshl_add_u64 v[218:219], s[22:23], 0, v[136:137]
	s_mov_b32 m0, s54
	s_nop 0
	global_load_lds_dwordx4 v[218:219], off
	v_lshl_add_u64 v[218:219], v[222:223], 0, s[8:9]
	s_mov_b32 m0, s51
	s_nop 0
	global_load_lds_dwordx4 v[218:219], off
	v_lshl_add_u64 v[218:219], v[224:225], 0, s[8:9]
	s_mov_b32 m0, s52
	s_nop 0
	global_load_lds_dwordx4 v[218:219], off
	s_waitcnt vmcnt(8)
	s_waitcnt lgkmcnt(0)
	s_barrier
	s_setprio 1
	s_waitcnt lgkmcnt(0)
	v_mfma_f32_16x16x32_bf16 v[62:65], v[154:157], v[186:189], v[62:65]
	v_mfma_f32_16x16x32_bf16 v[58:61], v[162:165], v[186:189], v[58:61]
	v_mfma_f32_16x16x32_bf16 v[54:57], v[154:157], v[194:197], v[54:57]
	v_mfma_f32_16x16x32_bf16 v[50:53], v[162:165], v[194:197], v[50:53]
	v_mfma_f32_16x16x32_bf16 v[38:41], v[154:157], v[202:205], v[38:41]
	v_mfma_f32_16x16x32_bf16 v[34:37], v[162:165], v[202:205], v[34:37]
	v_mfma_f32_16x16x32_bf16 v[22:25], v[154:157], v[210:213], v[22:25]
	v_mfma_f32_16x16x32_bf16 v[18:21], v[162:165], v[210:213], v[18:21]
	v_mfma_f32_16x16x32_bf16 v[62:65], v[158:161], v[190:193], v[62:65]
	v_mfma_f32_16x16x32_bf16 v[58:61], v[166:169], v[190:193], v[58:61]
	v_mfma_f32_16x16x32_bf16 v[54:57], v[158:161], v[198:201], v[54:57]
	v_mfma_f32_16x16x32_bf16 v[50:53], v[166:169], v[198:201], v[50:53]
	v_mfma_f32_16x16x32_bf16 v[38:41], v[158:161], v[206:209], v[38:41]
	v_mfma_f32_16x16x32_bf16 v[34:37], v[166:169], v[206:209], v[34:37]
	v_mfma_f32_16x16x32_bf16 v[22:25], v[158:161], v[214:217], v[22:25]
	v_mfma_f32_16x16x32_bf16 v[18:21], v[166:169], v[214:217], v[18:21]
	s_setprio 0
	s_setprio 1
	v_mfma_f32_16x16x32_bf16 v[46:49], v[170:173], v[186:189], v[46:49]
	v_mfma_f32_16x16x32_bf16 v[42:45], v[178:181], v[186:189], v[42:45]
	v_mfma_f32_16x16x32_bf16 v[30:33], v[170:173], v[194:197], v[30:33]
	v_mfma_f32_16x16x32_bf16 v[26:29], v[178:181], v[194:197], v[26:29]
	v_mfma_f32_16x16x32_bf16 v[14:17], v[170:173], v[202:205], v[14:17]
	v_mfma_f32_16x16x32_bf16 v[10:13], v[178:181], v[202:205], v[10:13]
	v_mfma_f32_16x16x32_bf16 v[6:9], v[170:173], v[210:213], v[6:9]
	v_mfma_f32_16x16x32_bf16 v[2:5], v[178:181], v[210:213], v[2:5]
	v_mfma_f32_16x16x32_bf16 v[46:49], v[174:177], v[190:193], v[46:49]
	v_mfma_f32_16x16x32_bf16 v[42:45], v[182:185], v[190:193], v[42:45]
	v_mfma_f32_16x16x32_bf16 v[30:33], v[174:177], v[198:201], v[30:33]
	v_mfma_f32_16x16x32_bf16 v[26:29], v[182:185], v[198:201], v[26:29]
	v_mfma_f32_16x16x32_bf16 v[14:17], v[174:177], v[206:209], v[14:17]
	v_mfma_f32_16x16x32_bf16 v[10:13], v[182:185], v[206:209], v[10:13]
	v_mfma_f32_16x16x32_bf16 v[6:9], v[174:177], v[214:217], v[6:9]
	v_mfma_f32_16x16x32_bf16 v[2:5], v[182:185], v[214:217], v[2:5]
	s_setprio 0
	s_barrier
	s_add_i32 s66, s66, 2
	s_add_u32 s64, s64, 0x100
	s_addc_u32 s65, s65, 0
	s_cmp_gt_u32 s66, 41
	s_mov_b64 s[22:23], s[24:25]
